# scans load bf16 operands with global_load_short_d16_hi (value lands as f32 bits), unpack shifts removed
# speedup vs baseline: 1.0030x; 1.0030x over previous
; __device__ __forceinline__ void hgrn_scan(const bf16_t* __restrict__ PH, int t0, int nsteps, int h, int half, int kh, int lane, float lb, f2 (&S)[32], float& cp, bf16_t* __restrict__ OHp, float* __restrict__ ckp, LAS float* L) {
;     const bf16_t* row = PH + (size_t)t0 * 2048 + h * 128 + kh * 64 + lane; const int voff = 1024 + (half - kh) * 64;
;     unsigned short q1[3], q2[3], q3[3];
;     { const bf16_t* r = row; q1[0] = r[0]; q1[1] = r[512]; q1[2] = r[voff];
;       r = row + 2048; q2[0] = r[0]; q2[1] = r[512]; q2[2] = r[voff];
;       r = row + 4096; q3[0] = r[0]; q3[1] = r[512]; q3[2] = r[voff]; }
;     const LAS f32x4* pf = (const LAS f32x4*)L;
; #pragma unroll 1
;     for (int s = 0; s < nsteps; ++s) {
;         const float ql = bf2f(q1[0]), fz = bf2f(q1[1]), v = bf2f(q1[2]);
; #pragma unroll
;         for (int j = 0; j < 3; ++j) { q1[j] = q2[j]; q2[j] = q3[j]; }
;         { const bf16_t* r = row + (size_t)(s + 3 < nsteps ? s + 3 : nsteps - 1) * 2048; q3[0] = r[0]; q3[1] = r[512]; q3[2] = r[voff]; }
;         const float fl = lb + (1.0f - lb) * sigm(fz);
;         cp *= fl;
;         if (ckp && (s & 31) == 31 && s < 127) ckp[(s >> 5) * 128 + lane] = cp;
;         L[lane] = fl; L[64 + lane] = ql * sigm(ql);
;         f32x4 F[2][4], Q[2][4];
; #pragma unroll
;         for (int i = 0; i < 4; ++i) { F[0][i] = pf[i]; Q[0][i] = pf[16 + i]; }
;         const f2 v2 = {v, v}; f2 o2 = {0.f, 0.f}, o3 = {0.f, 0.f};
; #pragma unroll
;         for (int g = 0; g < 4; ++g) {
;             if (g < 3) {
; #pragma unroll
;                 for (int i = 0; i < 4; ++i) { F[(g + 1) & 1][i] = pf[(g + 1) * 4 + i]; Q[(g + 1) & 1][i] = pf[16 + (g + 1) * 4 + i]; } }
;             __builtin_amdgcn_sched_barrier(0);
; #pragma unroll
;             for (int i = 0; i < 4; ++i) {
;                 const f32x4 f4 = F[g & 1][i], q4 = Q[g & 1][i]; const int idx = (g * 4 + i) * 2;
;                 const f2 f01 = {f4[0], f4[1]}, f23 = {f4[2], f4[3]}, q01 = {q4[0], q4[1]}, q23 = {q4[2], q4[3]};
;                 S[idx] = pfma(f01, S[idx] - v2, v2); o2 = pfma(S[idx], q01, o2);
;                 S[idx + 1] = pfma(f23, S[idx + 1] - v2, v2); o3 = pfma(S[idx + 1], q23, o3);
;             }
;         }
;         OHp[(size_t)(t0 + s) * 512 + h * 128 + half * 64 + lane] = f2bf((o2[0] + o2[1]) + (o3[0] + o3[1]));
;     }
.Lhs_go:
	global_load_short_d16_hi v224, v136, s[24:25]
	global_load_short_d16_hi v225, v136, s[24:25] offset:1024
	global_load_short_d16_hi v226, v137, s[24:25]
	global_load_short_d16_hi v227, v137, s[24:25] offset:128
	v_add_u32_e32 v136, 0x1000, v136
	v_add_u32_e32 v137, 0x1000, v137
	global_load_short_d16_hi v228, v136, s[24:25]
	global_load_short_d16_hi v229, v136, s[24:25] offset:1024
	global_load_short_d16_hi v230, v137, s[24:25]
	global_load_short_d16_hi v231, v137, s[24:25] offset:128
	v_add_u32_e32 v136, 0x1000, v136
	v_add_u32_e32 v137, 0x1000, v137
	global_load_short_d16_hi v232, v136, s[24:25]
	global_load_short_d16_hi v233, v136, s[24:25] offset:1024
	global_load_short_d16_hi v234, v137, s[24:25]
	global_load_short_d16_hi v235, v137, s[24:25] offset:128
	v_add_u32_e32 v136, 0x1000, v136
	v_add_u32_e32 v137, 0x1000, v137
	global_load_short_d16_hi v236, v136, s[24:25]
	global_load_short_d16_hi v237, v136, s[24:25] offset:1024
	global_load_short_d16_hi v238, v137, s[24:25]
	global_load_short_d16_hi v239, v137, s[24:25] offset:128
	v_add_u32_e32 v136, 0x1000, v136
	v_add_u32_e32 v137, 0x1000, v137
	s_waitcnt vmcnt(8)
	v_mul_f32_e32 v142, 0xbfb8aa3b, v225
	v_mul_f32_e32 v143, 0xbfb8aa3b, v224
	v_exp_f32_e32 v142, v142
	v_exp_f32_e32 v143, v143
	v_add_f32_e32 v142, 1.0, v142
	v_add_f32_e32 v143, 1.0, v143
	v_rcp_f32_e32 v142, v142
	v_rcp_f32_e32 v143, v143
	v_fma_f32 v142, v131, v142, v130
	v_mul_f32_e32 v143, v143, v224
	v_mul_f32_e32 v132, v132, v142
	ds_write2st64_b32 v134, v142, v143 offset0:0 offset1:1
	v_mov_b32_e32 v182, v143
	v_mov_b32_e32 v140, v226
	v_mov_b32_e32 v141, v227
	v_mov_b32_e32 v254, v230
	v_mov_b32_e32 v255, v231
	v_pk_add_f32 v[0:1], v[0:1], v[140:141] op_sel_hi:[1,0] neg_lo:[0,1] neg_hi:[0,1]
	v_pk_add_f32 v[2:3], v[2:3], v[140:141] op_sel_hi:[1,0] neg_lo:[0,1] neg_hi:[0,1]
	v_pk_add_f32 v[4:5], v[4:5], v[140:141] op_sel_hi:[1,0] neg_lo:[0,1] neg_hi:[0,1]
	v_pk_add_f32 v[6:7], v[6:7], v[140:141] op_sel_hi:[1,0] neg_lo:[0,1] neg_hi:[0,1]
	v_pk_add_f32 v[8:9], v[8:9], v[140:141] op_sel_hi:[1,0] neg_lo:[0,1] neg_hi:[0,1]
	v_pk_add_f32 v[10:11], v[10:11], v[140:141] op_sel_hi:[1,0] neg_lo:[0,1] neg_hi:[0,1]
	v_pk_add_f32 v[12:13], v[12:13], v[140:141] op_sel_hi:[1,0] neg_lo:[0,1] neg_hi:[0,1]
	v_pk_add_f32 v[14:15], v[14:15], v[140:141] op_sel_hi:[1,0] neg_lo:[0,1] neg_hi:[0,1]
	v_pk_add_f32 v[16:17], v[16:17], v[140:141] op_sel_hi:[1,0] neg_lo:[0,1] neg_hi:[0,1]
	v_pk_add_f32 v[18:19], v[18:19], v[140:141] op_sel_hi:[1,0] neg_lo:[0,1] neg_hi:[0,1]
	v_pk_add_f32 v[20:21], v[20:21], v[140:141] op_sel_hi:[1,0] neg_lo:[0,1] neg_hi:[0,1]
	v_pk_add_f32 v[22:23], v[22:23], v[140:141] op_sel_hi:[1,0] neg_lo:[0,1] neg_hi:[0,1]
	v_pk_add_f32 v[24:25], v[24:25], v[140:141] op_sel_hi:[1,0] neg_lo:[0,1] neg_hi:[0,1]
	v_pk_add_f32 v[26:27], v[26:27], v[140:141] op_sel_hi:[1,0] neg_lo:[0,1] neg_hi:[0,1]
	v_pk_add_f32 v[28:29], v[28:29], v[140:141] op_sel_hi:[1,0] neg_lo:[0,1] neg_hi:[0,1]
	v_pk_add_f32 v[30:31], v[30:31], v[140:141] op_sel_hi:[1,0] neg_lo:[0,1] neg_hi:[0,1]
	v_pk_add_f32 v[32:33], v[32:33], v[140:141] op_sel_hi:[1,0] neg_lo:[0,1] neg_hi:[0,1]
	v_pk_add_f32 v[34:35], v[34:35], v[140:141] op_sel_hi:[1,0] neg_lo:[0,1] neg_hi:[0,1]
	v_pk_add_f32 v[36:37], v[36:37], v[140:141] op_sel_hi:[1,0] neg_lo:[0,1] neg_hi:[0,1]
	v_pk_add_f32 v[38:39], v[38:39], v[140:141] op_sel_hi:[1,0] neg_lo:[0,1] neg_hi:[0,1]
	v_pk_add_f32 v[40:41], v[40:41], v[140:141] op_sel_hi:[1,0] neg_lo:[0,1] neg_hi:[0,1]
	v_pk_add_f32 v[42:43], v[42:43], v[140:141] op_sel_hi:[1,0] neg_lo:[0,1] neg_hi:[0,1]
	v_pk_add_f32 v[44:45], v[44:45], v[140:141] op_sel_hi:[1,0] neg_lo:[0,1] neg_hi:[0,1]
	v_pk_add_f32 v[46:47], v[46:47], v[140:141] op_sel_hi:[1,0] neg_lo:[0,1] neg_hi:[0,1]
	v_pk_add_f32 v[48:49], v[48:49], v[140:141] op_sel_hi:[1,0] neg_lo:[0,1] neg_hi:[0,1]
	v_pk_add_f32 v[50:51], v[50:51], v[140:141] op_sel_hi:[1,0] neg_lo:[0,1] neg_hi:[0,1]
	v_pk_add_f32 v[52:53], v[52:53], v[140:141] op_sel_hi:[1,0] neg_lo:[0,1] neg_hi:[0,1]
	v_pk_add_f32 v[54:55], v[54:55], v[140:141] op_sel_hi:[1,0] neg_lo:[0,1] neg_hi:[0,1]
	v_pk_add_f32 v[56:57], v[56:57], v[140:141] op_sel_hi:[1,0] neg_lo:[0,1] neg_hi:[0,1]
	v_pk_add_f32 v[58:59], v[58:59], v[140:141] op_sel_hi:[1,0] neg_lo:[0,1] neg_hi:[0,1]
	v_pk_add_f32 v[60:61], v[60:61], v[140:141] op_sel_hi:[1,0] neg_lo:[0,1] neg_hi:[0,1]
	v_pk_add_f32 v[62:63], v[62:63], v[140:141] op_sel_hi:[1,0] neg_lo:[0,1] neg_hi:[0,1]
	v_pk_add_f32 v[64:65], v[64:65], v[140:141] op_sel:[0,1] op_sel_hi:[1,1] neg_lo:[0,1] neg_hi:[0,1]
	v_pk_add_f32 v[66:67], v[66:67], v[140:141] op_sel:[0,1] op_sel_hi:[1,1] neg_lo:[0,1] neg_hi:[0,1]
	v_pk_add_f32 v[68:69], v[68:69], v[140:141] op_sel:[0,1] op_sel_hi:[1,1] neg_lo:[0,1] neg_hi:[0,1]
	v_pk_add_f32 v[70:71], v[70:71], v[140:141] op_sel:[0,1] op_sel_hi:[1,1] neg_lo:[0,1] neg_hi:[0,1]
	v_pk_add_f32 v[72:73], v[72:73], v[140:141] op_sel:[0,1] op_sel_hi:[1,1] neg_lo:[0,1] neg_hi:[0,1]
	v_pk_add_f32 v[74:75], v[74:75], v[140:141] op_sel:[0,1] op_sel_hi:[1,1] neg_lo:[0,1] neg_hi:[0,1]
	v_pk_add_f32 v[76:77], v[76:77], v[140:141] op_sel:[0,1] op_sel_hi:[1,1] neg_lo:[0,1] neg_hi:[0,1]
	v_pk_add_f32 v[78:79], v[78:79], v[140:141] op_sel:[0,1] op_sel_hi:[1,1] neg_lo:[0,1] neg_hi:[0,1]
	v_pk_add_f32 v[80:81], v[80:81], v[140:141] op_sel:[0,1] op_sel_hi:[1,1] neg_lo:[0,1] neg_hi:[0,1]
	v_pk_add_f32 v[82:83], v[82:83], v[140:141] op_sel:[0,1] op_sel_hi:[1,1] neg_lo:[0,1] neg_hi:[0,1]
	v_pk_add_f32 v[84:85], v[84:85], v[140:141] op_sel:[0,1] op_sel_hi:[1,1] neg_lo:[0,1] neg_hi:[0,1]
	v_pk_add_f32 v[86:87], v[86:87], v[140:141] op_sel:[0,1] op_sel_hi:[1,1] neg_lo:[0,1] neg_hi:[0,1]
; __device__ __forceinline__ float bf2f(unsigned short b) { return __uint_as_float((unsigned)b << 16); }
; __device__ __forceinline__ unsigned short f2bf(float f) { unsigned u = __float_as_uint(f); u += 0x7FFFu + ((u >> 16) & 1u); return (unsigned short)(u >> 16); }
; __device__ __forceinline__ float sigm(float x) { return __builtin_amdgcn_rcpf(1.0f + __expf(-x)); }
; __device__ __forceinline__ f2 pfma(f2 a, f2 b, f2 c) { return __builtin_elementwise_fma(a, b, c); }
; __device__ __forceinline__ void hgrn_scan(const bf16_t* __restrict__ PH, int t0, int nsteps, int h, int half, int kh, int lane, float lb, f2 (&S)[32], float& cp, bf16_t* __restrict__ OHp, float* __restrict__ ckp, LAS float* L) {
;     ...
;     for (int s = 0; s < nsteps; ++s) {
;         const float ql = bf2f(q1[0]), fz = bf2f(q1[1]), v = bf2f(q1[2]);
; #pragma unroll
;         for (int j = 0; j < 3; ++j) { q1[j] = q2[j]; q2[j] = q3[j]; }
;         { const bf16_t* r = row + (size_t)(s + 3 < nsteps ? s + 3 : nsteps - 1) * 2048; q3[0] = r[0]; q3[1] = r[512]; q3[2] = r[voff]; }
;         const float fl = lb + (1.0f - lb) * sigm(fz);
;         cp *= fl;
;         if (ckp && (s & 31) == 31 && s < 127) ckp[(s >> 5) * 128 + lane] = cp;
;         L[lane] = fl; L[64 + lane] = ql * sigm(ql);
;         f32x4 F[2][4], Q[2][4];
; #pragma unroll
;         for (int i = 0; i < 4; ++i) { F[0][i] = pf[i]; Q[0][i] = pf[16 + i]; }
;         const f2 v2 = {v, v}; f2 o2 = {0.f, 0.f}, o3 = {0.f, 0.f};
; #pragma unroll
;         for (int g = 0; g < 4; ++g) {
;             if (g < 3) {
; #pragma unroll
;                 for (int i = 0; i < 4; ++i) { F[(g + 1) & 1][i] = pf[(g + 1) * 4 + i]; Q[(g + 1) & 1][i] = pf[16 + (g + 1) * 4 + i]; } }
;             __builtin_amdgcn_sched_barrier(0);
; #pragma unroll
;             for (int i = 0; i < 4; ++i) {
;                 const f32x4 f4 = F[g & 1][i], q4 = Q[g & 1][i]; const int idx = (g * 4 + i) * 2;
;                 const f2 f01 = {f4[0], f4[1]}, f23 = {f4[2], f4[3]}, q01 = {q4[0], q4[1]}, q23 = {q4[2], q4[3]};
;                 S[idx] = pfma(f01, S[idx] - v2, v2); o2 = pfma(S[idx], q01, o2);
;                 S[idx + 1] = pfma(f23, S[idx + 1] - v2, v2); o3 = pfma(S[idx + 1], q23, o3);
;             }
;         }
;         OHp[(size_t)(t0 + s) * 512 + h * 128 + half * 64 + lane] = f2bf((o2[0] + o2[1]) + (o3[0] + o3[1]));
;     }
	v_pk_add_f32 v[88:89], v[88:89], v[140:141] op_sel:[0,1] op_sel_hi:[1,1] neg_lo:[0,1] neg_hi:[0,1]
	v_pk_add_f32 v[90:91], v[90:91], v[140:141] op_sel:[0,1] op_sel_hi:[1,1] neg_lo:[0,1] neg_hi:[0,1]
	v_pk_add_f32 v[92:93], v[92:93], v[140:141] op_sel:[0,1] op_sel_hi:[1,1] neg_lo:[0,1] neg_hi:[0,1]
	v_pk_add_f32 v[94:95], v[94:95], v[140:141] op_sel:[0,1] op_sel_hi:[1,1] neg_lo:[0,1] neg_hi:[0,1]
	v_pk_add_f32 v[96:97], v[96:97], v[140:141] op_sel:[0,1] op_sel_hi:[1,1] neg_lo:[0,1] neg_hi:[0,1]
	v_pk_add_f32 v[98:99], v[98:99], v[140:141] op_sel:[0,1] op_sel_hi:[1,1] neg_lo:[0,1] neg_hi:[0,1]
	v_pk_add_f32 v[100:101], v[100:101], v[140:141] op_sel:[0,1] op_sel_hi:[1,1] neg_lo:[0,1] neg_hi:[0,1]
	v_pk_add_f32 v[102:103], v[102:103], v[140:141] op_sel:[0,1] op_sel_hi:[1,1] neg_lo:[0,1] neg_hi:[0,1]
	v_pk_add_f32 v[104:105], v[104:105], v[140:141] op_sel:[0,1] op_sel_hi:[1,1] neg_lo:[0,1] neg_hi:[0,1]
	v_pk_add_f32 v[106:107], v[106:107], v[140:141] op_sel:[0,1] op_sel_hi:[1,1] neg_lo:[0,1] neg_hi:[0,1]
	v_pk_add_f32 v[108:109], v[108:109], v[140:141] op_sel:[0,1] op_sel_hi:[1,1] neg_lo:[0,1] neg_hi:[0,1]
	v_pk_add_f32 v[110:111], v[110:111], v[140:141] op_sel:[0,1] op_sel_hi:[1,1] neg_lo:[0,1] neg_hi:[0,1]
	v_pk_add_f32 v[112:113], v[112:113], v[140:141] op_sel:[0,1] op_sel_hi:[1,1] neg_lo:[0,1] neg_hi:[0,1]
	v_pk_add_f32 v[114:115], v[114:115], v[140:141] op_sel:[0,1] op_sel_hi:[1,1] neg_lo:[0,1] neg_hi:[0,1]
	v_pk_add_f32 v[116:117], v[116:117], v[140:141] op_sel:[0,1] op_sel_hi:[1,1] neg_lo:[0,1] neg_hi:[0,1]
	v_pk_add_f32 v[118:119], v[118:119], v[140:141] op_sel:[0,1] op_sel_hi:[1,1] neg_lo:[0,1] neg_hi:[0,1]
	v_pk_add_f32 v[120:121], v[120:121], v[140:141] op_sel:[0,1] op_sel_hi:[1,1] neg_lo:[0,1] neg_hi:[0,1]
	v_pk_add_f32 v[122:123], v[122:123], v[140:141] op_sel:[0,1] op_sel_hi:[1,1] neg_lo:[0,1] neg_hi:[0,1]
	v_pk_add_f32 v[124:125], v[124:125], v[140:141] op_sel:[0,1] op_sel_hi:[1,1] neg_lo:[0,1] neg_hi:[0,1]
	v_pk_add_f32 v[126:127], v[126:127], v[140:141] op_sel:[0,1] op_sel_hi:[1,1] neg_lo:[0,1] neg_hi:[0,1]
	v_pk_add_f32 v[250:251], v[140:141], v[254:255] neg_lo:[0,1] neg_hi:[0,1]
	v_add_f32_dpp v182, v182, v182 quad_perm:[1,0,3,2] row_mask:0xf bank_mask:0xf bound_ctrl:1
	s_nop 1
	v_add_f32_dpp v182, v182, v182 quad_perm:[2,3,0,1] row_mask:0xf bank_mask:0xf bound_ctrl:1
	s_nop 1
	v_add_f32_dpp v182, v182, v182 row_half_mirror row_mask:0xf bank_mask:0xf bound_ctrl:1
	s_nop 1
	v_add_f32_dpp v182, v182, v182 row_mirror row_mask:0xf bank_mask:0xf bound_ctrl:1
	s_nop 1
	v_readlane_b32 s0, v182, 0
	v_readlane_b32 s1, v182, 16
	v_readlane_b32 s6, v182, 32
	v_readlane_b32 s7, v182, 48
	s_nop 1
	v_mov_b32_e32 v183, s0
	v_add_f32_e32 v183, s1, v183
	v_add_f32_e32 v183, s6, v183
	v_add_f32_e32 v183, s7, v183
	s_nop 1
	v_readfirstlane_b32 s2, v183
	s_add_i32 s5, s36, -1
	s_mov_b32 s4, -1
	ds_read_b128 v[148:151], v135 offset:0
	ds_read_b128 v[152:155], v135 offset:16
	ds_read_b128 v[156:159], v135 offset:32
	ds_read_b128 v[160:163], v135 offset:48
	ds_read_b128 v[164:167], v135 offset:256
	ds_read_b128 v[168:171], v135 offset:272
	ds_read_b128 v[172:175], v135 offset:288
	ds_read_b128 v[176:179], v135 offset:304
	s_mov_b32 s37, 0
.Lhs_m_loop:
	global_load_short_d16_hi v224, v136, s[24:25]
	global_load_short_d16_hi v225, v136, s[24:25] offset:1024
	global_load_short_d16_hi v226, v137, s[24:25]
	global_load_short_d16_hi v227, v137, s[24:25] offset:128
	v_add_u32_e32 v136, 0x1000, v136
	v_add_u32_e32 v137, 0x1000, v137
	s_mov_b32 s4, -1
	ds_read_b128 v[192:195], v135 offset:64
	ds_read_b128 v[196:199], v135 offset:80
	ds_read_b128 v[200:203], v135 offset:96
	ds_read_b128 v[204:207], v135 offset:112
	ds_read_b128 v[208:211], v135 offset:320
	ds_read_b128 v[212:215], v135 offset:336
	ds_read_b128 v[216:219], v135 offset:352
	ds_read_b128 v[220:223], v135 offset:368
	s_waitcnt lgkmcnt(8)
	v_pk_fma_f32 v[0:1], v[148:149], v[0:1], v[250:251] op_sel_hi:[1,1,0]
	v_pk_fma_f32 v[2:3], v[150:151], v[2:3], v[250:251] op_sel_hi:[1,1,0]
	v_pk_fma_f32 v[4:5], v[152:153], v[4:5], v[250:251] op_sel_hi:[1,1,0]
	v_pk_fma_f32 v[6:7], v[154:155], v[6:7], v[250:251] op_sel_hi:[1,1,0]
	v_pk_fma_f32 v[240:241], v[0:1], v[164:165], 0 op_sel_hi:[1,1,0]
	v_pk_fma_f32 v[244:245], v[2:3], v[166:167], 0 op_sel_hi:[1,1,0]
	v_pk_fma_f32 v[240:241], v[4:5], v[168:169], v[240:241]
	v_pk_fma_f32 v[244:245], v[6:7], v[170:171], v[244:245]
	v_pk_fma_f32 v[8:9], v[156:157], v[8:9], v[250:251] op_sel_hi:[1,1,0]
	v_pk_fma_f32 v[10:11], v[158:159], v[10:11], v[250:251] op_sel_hi:[1,1,0]
	v_pk_fma_f32 v[12:13], v[160:161], v[12:13], v[250:251] op_sel_hi:[1,1,0]
	v_pk_fma_f32 v[14:15], v[162:163], v[14:15], v[250:251] op_sel_hi:[1,1,0]
	v_pk_fma_f32 v[240:241], v[8:9], v[172:173], v[240:241]
	v_pk_fma_f32 v[244:245], v[10:11], v[174:175], v[244:245]
	v_pk_fma_f32 v[240:241], v[12:13], v[176:177], v[240:241]
	v_pk_fma_f32 v[244:245], v[14:15], v[178:179], v[244:245]
	v_pk_fma_f32 v[64:65], v[148:149], v[64:65], v[250:251] op_sel:[0,0,1] op_sel_hi:[1,1,1]
	v_pk_fma_f32 v[66:67], v[150:151], v[66:67], v[250:251] op_sel:[0,0,1] op_sel_hi:[1,1,1]
	v_pk_fma_f32 v[68:69], v[152:153], v[68:69], v[250:251] op_sel:[0,0,1] op_sel_hi:[1,1,1]
	v_pk_fma_f32 v[70:71], v[154:155], v[70:71], v[250:251] op_sel:[0,0,1] op_sel_hi:[1,1,1]
	v_pk_fma_f32 v[246:247], v[64:65], v[164:165], 0 op_sel_hi:[1,1,0]
	v_pk_fma_f32 v[248:249], v[66:67], v[166:167], 0 op_sel_hi:[1,1,0]
	v_pk_fma_f32 v[246:247], v[68:69], v[168:169], v[246:247]
	v_pk_fma_f32 v[248:249], v[70:71], v[170:171], v[248:249]
	v_pk_fma_f32 v[72:73], v[156:157], v[72:73], v[250:251] op_sel:[0,0,1] op_sel_hi:[1,1,1]
	v_pk_fma_f32 v[74:75], v[158:159], v[74:75], v[250:251] op_sel:[0,0,1] op_sel_hi:[1,1,1]
	v_pk_fma_f32 v[76:77], v[160:161], v[76:77], v[250:251] op_sel:[0,0,1] op_sel_hi:[1,1,1]
	v_pk_fma_f32 v[78:79], v[162:163], v[78:79], v[250:251] op_sel:[0,0,1] op_sel_hi:[1,1,1]
	v_pk_fma_f32 v[246:247], v[72:73], v[172:173], v[246:247]
	v_pk_fma_f32 v[248:249], v[74:75], v[174:175], v[248:249]
	v_pk_fma_f32 v[246:247], v[76:77], v[176:177], v[246:247]
	v_pk_fma_f32 v[248:249], v[78:79], v[178:179], v[248:249]
	v_mul_f32_e32 v142, 0xbfb8aa3b, v229
	v_mul_f32_e32 v143, 0xbfb8aa3b, v228
	v_exp_f32_e32 v142, v142
	v_exp_f32_e32 v143, v143
	v_add_f32_e32 v142, 1.0, v142
	v_add_f32_e32 v143, 1.0, v143
	v_rcp_f32_e32 v142, v142
	v_rcp_f32_e32 v143, v143
	v_fma_f32 v142, v131, v142, v130
	v_mul_f32_e32 v143, v143, v228
	v_mul_f32_e32 v132, v132, v142
	ds_write2st64_b32 v134, v142, v143 offset0:2 offset1:3
	v_mov_b32_e32 v182, v143
	s_waitcnt vmcnt(8)
; __device__ __forceinline__ float bf2f(unsigned short b) { return __uint_as_float((unsigned)b << 16); }
; __device__ __forceinline__ unsigned short f2bf(float f) { unsigned u = __float_as_uint(f); u += 0x7FFFu + ((u >> 16) & 1u); return (unsigned short)(u >> 16); }
; __device__ __forceinline__ float sigm(float x) { return __builtin_amdgcn_rcpf(1.0f + __expf(-x)); }
; __device__ __forceinline__ f2 pfma(f2 a, f2 b, f2 c) { return __builtin_elementwise_fma(a, b, c); }
; __device__ __forceinline__ void hgrn_scan(const bf16_t* __restrict__ PH, int t0, int nsteps, int h, int half, int kh, int lane, float lb, f2 (&S)[32], float& cp, bf16_t* __restrict__ OHp, float* __restrict__ ckp, LAS float* L) {
;     ...
;     for (int s = 0; s < nsteps; ++s) {
;         const float ql = bf2f(q1[0]), fz = bf2f(q1[1]), v = bf2f(q1[2]);
; #pragma unroll
;         for (int j = 0; j < 3; ++j) { q1[j] = q2[j]; q2[j] = q3[j]; }
;         { const bf16_t* r = row + (size_t)(s + 3 < nsteps ? s + 3 : nsteps - 1) * 2048; q3[0] = r[0]; q3[1] = r[512]; q3[2] = r[voff]; }
;         const float fl = lb + (1.0f - lb) * sigm(fz);
;         cp *= fl;
;         if (ckp && (s & 31) == 31 && s < 127) ckp[(s >> 5) * 128 + lane] = cp;
;         L[lane] = fl; L[64 + lane] = ql * sigm(ql);
;         f32x4 F[2][4], Q[2][4];
; #pragma unroll
;         for (int i = 0; i < 4; ++i) { F[0][i] = pf[i]; Q[0][i] = pf[16 + i]; }
;         const f2 v2 = {v, v}; f2 o2 = {0.f, 0.f}, o3 = {0.f, 0.f};
; #pragma unroll
;         for (int g = 0; g < 4; ++g) {
;             if (g < 3) {
; #pragma unroll
;                 for (int i = 0; i < 4; ++i) { F[(g + 1) & 1][i] = pf[(g + 1) * 4 + i]; Q[(g + 1) & 1][i] = pf[16 + (g + 1) * 4 + i]; } }
;             __builtin_amdgcn_sched_barrier(0);
; #pragma unroll
;             for (int i = 0; i < 4; ++i) {
;                 const f32x4 f4 = F[g & 1][i], q4 = Q[g & 1][i]; const int idx = (g * 4 + i) * 2;
;                 const f2 f01 = {f4[0], f4[1]}, f23 = {f4[2], f4[3]}, q01 = {q4[0], q4[1]}, q23 = {q4[2], q4[3]};
;                 S[idx] = pfma(f01, S[idx] - v2, v2); o2 = pfma(S[idx], q01, o2);
;                 S[idx + 1] = pfma(f23, S[idx + 1] - v2, v2); o3 = pfma(S[idx + 1], q23, o3);
;             }
;         }
;         OHp[(size_t)(t0 + s) * 512 + h * 128 + half * 64 + lane] = f2bf((o2[0] + o2[1]) + (o3[0] + o3[1]));
;     }
	v_and_b32_e32 v180, s4, v234
	v_and_b32_e32 v181, s4, v235
	v_pk_add_f32 v[252:253], v[254:255], v[180:181] neg_lo:[0,1] neg_hi:[0,1]
	ds_read_b128 v[148:151], v135 offset:128
	ds_read_b128 v[152:155], v135 offset:144
	ds_read_b128 v[156:159], v135 offset:160
	ds_read_b128 v[160:163], v135 offset:176
	ds_read_b128 v[164:167], v135 offset:384
	ds_read_b128 v[168:171], v135 offset:400
	ds_read_b128 v[172:175], v135 offset:416
	ds_read_b128 v[176:179], v135 offset:432
	v_add_f32_dpp v182, v182, v182 quad_perm:[1,0,3,2] row_mask:0xf bank_mask:0xf bound_ctrl:1
	s_waitcnt lgkmcnt(9)
	v_pk_fma_f32 v[16:17], v[192:193], v[16:17], v[250:251] op_sel_hi:[1,1,0]
	v_pk_fma_f32 v[18:19], v[194:195], v[18:19], v[250:251] op_sel_hi:[1,1,0]
	v_pk_fma_f32 v[20:21], v[196:197], v[20:21], v[250:251] op_sel_hi:[1,1,0]
	v_pk_fma_f32 v[22:23], v[198:199], v[22:23], v[250:251] op_sel_hi:[1,1,0]
	v_pk_fma_f32 v[240:241], v[16:17], v[208:209], v[240:241]
	v_pk_fma_f32 v[244:245], v[18:19], v[210:211], v[244:245]
	v_pk_fma_f32 v[240:241], v[20:21], v[212:213], v[240:241]
	v_pk_fma_f32 v[244:245], v[22:23], v[214:215], v[244:245]
	v_pk_fma_f32 v[24:25], v[200:201], v[24:25], v[250:251] op_sel_hi:[1,1,0]
	v_pk_fma_f32 v[26:27], v[202:203], v[26:27], v[250:251] op_sel_hi:[1,1,0]
	v_pk_fma_f32 v[28:29], v[204:205], v[28:29], v[250:251] op_sel_hi:[1,1,0]
	v_pk_fma_f32 v[30:31], v[206:207], v[30:31], v[250:251] op_sel_hi:[1,1,0]
	v_pk_fma_f32 v[240:241], v[24:25], v[216:217], v[240:241]
	v_pk_fma_f32 v[244:245], v[26:27], v[218:219], v[244:245]
	v_pk_fma_f32 v[240:241], v[28:29], v[220:221], v[240:241]
	v_pk_fma_f32 v[244:245], v[30:31], v[222:223], v[244:245]
	v_pk_fma_f32 v[80:81], v[192:193], v[80:81], v[250:251] op_sel:[0,0,1] op_sel_hi:[1,1,1]
	v_pk_fma_f32 v[82:83], v[194:195], v[82:83], v[250:251] op_sel:[0,0,1] op_sel_hi:[1,1,1]
	v_pk_fma_f32 v[84:85], v[196:197], v[84:85], v[250:251] op_sel:[0,0,1] op_sel_hi:[1,1,1]
	v_pk_fma_f32 v[86:87], v[198:199], v[86:87], v[250:251] op_sel:[0,0,1] op_sel_hi:[1,1,1]
	v_pk_fma_f32 v[246:247], v[80:81], v[208:209], v[246:247]
	v_pk_fma_f32 v[248:249], v[82:83], v[210:211], v[248:249]
	v_pk_fma_f32 v[246:247], v[84:85], v[212:213], v[246:247]
	v_pk_fma_f32 v[248:249], v[86:87], v[214:215], v[248:249]
	v_pk_fma_f32 v[88:89], v[200:201], v[88:89], v[250:251] op_sel:[0,0,1] op_sel_hi:[1,1,1]
	v_pk_fma_f32 v[90:91], v[202:203], v[90:91], v[250:251] op_sel:[0,0,1] op_sel_hi:[1,1,1]
	v_pk_fma_f32 v[92:93], v[204:205], v[92:93], v[250:251] op_sel:[0,0,1] op_sel_hi:[1,1,1]
	v_pk_fma_f32 v[94:95], v[206:207], v[94:95], v[250:251] op_sel:[0,0,1] op_sel_hi:[1,1,1]
	v_pk_fma_f32 v[246:247], v[88:89], v[216:217], v[246:247]
	v_pk_fma_f32 v[248:249], v[90:91], v[218:219], v[248:249]
	v_pk_fma_f32 v[246:247], v[92:93], v[220:221], v[246:247]
	v_pk_fma_f32 v[248:249], v[94:95], v[222:223], v[248:249]
	v_add_f32_dpp v182, v182, v182 quad_perm:[2,3,0,1] row_mask:0xf bank_mask:0xf bound_ctrl:1
	ds_read_b128 v[192:195], v135 offset:192
	ds_read_b128 v[196:199], v135 offset:208
	ds_read_b128 v[200:203], v135 offset:224
	ds_read_b128 v[204:207], v135 offset:240
	ds_read_b128 v[208:211], v135 offset:448
	ds_read_b128 v[212:215], v135 offset:464
	ds_read_b128 v[216:219], v135 offset:480
	ds_read_b128 v[220:223], v135 offset:496
	v_add_f32_dpp v182, v182, v182 row_half_mirror row_mask:0xf bank_mask:0xf bound_ctrl:1
	s_waitcnt lgkmcnt(8)
	v_pk_fma_f32 v[32:33], v[148:149], v[32:33], v[250:251] op_sel_hi:[1,1,0]
	v_pk_fma_f32 v[34:35], v[150:151], v[34:35], v[250:251] op_sel_hi:[1,1,0]
	v_pk_fma_f32 v[36:37], v[152:153], v[36:37], v[250:251] op_sel_hi:[1,1,0]
	v_pk_fma_f32 v[38:39], v[154:155], v[38:39], v[250:251] op_sel_hi:[1,1,0]
	v_pk_fma_f32 v[240:241], v[32:33], v[164:165], v[240:241]
	v_pk_fma_f32 v[244:245], v[34:35], v[166:167], v[244:245]
	v_pk_fma_f32 v[240:241], v[36:37], v[168:169], v[240:241]
	v_pk_fma_f32 v[244:245], v[38:39], v[170:171], v[244:245]
	v_pk_fma_f32 v[40:41], v[156:157], v[40:41], v[250:251] op_sel_hi:[1,1,0]
	v_pk_fma_f32 v[42:43], v[158:159], v[42:43], v[250:251] op_sel_hi:[1,1,0]
	v_pk_fma_f32 v[44:45], v[160:161], v[44:45], v[250:251] op_sel_hi:[1,1,0]
	v_pk_fma_f32 v[46:47], v[162:163], v[46:47], v[250:251] op_sel_hi:[1,1,0]
	v_pk_fma_f32 v[240:241], v[40:41], v[172:173], v[240:241]
	v_pk_fma_f32 v[244:245], v[42:43], v[174:175], v[244:245]
	v_pk_fma_f32 v[240:241], v[44:45], v[176:177], v[240:241]
	v_pk_fma_f32 v[244:245], v[46:47], v[178:179], v[244:245]
	v_pk_fma_f32 v[96:97], v[148:149], v[96:97], v[250:251] op_sel:[0,0,1] op_sel_hi:[1,1,1]
	v_pk_fma_f32 v[98:99], v[150:151], v[98:99], v[250:251] op_sel:[0,0,1] op_sel_hi:[1,1,1]
	v_pk_fma_f32 v[100:101], v[152:153], v[100:101], v[250:251] op_sel:[0,0,1] op_sel_hi:[1,1,1]
	v_pk_fma_f32 v[102:103], v[154:155], v[102:103], v[250:251] op_sel:[0,0,1] op_sel_hi:[1,1,1]
	v_pk_fma_f32 v[246:247], v[96:97], v[164:165], v[246:247]
	v_pk_fma_f32 v[248:249], v[98:99], v[166:167], v[248:249]
	v_pk_fma_f32 v[246:247], v[100:101], v[168:169], v[246:247]
	v_pk_fma_f32 v[248:249], v[102:103], v[170:171], v[248:249]
	v_pk_fma_f32 v[104:105], v[156:157], v[104:105], v[250:251] op_sel:[0,0,1] op_sel_hi:[1,1,1]
	v_pk_fma_f32 v[106:107], v[158:159], v[106:107], v[250:251] op_sel:[0,0,1] op_sel_hi:[1,1,1]
	v_pk_fma_f32 v[108:109], v[160:161], v[108:109], v[250:251] op_sel:[0,0,1] op_sel_hi:[1,1,1]
	v_pk_fma_f32 v[110:111], v[162:163], v[110:111], v[250:251] op_sel:[0,0,1] op_sel_hi:[1,1,1]
	v_pk_fma_f32 v[246:247], v[104:105], v[172:173], v[246:247]
	v_pk_fma_f32 v[248:249], v[106:107], v[174:175], v[248:249]
	v_pk_fma_f32 v[246:247], v[108:109], v[176:177], v[246:247]
	v_pk_fma_f32 v[248:249], v[110:111], v[178:179], v[248:249]
	v_add_f32_dpp v182, v182, v182 row_mirror row_mask:0xf bank_mask:0xf bound_ctrl:1
	ds_read_b128 v[148:151], v135 offset:512
	ds_read_b128 v[152:155], v135 offset:528
	ds_read_b128 v[156:159], v135 offset:544
	ds_read_b128 v[160:163], v135 offset:560
	ds_read_b128 v[164:167], v135 offset:768
	ds_read_b128 v[168:171], v135 offset:784
	ds_read_b128 v[172:175], v135 offset:800
	ds_read_b128 v[176:179], v135 offset:816
	v_readlane_b32 s0, v182, 0
	v_readlane_b32 s1, v182, 16
	v_readlane_b32 s6, v182, 32
	v_readlane_b32 s7, v182, 48
	s_waitcnt lgkmcnt(8)
; __device__ __forceinline__ float bf2f(unsigned short b) { return __uint_as_float((unsigned)b << 16); }
; __device__ __forceinline__ unsigned short f2bf(float f) { unsigned u = __float_as_uint(f); u += 0x7FFFu + ((u >> 16) & 1u); return (unsigned short)(u >> 16); }
; __device__ __forceinline__ float sigm(float x) { return __builtin_amdgcn_rcpf(1.0f + __expf(-x)); }
; __device__ __forceinline__ f2 pfma(f2 a, f2 b, f2 c) { return __builtin_elementwise_fma(a, b, c); }
; __device__ __forceinline__ void hgrn_scan(const bf16_t* __restrict__ PH, int t0, int nsteps, int h, int half, int kh, int lane, float lb, f2 (&S)[32], float& cp, bf16_t* __restrict__ OHp, float* __restrict__ ckp, LAS float* L) {
;     ...
;     for (int s = 0; s < nsteps; ++s) {
;         const float ql = bf2f(q1[0]), fz = bf2f(q1[1]), v = bf2f(q1[2]);
; #pragma unroll
;         for (int j = 0; j < 3; ++j) { q1[j] = q2[j]; q2[j] = q3[j]; }
;         { const bf16_t* r = row + (size_t)(s + 3 < nsteps ? s + 3 : nsteps - 1) * 2048; q3[0] = r[0]; q3[1] = r[512]; q3[2] = r[voff]; }
;         const float fl = lb + (1.0f - lb) * sigm(fz);
;         cp *= fl;
;         if (ckp && (s & 31) == 31 && s < 127) ckp[(s >> 5) * 128 + lane] = cp;
;         L[lane] = fl; L[64 + lane] = ql * sigm(ql);
;         f32x4 F[2][4], Q[2][4];
; #pragma unroll
;         for (int i = 0; i < 4; ++i) { F[0][i] = pf[i]; Q[0][i] = pf[16 + i]; }
;         const f2 v2 = {v, v}; f2 o2 = {0.f, 0.f}, o3 = {0.f, 0.f};
; #pragma unroll
;         for (int g = 0; g < 4; ++g) {
;             if (g < 3) {
; #pragma unroll
;                 for (int i = 0; i < 4; ++i) { F[(g + 1) & 1][i] = pf[(g + 1) * 4 + i]; Q[(g + 1) & 1][i] = pf[16 + (g + 1) * 4 + i]; } }
;             __builtin_amdgcn_sched_barrier(0);
; #pragma unroll
;             for (int i = 0; i < 4; ++i) {
;                 const f32x4 f4 = F[g & 1][i], q4 = Q[g & 1][i]; const int idx = (g * 4 + i) * 2;
;                 const f2 f01 = {f4[0], f4[1]}, f23 = {f4[2], f4[3]}, q01 = {q4[0], q4[1]}, q23 = {q4[2], q4[3]};
;                 S[idx] = pfma(f01, S[idx] - v2, v2); o2 = pfma(S[idx], q01, o2);
;                 S[idx + 1] = pfma(f23, S[idx + 1] - v2, v2); o3 = pfma(S[idx + 1], q23, o3);
;             }
;         }
;         OHp[(size_t)(t0 + s) * 512 + h * 128 + half * 64 + lane] = f2bf((o2[0] + o2[1]) + (o3[0] + o3[1]));
;     }
	v_pk_fma_f32 v[48:49], v[192:193], v[48:49], v[250:251] op_sel_hi:[1,1,0]
	v_pk_fma_f32 v[50:51], v[194:195], v[50:51], v[250:251] op_sel_hi:[1,1,0]
	v_pk_fma_f32 v[52:53], v[196:197], v[52:53], v[250:251] op_sel_hi:[1,1,0]
	v_pk_fma_f32 v[54:55], v[198:199], v[54:55], v[250:251] op_sel_hi:[1,1,0]
	v_pk_fma_f32 v[240:241], v[48:49], v[208:209], v[240:241]
	v_pk_fma_f32 v[244:245], v[50:51], v[210:211], v[244:245]
	v_pk_fma_f32 v[240:241], v[52:53], v[212:213], v[240:241]
	v_pk_fma_f32 v[244:245], v[54:55], v[214:215], v[244:245]
	v_pk_fma_f32 v[56:57], v[200:201], v[56:57], v[250:251] op_sel_hi:[1,1,0]
	v_pk_fma_f32 v[58:59], v[202:203], v[58:59], v[250:251] op_sel_hi:[1,1,0]
	v_pk_fma_f32 v[60:61], v[204:205], v[60:61], v[250:251] op_sel_hi:[1,1,0]
	v_pk_fma_f32 v[62:63], v[206:207], v[62:63], v[250:251] op_sel_hi:[1,1,0]
	v_pk_fma_f32 v[240:241], v[56:57], v[216:217], v[240:241]
	v_pk_fma_f32 v[244:245], v[58:59], v[218:219], v[244:245]
	v_pk_fma_f32 v[240:241], v[60:61], v[220:221], v[240:241]
	v_pk_fma_f32 v[244:245], v[62:63], v[222:223], v[244:245]
	v_pk_fma_f32 v[112:113], v[192:193], v[112:113], v[250:251] op_sel:[0,0,1] op_sel_hi:[1,1,1]
	v_pk_fma_f32 v[114:115], v[194:195], v[114:115], v[250:251] op_sel:[0,0,1] op_sel_hi:[1,1,1]
	v_pk_fma_f32 v[116:117], v[196:197], v[116:117], v[250:251] op_sel:[0,0,1] op_sel_hi:[1,1,1]
	v_pk_fma_f32 v[118:119], v[198:199], v[118:119], v[250:251] op_sel:[0,0,1] op_sel_hi:[1,1,1]
	v_pk_fma_f32 v[246:247], v[112:113], v[208:209], v[246:247]
	v_pk_fma_f32 v[248:249], v[114:115], v[210:211], v[248:249]
	v_pk_fma_f32 v[246:247], v[116:117], v[212:213], v[246:247]
	v_pk_fma_f32 v[248:249], v[118:119], v[214:215], v[248:249]
	v_pk_fma_f32 v[120:121], v[200:201], v[120:121], v[250:251] op_sel:[0,0,1] op_sel_hi:[1,1,1]
	v_pk_fma_f32 v[122:123], v[202:203], v[122:123], v[250:251] op_sel:[0,0,1] op_sel_hi:[1,1,1]
	v_pk_fma_f32 v[124:125], v[204:205], v[124:125], v[250:251] op_sel:[0,0,1] op_sel_hi:[1,1,1]
	v_pk_fma_f32 v[126:127], v[206:207], v[126:127], v[250:251] op_sel:[0,0,1] op_sel_hi:[1,1,1]
	v_pk_fma_f32 v[246:247], v[120:121], v[216:217], v[246:247]
	v_pk_fma_f32 v[248:249], v[122:123], v[218:219], v[248:249]
	v_pk_fma_f32 v[246:247], v[124:125], v[220:221], v[246:247]
	v_pk_fma_f32 v[248:249], v[126:127], v[222:223], v[248:249]
	v_mov_b32_e32 v183, s0
	v_add_f32_e32 v183, s1, v183
	v_add_f32_e32 v183, s6, v183
	v_add_f32_e32 v183, s7, v183
	v_add_f32_e32 v240, v240, v241
	v_add_f32_e32 v244, v244, v245
	v_add_f32_e32 v240, v240, v244
	v_fmac_f32_e32 v240, s2, v254
	v_bfe_u32 v244, v240, 16, 1
	v_add3_u32 v240, v240, v244, s69
	global_store_short_d16_hi v138, v240, s[26:27]
	v_add_f32_e32 v246, v246, v247
	v_add_f32_e32 v248, v248, v249
	v_add_f32_e32 v246, v246, v248
	v_fmac_f32_e32 v246, s2, v255
	v_bfe_u32 v248, v246, 16, 1
	v_add3_u32 v246, v246, v248, s69
	global_store_short_d16_hi v138, v246, s[26:27] offset:128
	v_readfirstlane_b32 s2, v183
	v_mov_b64_e32 v[250:251], v[252:253]
	v_mov_b64_e32 v[254:255], v[180:181]
	v_add_u32_e32 v138, 0x400, v138
	global_load_short_d16_hi v228, v136, s[24:25]
	global_load_short_d16_hi v229, v136, s[24:25] offset:1024
	global_load_short_d16_hi v230, v137, s[24:25]
	global_load_short_d16_hi v231, v137, s[24:25] offset:128
	v_add_u32_e32 v136, 0x1000, v136
	v_add_u32_e32 v137, 0x1000, v137
	ds_read_b128 v[192:195], v135 offset:576
	ds_read_b128 v[196:199], v135 offset:592
	ds_read_b128 v[200:203], v135 offset:608
	ds_read_b128 v[204:207], v135 offset:624
	ds_read_b128 v[208:211], v135 offset:832
	ds_read_b128 v[212:215], v135 offset:848
	ds_read_b128 v[216:219], v135 offset:864
	ds_read_b128 v[220:223], v135 offset:880
	s_waitcnt lgkmcnt(8)
	v_pk_fma_f32 v[0:1], v[148:149], v[0:1], v[250:251] op_sel_hi:[1,1,0]
	v_pk_fma_f32 v[2:3], v[150:151], v[2:3], v[250:251] op_sel_hi:[1,1,0]
	v_pk_fma_f32 v[4:5], v[152:153], v[4:5], v[250:251] op_sel_hi:[1,1,0]
	v_pk_fma_f32 v[6:7], v[154:155], v[6:7], v[250:251] op_sel_hi:[1,1,0]
	v_pk_fma_f32 v[240:241], v[0:1], v[164:165], 0 op_sel_hi:[1,1,0]
	v_pk_fma_f32 v[244:245], v[2:3], v[166:167], 0 op_sel_hi:[1,1,0]
	v_pk_fma_f32 v[240:241], v[4:5], v[168:169], v[240:241]
	v_pk_fma_f32 v[244:245], v[6:7], v[170:171], v[244:245]
	v_pk_fma_f32 v[8:9], v[156:157], v[8:9], v[250:251] op_sel_hi:[1,1,0]
	v_pk_fma_f32 v[10:11], v[158:159], v[10:11], v[250:251] op_sel_hi:[1,1,0]
	v_pk_fma_f32 v[12:13], v[160:161], v[12:13], v[250:251] op_sel_hi:[1,1,0]
	v_pk_fma_f32 v[14:15], v[162:163], v[14:15], v[250:251] op_sel_hi:[1,1,0]
	v_pk_fma_f32 v[240:241], v[8:9], v[172:173], v[240:241]
	v_pk_fma_f32 v[244:245], v[10:11], v[174:175], v[244:245]
	v_pk_fma_f32 v[240:241], v[12:13], v[176:177], v[240:241]
	v_pk_fma_f32 v[244:245], v[14:15], v[178:179], v[244:245]
	v_pk_fma_f32 v[64:65], v[148:149], v[64:65], v[250:251] op_sel:[0,0,1] op_sel_hi:[1,1,1]
	v_pk_fma_f32 v[66:67], v[150:151], v[66:67], v[250:251] op_sel:[0,0,1] op_sel_hi:[1,1,1]
	v_pk_fma_f32 v[68:69], v[152:153], v[68:69], v[250:251] op_sel:[0,0,1] op_sel_hi:[1,1,1]
	v_pk_fma_f32 v[70:71], v[154:155], v[70:71], v[250:251] op_sel:[0,0,1] op_sel_hi:[1,1,1]
	v_pk_fma_f32 v[246:247], v[64:65], v[164:165], 0 op_sel_hi:[1,1,0]
	v_pk_fma_f32 v[248:249], v[66:67], v[166:167], 0 op_sel_hi:[1,1,0]
	v_pk_fma_f32 v[246:247], v[68:69], v[168:169], v[246:247]
	v_pk_fma_f32 v[248:249], v[70:71], v[170:171], v[248:249]
	v_pk_fma_f32 v[72:73], v[156:157], v[72:73], v[250:251] op_sel:[0,0,1] op_sel_hi:[1,1,1]
	v_pk_fma_f32 v[74:75], v[158:159], v[74:75], v[250:251] op_sel:[0,0,1] op_sel_hi:[1,1,1]
	v_pk_fma_f32 v[76:77], v[160:161], v[76:77], v[250:251] op_sel:[0,0,1] op_sel_hi:[1,1,1]
	v_pk_fma_f32 v[78:79], v[162:163], v[78:79], v[250:251] op_sel:[0,0,1] op_sel_hi:[1,1,1]
	v_pk_fma_f32 v[246:247], v[72:73], v[172:173], v[246:247]
	v_pk_fma_f32 v[248:249], v[74:75], v[174:175], v[248:249]
	v_pk_fma_f32 v[246:247], v[76:77], v[176:177], v[246:247]
	v_pk_fma_f32 v[248:249], v[78:79], v[178:179], v[248:249]
	v_mul_f32_e32 v142, 0xbfb8aa3b, v233
	v_mul_f32_e32 v143, 0xbfb8aa3b, v232
	v_exp_f32_e32 v142, v142
	v_exp_f32_e32 v143, v143
	v_add_f32_e32 v142, 1.0, v142
	v_add_f32_e32 v143, 1.0, v143
	v_rcp_f32_e32 v142, v142
	v_rcp_f32_e32 v143, v143
	v_fma_f32 v142, v131, v142, v130
	v_mul_f32_e32 v143, v143, v232
	v_mul_f32_e32 v132, v132, v142
	ds_write2st64_b32 v134, v142, v143 offset0:0 offset1:1
	v_mov_b32_e32 v182, v143
	s_waitcnt vmcnt(10)
; __device__ __forceinline__ float bf2f(unsigned short b) { return __uint_as_float((unsigned)b << 16); }
; __device__ __forceinline__ unsigned short f2bf(float f) { unsigned u = __float_as_uint(f); u += 0x7FFFu + ((u >> 16) & 1u); return (unsigned short)(u >> 16); }
; __device__ __forceinline__ float sigm(float x) { return __builtin_amdgcn_rcpf(1.0f + __expf(-x)); }
; __device__ __forceinline__ f2 pfma(f2 a, f2 b, f2 c) { return __builtin_elementwise_fma(a, b, c); }
; __device__ __forceinline__ void hgrn_scan(const bf16_t* __restrict__ PH, int t0, int nsteps, int h, int half, int kh, int lane, float lb, f2 (&S)[32], float& cp, bf16_t* __restrict__ OHp, float* __restrict__ ckp, LAS float* L) {
;     ...
;     for (int s = 0; s < nsteps; ++s) {
;         const float ql = bf2f(q1[0]), fz = bf2f(q1[1]), v = bf2f(q1[2]);
; #pragma unroll
;         for (int j = 0; j < 3; ++j) { q1[j] = q2[j]; q2[j] = q3[j]; }
;         { const bf16_t* r = row + (size_t)(s + 3 < nsteps ? s + 3 : nsteps - 1) * 2048; q3[0] = r[0]; q3[1] = r[512]; q3[2] = r[voff]; }
;         const float fl = lb + (1.0f - lb) * sigm(fz);
;         cp *= fl;
;         if (ckp && (s & 31) == 31 && s < 127) ckp[(s >> 5) * 128 + lane] = cp;
;         L[lane] = fl; L[64 + lane] = ql * sigm(ql);
;         f32x4 F[2][4], Q[2][4];
; #pragma unroll
;         for (int i = 0; i < 4; ++i) { F[0][i] = pf[i]; Q[0][i] = pf[16 + i]; }
;         const f2 v2 = {v, v}; f2 o2 = {0.f, 0.f}, o3 = {0.f, 0.f};
; #pragma unroll
;         for (int g = 0; g < 4; ++g) {
;             if (g < 3) {
; #pragma unroll
;                 for (int i = 0; i < 4; ++i) { F[(g + 1) & 1][i] = pf[(g + 1) * 4 + i]; Q[(g + 1) & 1][i] = pf[16 + (g + 1) * 4 + i]; } }
;             __builtin_amdgcn_sched_barrier(0);
; #pragma unroll
;             for (int i = 0; i < 4; ++i) {
;                 const f32x4 f4 = F[g & 1][i], q4 = Q[g & 1][i]; const int idx = (g * 4 + i) * 2;
;                 const f2 f01 = {f4[0], f4[1]}, f23 = {f4[2], f4[3]}, q01 = {q4[0], q4[1]}, q23 = {q4[2], q4[3]};
;                 S[idx] = pfma(f01, S[idx] - v2, v2); o2 = pfma(S[idx], q01, o2);
;                 S[idx + 1] = pfma(f23, S[idx + 1] - v2, v2); o3 = pfma(S[idx + 1], q23, o3);
;             }
;         }
;         OHp[(size_t)(t0 + s) * 512 + h * 128 + half * 64 + lane] = f2bf((o2[0] + o2[1]) + (o3[0] + o3[1]));
;     }
	v_and_b32_e32 v180, s4, v238
	v_and_b32_e32 v181, s4, v239
	v_pk_add_f32 v[252:253], v[254:255], v[180:181] neg_lo:[0,1] neg_hi:[0,1]
	ds_read_b128 v[148:151], v135 offset:640
	ds_read_b128 v[152:155], v135 offset:656
	ds_read_b128 v[156:159], v135 offset:672
	ds_read_b128 v[160:163], v135 offset:688
	ds_read_b128 v[164:167], v135 offset:896
	ds_read_b128 v[168:171], v135 offset:912
	ds_read_b128 v[172:175], v135 offset:928
	ds_read_b128 v[176:179], v135 offset:944
	v_add_f32_dpp v182, v182, v182 quad_perm:[1,0,3,2] row_mask:0xf bank_mask:0xf bound_ctrl:1
	s_waitcnt lgkmcnt(9)
	v_pk_fma_f32 v[16:17], v[192:193], v[16:17], v[250:251] op_sel_hi:[1,1,0]
	v_pk_fma_f32 v[18:19], v[194:195], v[18:19], v[250:251] op_sel_hi:[1,1,0]
	v_pk_fma_f32 v[20:21], v[196:197], v[20:21], v[250:251] op_sel_hi:[1,1,0]
	v_pk_fma_f32 v[22:23], v[198:199], v[22:23], v[250:251] op_sel_hi:[1,1,0]
	v_pk_fma_f32 v[240:241], v[16:17], v[208:209], v[240:241]
	v_pk_fma_f32 v[244:245], v[18:19], v[210:211], v[244:245]
	v_pk_fma_f32 v[240:241], v[20:21], v[212:213], v[240:241]
	v_pk_fma_f32 v[244:245], v[22:23], v[214:215], v[244:245]
	v_pk_fma_f32 v[24:25], v[200:201], v[24:25], v[250:251] op_sel_hi:[1,1,0]
	v_pk_fma_f32 v[26:27], v[202:203], v[26:27], v[250:251] op_sel_hi:[1,1,0]
	v_pk_fma_f32 v[28:29], v[204:205], v[28:29], v[250:251] op_sel_hi:[1,1,0]
	v_pk_fma_f32 v[30:31], v[206:207], v[30:31], v[250:251] op_sel_hi:[1,1,0]
	v_pk_fma_f32 v[240:241], v[24:25], v[216:217], v[240:241]
	v_pk_fma_f32 v[244:245], v[26:27], v[218:219], v[244:245]
	v_pk_fma_f32 v[240:241], v[28:29], v[220:221], v[240:241]
	v_pk_fma_f32 v[244:245], v[30:31], v[222:223], v[244:245]
	v_pk_fma_f32 v[80:81], v[192:193], v[80:81], v[250:251] op_sel:[0,0,1] op_sel_hi:[1,1,1]
	v_pk_fma_f32 v[82:83], v[194:195], v[82:83], v[250:251] op_sel:[0,0,1] op_sel_hi:[1,1,1]
	v_pk_fma_f32 v[84:85], v[196:197], v[84:85], v[250:251] op_sel:[0,0,1] op_sel_hi:[1,1,1]
	v_pk_fma_f32 v[86:87], v[198:199], v[86:87], v[250:251] op_sel:[0,0,1] op_sel_hi:[1,1,1]
	v_pk_fma_f32 v[246:247], v[80:81], v[208:209], v[246:247]
	v_pk_fma_f32 v[248:249], v[82:83], v[210:211], v[248:249]
	v_pk_fma_f32 v[246:247], v[84:85], v[212:213], v[246:247]
	v_pk_fma_f32 v[248:249], v[86:87], v[214:215], v[248:249]
	v_pk_fma_f32 v[88:89], v[200:201], v[88:89], v[250:251] op_sel:[0,0,1] op_sel_hi:[1,1,1]
	v_pk_fma_f32 v[90:91], v[202:203], v[90:91], v[250:251] op_sel:[0,0,1] op_sel_hi:[1,1,1]
	v_pk_fma_f32 v[92:93], v[204:205], v[92:93], v[250:251] op_sel:[0,0,1] op_sel_hi:[1,1,1]
	v_pk_fma_f32 v[94:95], v[206:207], v[94:95], v[250:251] op_sel:[0,0,1] op_sel_hi:[1,1,1]
	v_pk_fma_f32 v[246:247], v[88:89], v[216:217], v[246:247]
	v_pk_fma_f32 v[248:249], v[90:91], v[218:219], v[248:249]
	v_pk_fma_f32 v[246:247], v[92:93], v[220:221], v[246:247]
	v_pk_fma_f32 v[248:249], v[94:95], v[222:223], v[248:249]
	v_add_f32_dpp v182, v182, v182 quad_perm:[2,3,0,1] row_mask:0xf bank_mask:0xf bound_ctrl:1
	ds_read_b128 v[192:195], v135 offset:704
	ds_read_b128 v[196:199], v135 offset:720
	ds_read_b128 v[200:203], v135 offset:736
	ds_read_b128 v[204:207], v135 offset:752
	ds_read_b128 v[208:211], v135 offset:960
	ds_read_b128 v[212:215], v135 offset:976
	ds_read_b128 v[216:219], v135 offset:992
	ds_read_b128 v[220:223], v135 offset:1008
	v_add_f32_dpp v182, v182, v182 row_half_mirror row_mask:0xf bank_mask:0xf bound_ctrl:1
	s_waitcnt lgkmcnt(8)
	v_pk_fma_f32 v[32:33], v[148:149], v[32:33], v[250:251] op_sel_hi:[1,1,0]
	v_pk_fma_f32 v[34:35], v[150:151], v[34:35], v[250:251] op_sel_hi:[1,1,0]
	v_pk_fma_f32 v[36:37], v[152:153], v[36:37], v[250:251] op_sel_hi:[1,1,0]
	v_pk_fma_f32 v[38:39], v[154:155], v[38:39], v[250:251] op_sel_hi:[1,1,0]
	v_pk_fma_f32 v[240:241], v[32:33], v[164:165], v[240:241]
	v_pk_fma_f32 v[244:245], v[34:35], v[166:167], v[244:245]
	v_pk_fma_f32 v[240:241], v[36:37], v[168:169], v[240:241]
	v_pk_fma_f32 v[244:245], v[38:39], v[170:171], v[244:245]
	v_pk_fma_f32 v[40:41], v[156:157], v[40:41], v[250:251] op_sel_hi:[1,1,0]
	v_pk_fma_f32 v[42:43], v[158:159], v[42:43], v[250:251] op_sel_hi:[1,1,0]
	v_pk_fma_f32 v[44:45], v[160:161], v[44:45], v[250:251] op_sel_hi:[1,1,0]
	v_pk_fma_f32 v[46:47], v[162:163], v[46:47], v[250:251] op_sel_hi:[1,1,0]
	v_pk_fma_f32 v[240:241], v[40:41], v[172:173], v[240:241]
	v_pk_fma_f32 v[244:245], v[42:43], v[174:175], v[244:245]
	v_pk_fma_f32 v[240:241], v[44:45], v[176:177], v[240:241]
	v_pk_fma_f32 v[244:245], v[46:47], v[178:179], v[244:245]
	v_pk_fma_f32 v[96:97], v[148:149], v[96:97], v[250:251] op_sel:[0,0,1] op_sel_hi:[1,1,1]
	v_pk_fma_f32 v[98:99], v[150:151], v[98:99], v[250:251] op_sel:[0,0,1] op_sel_hi:[1,1,1]
	v_pk_fma_f32 v[100:101], v[152:153], v[100:101], v[250:251] op_sel:[0,0,1] op_sel_hi:[1,1,1]
	v_pk_fma_f32 v[102:103], v[154:155], v[102:103], v[250:251] op_sel:[0,0,1] op_sel_hi:[1,1,1]
	v_pk_fma_f32 v[246:247], v[96:97], v[164:165], v[246:247]
	v_pk_fma_f32 v[248:249], v[98:99], v[166:167], v[248:249]
	v_pk_fma_f32 v[246:247], v[100:101], v[168:169], v[246:247]
	v_pk_fma_f32 v[248:249], v[102:103], v[170:171], v[248:249]
	v_pk_fma_f32 v[104:105], v[156:157], v[104:105], v[250:251] op_sel:[0,0,1] op_sel_hi:[1,1,1]
	v_pk_fma_f32 v[106:107], v[158:159], v[106:107], v[250:251] op_sel:[0,0,1] op_sel_hi:[1,1,1]
	v_pk_fma_f32 v[108:109], v[160:161], v[108:109], v[250:251] op_sel:[0,0,1] op_sel_hi:[1,1,1]
	v_pk_fma_f32 v[110:111], v[162:163], v[110:111], v[250:251] op_sel:[0,0,1] op_sel_hi:[1,1,1]
	v_pk_fma_f32 v[246:247], v[104:105], v[172:173], v[246:247]
	v_pk_fma_f32 v[248:249], v[106:107], v[174:175], v[248:249]
	v_pk_fma_f32 v[246:247], v[108:109], v[176:177], v[246:247]
	v_pk_fma_f32 v[248:249], v[110:111], v[178:179], v[248:249]
	v_add_f32_dpp v182, v182, v182 row_mirror row_mask:0xf bank_mask:0xf bound_ctrl:1
	ds_read_b128 v[148:151], v135 offset:0
	ds_read_b128 v[152:155], v135 offset:16
	ds_read_b128 v[156:159], v135 offset:32
	ds_read_b128 v[160:163], v135 offset:48
	ds_read_b128 v[164:167], v135 offset:256
	ds_read_b128 v[168:171], v135 offset:272
	ds_read_b128 v[172:175], v135 offset:288
	ds_read_b128 v[176:179], v135 offset:304
	v_readlane_b32 s0, v182, 0
	v_readlane_b32 s1, v182, 16
	v_readlane_b32 s6, v182, 32
	v_readlane_b32 s7, v182, 48
	s_waitcnt lgkmcnt(8)
; __device__ __forceinline__ float bf2f(unsigned short b) { return __uint_as_float((unsigned)b << 16); }
; __device__ __forceinline__ unsigned short f2bf(float f) { unsigned u = __float_as_uint(f); u += 0x7FFFu + ((u >> 16) & 1u); return (unsigned short)(u >> 16); }
; __device__ __forceinline__ float sigm(float x) { return __builtin_amdgcn_rcpf(1.0f + __expf(-x)); }
; __device__ __forceinline__ f2 pfma(f2 a, f2 b, f2 c) { return __builtin_elementwise_fma(a, b, c); }
; __device__ __forceinline__ void hgrn_scan(const bf16_t* __restrict__ PH, int t0, int nsteps, int h, int half, int kh, int lane, float lb, f2 (&S)[32], float& cp, bf16_t* __restrict__ OHp, float* __restrict__ ckp, LAS float* L) {
;     ...
;     for (int s = 0; s < nsteps; ++s) {
;         const float ql = bf2f(q1[0]), fz = bf2f(q1[1]), v = bf2f(q1[2]);
; #pragma unroll
;         for (int j = 0; j < 3; ++j) { q1[j] = q2[j]; q2[j] = q3[j]; }
;         { const bf16_t* r = row + (size_t)(s + 3 < nsteps ? s + 3 : nsteps - 1) * 2048; q3[0] = r[0]; q3[1] = r[512]; q3[2] = r[voff]; }
;         const float fl = lb + (1.0f - lb) * sigm(fz);
;         cp *= fl;
;         if (ckp && (s & 31) == 31 && s < 127) ckp[(s >> 5) * 128 + lane] = cp;
;         L[lane] = fl; L[64 + lane] = ql * sigm(ql);
;         f32x4 F[2][4], Q[2][4];
; #pragma unroll
;         for (int i = 0; i < 4; ++i) { F[0][i] = pf[i]; Q[0][i] = pf[16 + i]; }
;         const f2 v2 = {v, v}; f2 o2 = {0.f, 0.f}, o3 = {0.f, 0.f};
; #pragma unroll
;         for (int g = 0; g < 4; ++g) {
;             if (g < 3) {
; #pragma unroll
;                 for (int i = 0; i < 4; ++i) { F[(g + 1) & 1][i] = pf[(g + 1) * 4 + i]; Q[(g + 1) & 1][i] = pf[16 + (g + 1) * 4 + i]; } }
;             __builtin_amdgcn_sched_barrier(0);
; #pragma unroll
;             for (int i = 0; i < 4; ++i) {
;                 const f32x4 f4 = F[g & 1][i], q4 = Q[g & 1][i]; const int idx = (g * 4 + i) * 2;
;                 const f2 f01 = {f4[0], f4[1]}, f23 = {f4[2], f4[3]}, q01 = {q4[0], q4[1]}, q23 = {q4[2], q4[3]};
;                 S[idx] = pfma(f01, S[idx] - v2, v2); o2 = pfma(S[idx], q01, o2);
;                 S[idx + 1] = pfma(f23, S[idx + 1] - v2, v2); o3 = pfma(S[idx + 1], q23, o3);
;             }
;         }
;         OHp[(size_t)(t0 + s) * 512 + h * 128 + half * 64 + lane] = f2bf((o2[0] + o2[1]) + (o3[0] + o3[1]));
;     }
	v_pk_fma_f32 v[48:49], v[192:193], v[48:49], v[250:251] op_sel_hi:[1,1,0]
	v_pk_fma_f32 v[50:51], v[194:195], v[50:51], v[250:251] op_sel_hi:[1,1,0]
	v_pk_fma_f32 v[52:53], v[196:197], v[52:53], v[250:251] op_sel_hi:[1,1,0]
	v_pk_fma_f32 v[54:55], v[198:199], v[54:55], v[250:251] op_sel_hi:[1,1,0]
	v_pk_fma_f32 v[240:241], v[48:49], v[208:209], v[240:241]
	v_pk_fma_f32 v[244:245], v[50:51], v[210:211], v[244:245]
	v_pk_fma_f32 v[240:241], v[52:53], v[212:213], v[240:241]
	v_pk_fma_f32 v[244:245], v[54:55], v[214:215], v[244:245]
	v_pk_fma_f32 v[56:57], v[200:201], v[56:57], v[250:251] op_sel_hi:[1,1,0]
	v_pk_fma_f32 v[58:59], v[202:203], v[58:59], v[250:251] op_sel_hi:[1,1,0]
	v_pk_fma_f32 v[60:61], v[204:205], v[60:61], v[250:251] op_sel_hi:[1,1,0]
	v_pk_fma_f32 v[62:63], v[206:207], v[62:63], v[250:251] op_sel_hi:[1,1,0]
	v_pk_fma_f32 v[240:241], v[56:57], v[216:217], v[240:241]
	v_pk_fma_f32 v[244:245], v[58:59], v[218:219], v[244:245]
	v_pk_fma_f32 v[240:241], v[60:61], v[220:221], v[240:241]
	v_pk_fma_f32 v[244:245], v[62:63], v[222:223], v[244:245]
	v_pk_fma_f32 v[112:113], v[192:193], v[112:113], v[250:251] op_sel:[0,0,1] op_sel_hi:[1,1,1]
	v_pk_fma_f32 v[114:115], v[194:195], v[114:115], v[250:251] op_sel:[0,0,1] op_sel_hi:[1,1,1]
	v_pk_fma_f32 v[116:117], v[196:197], v[116:117], v[250:251] op_sel:[0,0,1] op_sel_hi:[1,1,1]
	v_pk_fma_f32 v[118:119], v[198:199], v[118:119], v[250:251] op_sel:[0,0,1] op_sel_hi:[1,1,1]
	v_pk_fma_f32 v[246:247], v[112:113], v[208:209], v[246:247]
	v_pk_fma_f32 v[248:249], v[114:115], v[210:211], v[248:249]
	v_pk_fma_f32 v[246:247], v[116:117], v[212:213], v[246:247]
	v_pk_fma_f32 v[248:249], v[118:119], v[214:215], v[248:249]
	v_pk_fma_f32 v[120:121], v[200:201], v[120:121], v[250:251] op_sel:[0,0,1] op_sel_hi:[1,1,1]
	v_pk_fma_f32 v[122:123], v[202:203], v[122:123], v[250:251] op_sel:[0,0,1] op_sel_hi:[1,1,1]
	v_pk_fma_f32 v[124:125], v[204:205], v[124:125], v[250:251] op_sel:[0,0,1] op_sel_hi:[1,1,1]
	v_pk_fma_f32 v[126:127], v[206:207], v[126:127], v[250:251] op_sel:[0,0,1] op_sel_hi:[1,1,1]
	v_pk_fma_f32 v[246:247], v[120:121], v[216:217], v[246:247]
	v_pk_fma_f32 v[248:249], v[122:123], v[218:219], v[248:249]
	v_pk_fma_f32 v[246:247], v[124:125], v[220:221], v[246:247]
	v_pk_fma_f32 v[248:249], v[126:127], v[222:223], v[248:249]
	v_mov_b32_e32 v183, s0
	v_add_f32_e32 v183, s1, v183
	v_add_f32_e32 v183, s6, v183
	v_add_f32_e32 v183, s7, v183
	v_add_f32_e32 v240, v240, v241
	v_add_f32_e32 v244, v244, v245
	v_add_f32_e32 v240, v240, v244
	v_fmac_f32_e32 v240, s2, v254
	v_bfe_u32 v244, v240, 16, 1
	v_add3_u32 v240, v240, v244, s69
	global_store_short_d16_hi v138, v240, s[26:27]
	v_add_f32_e32 v246, v246, v247
	v_add_f32_e32 v248, v248, v249
	v_add_f32_e32 v246, v246, v248
	v_fmac_f32_e32 v246, s2, v255
	v_bfe_u32 v248, v246, 16, 1
	v_add3_u32 v246, v246, v248, s69
	global_store_short_d16_hi v138, v246, s[26:27] offset:128
	v_readfirstlane_b32 s2, v183
	v_mov_b64_e32 v[250:251], v[252:253]
	v_mov_b64_e32 v[254:255], v[180:181]
	v_add_u32_e32 v138, 0x400, v138
	global_load_short_d16_hi v232, v136, s[24:25]
	global_load_short_d16_hi v233, v136, s[24:25] offset:1024
	global_load_short_d16_hi v234, v137, s[24:25]
	global_load_short_d16_hi v235, v137, s[24:25] offset:128
	v_add_u32_e32 v136, 0x1000, v136
	v_add_u32_e32 v137, 0x1000, v137
	s_cmp_eq_u32 s37, s5
	s_cselect_b32 s4, 0, -1
	ds_read_b128 v[192:195], v135 offset:64
	ds_read_b128 v[196:199], v135 offset:80
	ds_read_b128 v[200:203], v135 offset:96
	ds_read_b128 v[204:207], v135 offset:112
	ds_read_b128 v[208:211], v135 offset:320
	ds_read_b128 v[212:215], v135 offset:336
	ds_read_b128 v[216:219], v135 offset:352
	ds_read_b128 v[220:223], v135 offset:368
	s_waitcnt lgkmcnt(8)
	v_pk_fma_f32 v[0:1], v[148:149], v[0:1], v[250:251] op_sel_hi:[1,1,0]
	v_pk_fma_f32 v[2:3], v[150:151], v[2:3], v[250:251] op_sel_hi:[1,1,0]
	v_pk_fma_f32 v[4:5], v[152:153], v[4:5], v[250:251] op_sel_hi:[1,1,0]
	v_pk_fma_f32 v[6:7], v[154:155], v[6:7], v[250:251] op_sel_hi:[1,1,0]
	v_pk_fma_f32 v[240:241], v[0:1], v[164:165], 0 op_sel_hi:[1,1,0]
	v_pk_fma_f32 v[244:245], v[2:3], v[166:167], 0 op_sel_hi:[1,1,0]
	v_pk_fma_f32 v[240:241], v[4:5], v[168:169], v[240:241]
	v_pk_fma_f32 v[244:245], v[6:7], v[170:171], v[244:245]
	v_pk_fma_f32 v[8:9], v[156:157], v[8:9], v[250:251] op_sel_hi:[1,1,0]
	v_pk_fma_f32 v[10:11], v[158:159], v[10:11], v[250:251] op_sel_hi:[1,1,0]
	v_pk_fma_f32 v[12:13], v[160:161], v[12:13], v[250:251] op_sel_hi:[1,1,0]
	v_pk_fma_f32 v[14:15], v[162:163], v[14:15], v[250:251] op_sel_hi:[1,1,0]
	v_pk_fma_f32 v[240:241], v[8:9], v[172:173], v[240:241]
	v_pk_fma_f32 v[244:245], v[10:11], v[174:175], v[244:245]
	v_pk_fma_f32 v[240:241], v[12:13], v[176:177], v[240:241]
	v_pk_fma_f32 v[244:245], v[14:15], v[178:179], v[244:245]
	v_pk_fma_f32 v[64:65], v[148:149], v[64:65], v[250:251] op_sel:[0,0,1] op_sel_hi:[1,1,1]
	v_pk_fma_f32 v[66:67], v[150:151], v[66:67], v[250:251] op_sel:[0,0,1] op_sel_hi:[1,1,1]
	v_pk_fma_f32 v[68:69], v[152:153], v[68:69], v[250:251] op_sel:[0,0,1] op_sel_hi:[1,1,1]
	v_pk_fma_f32 v[70:71], v[154:155], v[70:71], v[250:251] op_sel:[0,0,1] op_sel_hi:[1,1,1]
	v_pk_fma_f32 v[246:247], v[64:65], v[164:165], 0 op_sel_hi:[1,1,0]
	v_pk_fma_f32 v[248:249], v[66:67], v[166:167], 0 op_sel_hi:[1,1,0]
	v_pk_fma_f32 v[246:247], v[68:69], v[168:169], v[246:247]
	v_pk_fma_f32 v[248:249], v[70:71], v[170:171], v[248:249]
	v_pk_fma_f32 v[72:73], v[156:157], v[72:73], v[250:251] op_sel:[0,0,1] op_sel_hi:[1,1,1]
	v_pk_fma_f32 v[74:75], v[158:159], v[74:75], v[250:251] op_sel:[0,0,1] op_sel_hi:[1,1,1]
	v_pk_fma_f32 v[76:77], v[160:161], v[76:77], v[250:251] op_sel:[0,0,1] op_sel_hi:[1,1,1]
	v_pk_fma_f32 v[78:79], v[162:163], v[78:79], v[250:251] op_sel:[0,0,1] op_sel_hi:[1,1,1]
	v_pk_fma_f32 v[246:247], v[72:73], v[172:173], v[246:247]
	v_pk_fma_f32 v[248:249], v[74:75], v[174:175], v[248:249]
	v_pk_fma_f32 v[246:247], v[76:77], v[176:177], v[246:247]
	v_pk_fma_f32 v[248:249], v[78:79], v[178:179], v[248:249]
	v_mul_f32_e32 v142, 0xbfb8aa3b, v237
	v_mul_f32_e32 v143, 0xbfb8aa3b, v236
	v_exp_f32_e32 v142, v142
	v_exp_f32_e32 v143, v143
	v_add_f32_e32 v142, 1.0, v142
	v_add_f32_e32 v143, 1.0, v143
	v_rcp_f32_e32 v142, v142
	v_rcp_f32_e32 v143, v143
	v_fma_f32 v142, v131, v142, v130
	v_mul_f32_e32 v143, v143, v236
	v_mul_f32_e32 v132, v132, v142
	ds_write2st64_b32 v134, v142, v143 offset0:2 offset1:3
	v_mov_b32_e32 v182, v143
	s_waitcnt vmcnt(12)
; __device__ __forceinline__ float bf2f(unsigned short b) { return __uint_as_float((unsigned)b << 16); }
; __device__ __forceinline__ unsigned short f2bf(float f) { unsigned u = __float_as_uint(f); u += 0x7FFFu + ((u >> 16) & 1u); return (unsigned short)(u >> 16); }
; __device__ __forceinline__ float sigm(float x) { return __builtin_amdgcn_rcpf(1.0f + __expf(-x)); }
; __device__ __forceinline__ f2 pfma(f2 a, f2 b, f2 c) { return __builtin_elementwise_fma(a, b, c); }
; __device__ __forceinline__ void hgrn_scan(const bf16_t* __restrict__ PH, int t0, int nsteps, int h, int half, int kh, int lane, float lb, f2 (&S)[32], float& cp, bf16_t* __restrict__ OHp, float* __restrict__ ckp, LAS float* L) {
;     ...
;     for (int s = 0; s < nsteps; ++s) {
;         const float ql = bf2f(q1[0]), fz = bf2f(q1[1]), v = bf2f(q1[2]);
; #pragma unroll
;         for (int j = 0; j < 3; ++j) { q1[j] = q2[j]; q2[j] = q3[j]; }
;         { const bf16_t* r = row + (size_t)(s + 3 < nsteps ? s + 3 : nsteps - 1) * 2048; q3[0] = r[0]; q3[1] = r[512]; q3[2] = r[voff]; }
;         const float fl = lb + (1.0f - lb) * sigm(fz);
;         cp *= fl;
;         if (ckp && (s & 31) == 31 && s < 127) ckp[(s >> 5) * 128 + lane] = cp;
;         L[lane] = fl; L[64 + lane] = ql * sigm(ql);
;         f32x4 F[2][4], Q[2][4];
; #pragma unroll
;         for (int i = 0; i < 4; ++i) { F[0][i] = pf[i]; Q[0][i] = pf[16 + i]; }
;         const f2 v2 = {v, v}; f2 o2 = {0.f, 0.f}, o3 = {0.f, 0.f};
; #pragma unroll
;         for (int g = 0; g < 4; ++g) {
;             if (g < 3) {
; #pragma unroll
;                 for (int i = 0; i < 4; ++i) { F[(g + 1) & 1][i] = pf[(g + 1) * 4 + i]; Q[(g + 1) & 1][i] = pf[16 + (g + 1) * 4 + i]; } }
;             __builtin_amdgcn_sched_barrier(0);
; #pragma unroll
;             for (int i = 0; i < 4; ++i) {
;                 const f32x4 f4 = F[g & 1][i], q4 = Q[g & 1][i]; const int idx = (g * 4 + i) * 2;
;                 const f2 f01 = {f4[0], f4[1]}, f23 = {f4[2], f4[3]}, q01 = {q4[0], q4[1]}, q23 = {q4[2], q4[3]};
;                 S[idx] = pfma(f01, S[idx] - v2, v2); o2 = pfma(S[idx], q01, o2);
;                 S[idx + 1] = pfma(f23, S[idx + 1] - v2, v2); o3 = pfma(S[idx + 1], q23, o3);
;             }
;         }
;         OHp[(size_t)(t0 + s) * 512 + h * 128 + half * 64 + lane] = f2bf((o2[0] + o2[1]) + (o3[0] + o3[1]));
;     }
	v_and_b32_e32 v180, s4, v226
	v_and_b32_e32 v181, s4, v227
	v_pk_add_f32 v[252:253], v[254:255], v[180:181] neg_lo:[0,1] neg_hi:[0,1]
	ds_read_b128 v[148:151], v135 offset:128
	ds_read_b128 v[152:155], v135 offset:144
	ds_read_b128 v[156:159], v135 offset:160
	ds_read_b128 v[160:163], v135 offset:176
	ds_read_b128 v[164:167], v135 offset:384
	ds_read_b128 v[168:171], v135 offset:400
	ds_read_b128 v[172:175], v135 offset:416
	ds_read_b128 v[176:179], v135 offset:432
	v_add_f32_dpp v182, v182, v182 quad_perm:[1,0,3,2] row_mask:0xf bank_mask:0xf bound_ctrl:1
	s_waitcnt lgkmcnt(9)
	v_pk_fma_f32 v[16:17], v[192:193], v[16:17], v[250:251] op_sel_hi:[1,1,0]
	v_pk_fma_f32 v[18:19], v[194:195], v[18:19], v[250:251] op_sel_hi:[1,1,0]
	v_pk_fma_f32 v[20:21], v[196:197], v[20:21], v[250:251] op_sel_hi:[1,1,0]
	v_pk_fma_f32 v[22:23], v[198:199], v[22:23], v[250:251] op_sel_hi:[1,1,0]
	v_pk_fma_f32 v[240:241], v[16:17], v[208:209], v[240:241]
	v_pk_fma_f32 v[244:245], v[18:19], v[210:211], v[244:245]
	v_pk_fma_f32 v[240:241], v[20:21], v[212:213], v[240:241]
	v_pk_fma_f32 v[244:245], v[22:23], v[214:215], v[244:245]
	v_pk_fma_f32 v[24:25], v[200:201], v[24:25], v[250:251] op_sel_hi:[1,1,0]
	v_pk_fma_f32 v[26:27], v[202:203], v[26:27], v[250:251] op_sel_hi:[1,1,0]
	v_pk_fma_f32 v[28:29], v[204:205], v[28:29], v[250:251] op_sel_hi:[1,1,0]
	v_pk_fma_f32 v[30:31], v[206:207], v[30:31], v[250:251] op_sel_hi:[1,1,0]
	v_pk_fma_f32 v[240:241], v[24:25], v[216:217], v[240:241]
	v_pk_fma_f32 v[244:245], v[26:27], v[218:219], v[244:245]
	v_pk_fma_f32 v[240:241], v[28:29], v[220:221], v[240:241]
	v_pk_fma_f32 v[244:245], v[30:31], v[222:223], v[244:245]
	v_pk_fma_f32 v[80:81], v[192:193], v[80:81], v[250:251] op_sel:[0,0,1] op_sel_hi:[1,1,1]
	v_pk_fma_f32 v[82:83], v[194:195], v[82:83], v[250:251] op_sel:[0,0,1] op_sel_hi:[1,1,1]
	v_pk_fma_f32 v[84:85], v[196:197], v[84:85], v[250:251] op_sel:[0,0,1] op_sel_hi:[1,1,1]
	v_pk_fma_f32 v[86:87], v[198:199], v[86:87], v[250:251] op_sel:[0,0,1] op_sel_hi:[1,1,1]
	v_pk_fma_f32 v[246:247], v[80:81], v[208:209], v[246:247]
	v_pk_fma_f32 v[248:249], v[82:83], v[210:211], v[248:249]
	v_pk_fma_f32 v[246:247], v[84:85], v[212:213], v[246:247]
	v_pk_fma_f32 v[248:249], v[86:87], v[214:215], v[248:249]
	v_pk_fma_f32 v[88:89], v[200:201], v[88:89], v[250:251] op_sel:[0,0,1] op_sel_hi:[1,1,1]
	v_pk_fma_f32 v[90:91], v[202:203], v[90:91], v[250:251] op_sel:[0,0,1] op_sel_hi:[1,1,1]
	v_pk_fma_f32 v[92:93], v[204:205], v[92:93], v[250:251] op_sel:[0,0,1] op_sel_hi:[1,1,1]
	v_pk_fma_f32 v[94:95], v[206:207], v[94:95], v[250:251] op_sel:[0,0,1] op_sel_hi:[1,1,1]
	v_pk_fma_f32 v[246:247], v[88:89], v[216:217], v[246:247]
	v_pk_fma_f32 v[248:249], v[90:91], v[218:219], v[248:249]
	v_pk_fma_f32 v[246:247], v[92:93], v[220:221], v[246:247]
	v_pk_fma_f32 v[248:249], v[94:95], v[222:223], v[248:249]
	v_add_f32_dpp v182, v182, v182 quad_perm:[2,3,0,1] row_mask:0xf bank_mask:0xf bound_ctrl:1
	ds_read_b128 v[192:195], v135 offset:192
	ds_read_b128 v[196:199], v135 offset:208
	ds_read_b128 v[200:203], v135 offset:224
	ds_read_b128 v[204:207], v135 offset:240
	ds_read_b128 v[208:211], v135 offset:448
	ds_read_b128 v[212:215], v135 offset:464
	ds_read_b128 v[216:219], v135 offset:480
	ds_read_b128 v[220:223], v135 offset:496
	v_add_f32_dpp v182, v182, v182 row_half_mirror row_mask:0xf bank_mask:0xf bound_ctrl:1
	s_waitcnt lgkmcnt(8)
	v_pk_fma_f32 v[32:33], v[148:149], v[32:33], v[250:251] op_sel_hi:[1,1,0]
	v_pk_fma_f32 v[34:35], v[150:151], v[34:35], v[250:251] op_sel_hi:[1,1,0]
	v_pk_fma_f32 v[36:37], v[152:153], v[36:37], v[250:251] op_sel_hi:[1,1,0]
	v_pk_fma_f32 v[38:39], v[154:155], v[38:39], v[250:251] op_sel_hi:[1,1,0]
	v_pk_fma_f32 v[240:241], v[32:33], v[164:165], v[240:241]
	v_pk_fma_f32 v[244:245], v[34:35], v[166:167], v[244:245]
	v_pk_fma_f32 v[240:241], v[36:37], v[168:169], v[240:241]
	v_pk_fma_f32 v[244:245], v[38:39], v[170:171], v[244:245]
	v_pk_fma_f32 v[40:41], v[156:157], v[40:41], v[250:251] op_sel_hi:[1,1,0]
	v_pk_fma_f32 v[42:43], v[158:159], v[42:43], v[250:251] op_sel_hi:[1,1,0]
	v_pk_fma_f32 v[44:45], v[160:161], v[44:45], v[250:251] op_sel_hi:[1,1,0]
	v_pk_fma_f32 v[46:47], v[162:163], v[46:47], v[250:251] op_sel_hi:[1,1,0]
	v_pk_fma_f32 v[240:241], v[40:41], v[172:173], v[240:241]
	v_pk_fma_f32 v[244:245], v[42:43], v[174:175], v[244:245]
	v_pk_fma_f32 v[240:241], v[44:45], v[176:177], v[240:241]
	v_pk_fma_f32 v[244:245], v[46:47], v[178:179], v[244:245]
	v_pk_fma_f32 v[96:97], v[148:149], v[96:97], v[250:251] op_sel:[0,0,1] op_sel_hi:[1,1,1]
	v_pk_fma_f32 v[98:99], v[150:151], v[98:99], v[250:251] op_sel:[0,0,1] op_sel_hi:[1,1,1]
	v_pk_fma_f32 v[100:101], v[152:153], v[100:101], v[250:251] op_sel:[0,0,1] op_sel_hi:[1,1,1]
	v_pk_fma_f32 v[102:103], v[154:155], v[102:103], v[250:251] op_sel:[0,0,1] op_sel_hi:[1,1,1]
	v_pk_fma_f32 v[246:247], v[96:97], v[164:165], v[246:247]
	v_pk_fma_f32 v[248:249], v[98:99], v[166:167], v[248:249]
	v_pk_fma_f32 v[246:247], v[100:101], v[168:169], v[246:247]
	v_pk_fma_f32 v[248:249], v[102:103], v[170:171], v[248:249]
	v_pk_fma_f32 v[104:105], v[156:157], v[104:105], v[250:251] op_sel:[0,0,1] op_sel_hi:[1,1,1]
	v_pk_fma_f32 v[106:107], v[158:159], v[106:107], v[250:251] op_sel:[0,0,1] op_sel_hi:[1,1,1]
	v_pk_fma_f32 v[108:109], v[160:161], v[108:109], v[250:251] op_sel:[0,0,1] op_sel_hi:[1,1,1]
	v_pk_fma_f32 v[110:111], v[162:163], v[110:111], v[250:251] op_sel:[0,0,1] op_sel_hi:[1,1,1]
	v_pk_fma_f32 v[246:247], v[104:105], v[172:173], v[246:247]
	v_pk_fma_f32 v[248:249], v[106:107], v[174:175], v[248:249]
	v_pk_fma_f32 v[246:247], v[108:109], v[176:177], v[246:247]
	v_pk_fma_f32 v[248:249], v[110:111], v[178:179], v[248:249]
	v_add_f32_dpp v182, v182, v182 row_mirror row_mask:0xf bank_mask:0xf bound_ctrl:1
	ds_read_b128 v[148:151], v135 offset:512
	ds_read_b128 v[152:155], v135 offset:528
	ds_read_b128 v[156:159], v135 offset:544
	ds_read_b128 v[160:163], v135 offset:560
	ds_read_b128 v[164:167], v135 offset:768
	ds_read_b128 v[168:171], v135 offset:784
	ds_read_b128 v[172:175], v135 offset:800
	ds_read_b128 v[176:179], v135 offset:816
	v_readlane_b32 s0, v182, 0
	v_readlane_b32 s1, v182, 16
	v_readlane_b32 s6, v182, 32
	v_readlane_b32 s7, v182, 48
	s_waitcnt lgkmcnt(8)
; __device__ __forceinline__ float bf2f(unsigned short b) { return __uint_as_float((unsigned)b << 16); }
; __device__ __forceinline__ unsigned short f2bf(float f) { unsigned u = __float_as_uint(f); u += 0x7FFFu + ((u >> 16) & 1u); return (unsigned short)(u >> 16); }
; __device__ __forceinline__ float sigm(float x) { return __builtin_amdgcn_rcpf(1.0f + __expf(-x)); }
; __device__ __forceinline__ f2 pfma(f2 a, f2 b, f2 c) { return __builtin_elementwise_fma(a, b, c); }
; __device__ __forceinline__ void hgrn_scan(const bf16_t* __restrict__ PH, int t0, int nsteps, int h, int half, int kh, int lane, float lb, f2 (&S)[32], float& cp, bf16_t* __restrict__ OHp, float* __restrict__ ckp, LAS float* L) {
;     ...
;     for (int s = 0; s < nsteps; ++s) {
;         const float ql = bf2f(q1[0]), fz = bf2f(q1[1]), v = bf2f(q1[2]);
; #pragma unroll
;         for (int j = 0; j < 3; ++j) { q1[j] = q2[j]; q2[j] = q3[j]; }
;         { const bf16_t* r = row + (size_t)(s + 3 < nsteps ? s + 3 : nsteps - 1) * 2048; q3[0] = r[0]; q3[1] = r[512]; q3[2] = r[voff]; }
;         const float fl = lb + (1.0f - lb) * sigm(fz);
;         cp *= fl;
;         if (ckp && (s & 31) == 31 && s < 127) ckp[(s >> 5) * 128 + lane] = cp;
;         L[lane] = fl; L[64 + lane] = ql * sigm(ql);
;         f32x4 F[2][4], Q[2][4];
; #pragma unroll
;         for (int i = 0; i < 4; ++i) { F[0][i] = pf[i]; Q[0][i] = pf[16 + i]; }
;         const f2 v2 = {v, v}; f2 o2 = {0.f, 0.f}, o3 = {0.f, 0.f};
; #pragma unroll
;         for (int g = 0; g < 4; ++g) {
;             if (g < 3) {
; #pragma unroll
;                 for (int i = 0; i < 4; ++i) { F[(g + 1) & 1][i] = pf[(g + 1) * 4 + i]; Q[(g + 1) & 1][i] = pf[16 + (g + 1) * 4 + i]; } }
;             __builtin_amdgcn_sched_barrier(0);
; #pragma unroll
;             for (int i = 0; i < 4; ++i) {
;                 const f32x4 f4 = F[g & 1][i], q4 = Q[g & 1][i]; const int idx = (g * 4 + i) * 2;
;                 const f2 f01 = {f4[0], f4[1]}, f23 = {f4[2], f4[3]}, q01 = {q4[0], q4[1]}, q23 = {q4[2], q4[3]};
;                 S[idx] = pfma(f01, S[idx] - v2, v2); o2 = pfma(S[idx], q01, o2);
;                 S[idx + 1] = pfma(f23, S[idx + 1] - v2, v2); o3 = pfma(S[idx + 1], q23, o3);
;             }
;         }
;         OHp[(size_t)(t0 + s) * 512 + h * 128 + half * 64 + lane] = f2bf((o2[0] + o2[1]) + (o3[0] + o3[1]));
;     }
	v_pk_fma_f32 v[48:49], v[192:193], v[48:49], v[250:251] op_sel_hi:[1,1,0]
	v_pk_fma_f32 v[50:51], v[194:195], v[50:51], v[250:251] op_sel_hi:[1,1,0]
	v_pk_fma_f32 v[52:53], v[196:197], v[52:53], v[250:251] op_sel_hi:[1,1,0]
	v_pk_fma_f32 v[54:55], v[198:199], v[54:55], v[250:251] op_sel_hi:[1,1,0]
	v_pk_fma_f32 v[240:241], v[48:49], v[208:209], v[240:241]
	v_pk_fma_f32 v[244:245], v[50:51], v[210:211], v[244:245]
	v_pk_fma_f32 v[240:241], v[52:53], v[212:213], v[240:241]
	v_pk_fma_f32 v[244:245], v[54:55], v[214:215], v[244:245]
	v_pk_fma_f32 v[56:57], v[200:201], v[56:57], v[250:251] op_sel_hi:[1,1,0]
	v_pk_fma_f32 v[58:59], v[202:203], v[58:59], v[250:251] op_sel_hi:[1,1,0]
	v_pk_fma_f32 v[60:61], v[204:205], v[60:61], v[250:251] op_sel_hi:[1,1,0]
	v_pk_fma_f32 v[62:63], v[206:207], v[62:63], v[250:251] op_sel_hi:[1,1,0]
	v_pk_fma_f32 v[240:241], v[56:57], v[216:217], v[240:241]
	v_pk_fma_f32 v[244:245], v[58:59], v[218:219], v[244:245]
	v_pk_fma_f32 v[240:241], v[60:61], v[220:221], v[240:241]
	v_pk_fma_f32 v[244:245], v[62:63], v[222:223], v[244:245]
	v_pk_fma_f32 v[112:113], v[192:193], v[112:113], v[250:251] op_sel:[0,0,1] op_sel_hi:[1,1,1]
	v_pk_fma_f32 v[114:115], v[194:195], v[114:115], v[250:251] op_sel:[0,0,1] op_sel_hi:[1,1,1]
	v_pk_fma_f32 v[116:117], v[196:197], v[116:117], v[250:251] op_sel:[0,0,1] op_sel_hi:[1,1,1]
	v_pk_fma_f32 v[118:119], v[198:199], v[118:119], v[250:251] op_sel:[0,0,1] op_sel_hi:[1,1,1]
	v_pk_fma_f32 v[246:247], v[112:113], v[208:209], v[246:247]
	v_pk_fma_f32 v[248:249], v[114:115], v[210:211], v[248:249]
	v_pk_fma_f32 v[246:247], v[116:117], v[212:213], v[246:247]
	v_pk_fma_f32 v[248:249], v[118:119], v[214:215], v[248:249]
	v_pk_fma_f32 v[120:121], v[200:201], v[120:121], v[250:251] op_sel:[0,0,1] op_sel_hi:[1,1,1]
	v_pk_fma_f32 v[122:123], v[202:203], v[122:123], v[250:251] op_sel:[0,0,1] op_sel_hi:[1,1,1]
	v_pk_fma_f32 v[124:125], v[204:205], v[124:125], v[250:251] op_sel:[0,0,1] op_sel_hi:[1,1,1]
	v_pk_fma_f32 v[126:127], v[206:207], v[126:127], v[250:251] op_sel:[0,0,1] op_sel_hi:[1,1,1]
	v_pk_fma_f32 v[246:247], v[120:121], v[216:217], v[246:247]
	v_pk_fma_f32 v[248:249], v[122:123], v[218:219], v[248:249]
	v_pk_fma_f32 v[246:247], v[124:125], v[220:221], v[246:247]
	v_pk_fma_f32 v[248:249], v[126:127], v[222:223], v[248:249]
	v_mov_b32_e32 v183, s0
	v_add_f32_e32 v183, s1, v183
	v_add_f32_e32 v183, s6, v183
	v_add_f32_e32 v183, s7, v183
	v_add_f32_e32 v240, v240, v241
	v_add_f32_e32 v244, v244, v245
	v_add_f32_e32 v240, v240, v244
	v_fmac_f32_e32 v240, s2, v254
	v_bfe_u32 v244, v240, 16, 1
	v_add3_u32 v240, v240, v244, s69
	global_store_short_d16_hi v138, v240, s[26:27]
	v_add_f32_e32 v246, v246, v247
	v_add_f32_e32 v248, v248, v249
	v_add_f32_e32 v246, v246, v248
	v_fmac_f32_e32 v246, s2, v255
	v_bfe_u32 v248, v246, 16, 1
	v_add3_u32 v246, v246, v248, s69
	global_store_short_d16_hi v138, v246, s[26:27] offset:128
	v_readfirstlane_b32 s2, v183
	v_mov_b64_e32 v[250:251], v[252:253]
	v_mov_b64_e32 v[254:255], v[180:181]
	v_add_u32_e32 v138, 0x400, v138
	global_load_short_d16_hi v236, v136, s[24:25]
	global_load_short_d16_hi v237, v136, s[24:25] offset:1024
	global_load_short_d16_hi v238, v137, s[24:25]
	global_load_short_d16_hi v239, v137, s[24:25] offset:128
	v_add_u32_e32 v136, 0x1000, v136
	v_add_u32_e32 v137, 0x1000, v137
	v_mov_b32_e32 v133, v132
	s_cmp_lg_u32 s36, 32
	s_cbranch_scc1 .Lhs_m_nock
	s_and_b32 s0, s37, 7
	s_cmp_lg_u32 s0, 7
	s_cbranch_scc1 .Lhs_m_nock
	s_cmp_eq_u32 s37, 31
	s_cbranch_scc1 .Lhs_m_nock
	s_lshr_b32 s0, s37, 3
	s_lshl_b32 s0, s0, 9
	s_add_u32 s0, s42, s0
	s_addc_u32 s1, s43, 0
	global_store_dword v147, v133, s[0:1]
.Lhs_m_nock:
	s_cmp_eq_u32 s37, s5
	s_cselect_b32 s4, 0, -1
	ds_read_b128 v[192:195], v135 offset:576
	ds_read_b128 v[196:199], v135 offset:592
	ds_read_b128 v[200:203], v135 offset:608
	ds_read_b128 v[204:207], v135 offset:624
	ds_read_b128 v[208:211], v135 offset:832
	ds_read_b128 v[212:215], v135 offset:848
	ds_read_b128 v[216:219], v135 offset:864
	ds_read_b128 v[220:223], v135 offset:880
	s_waitcnt lgkmcnt(8)
	v_pk_fma_f32 v[0:1], v[148:149], v[0:1], v[250:251] op_sel_hi:[1,1,0]
	v_pk_fma_f32 v[2:3], v[150:151], v[2:3], v[250:251] op_sel_hi:[1,1,0]
	v_pk_fma_f32 v[4:5], v[152:153], v[4:5], v[250:251] op_sel_hi:[1,1,0]
	v_pk_fma_f32 v[6:7], v[154:155], v[6:7], v[250:251] op_sel_hi:[1,1,0]
	v_pk_fma_f32 v[240:241], v[0:1], v[164:165], 0 op_sel_hi:[1,1,0]
	v_pk_fma_f32 v[244:245], v[2:3], v[166:167], 0 op_sel_hi:[1,1,0]
	v_pk_fma_f32 v[240:241], v[4:5], v[168:169], v[240:241]
	v_pk_fma_f32 v[244:245], v[6:7], v[170:171], v[244:245]
	v_pk_fma_f32 v[8:9], v[156:157], v[8:9], v[250:251] op_sel_hi:[1,1,0]
	v_pk_fma_f32 v[10:11], v[158:159], v[10:11], v[250:251] op_sel_hi:[1,1,0]
	v_pk_fma_f32 v[12:13], v[160:161], v[12:13], v[250:251] op_sel_hi:[1,1,0]
	v_pk_fma_f32 v[14:15], v[162:163], v[14:15], v[250:251] op_sel_hi:[1,1,0]
	v_pk_fma_f32 v[240:241], v[8:9], v[172:173], v[240:241]
	v_pk_fma_f32 v[244:245], v[10:11], v[174:175], v[244:245]
	v_pk_fma_f32 v[240:241], v[12:13], v[176:177], v[240:241]
	v_pk_fma_f32 v[244:245], v[14:15], v[178:179], v[244:245]
	v_pk_fma_f32 v[64:65], v[148:149], v[64:65], v[250:251] op_sel:[0,0,1] op_sel_hi:[1,1,1]
	v_pk_fma_f32 v[66:67], v[150:151], v[66:67], v[250:251] op_sel:[0,0,1] op_sel_hi:[1,1,1]
	v_pk_fma_f32 v[68:69], v[152:153], v[68:69], v[250:251] op_sel:[0,0,1] op_sel_hi:[1,1,1]
	v_pk_fma_f32 v[70:71], v[154:155], v[70:71], v[250:251] op_sel:[0,0,1] op_sel_hi:[1,1,1]
	v_pk_fma_f32 v[246:247], v[64:65], v[164:165], 0 op_sel_hi:[1,1,0]
	v_pk_fma_f32 v[248:249], v[66:67], v[166:167], 0 op_sel_hi:[1,1,0]
	v_pk_fma_f32 v[246:247], v[68:69], v[168:169], v[246:247]
	v_pk_fma_f32 v[248:249], v[70:71], v[170:171], v[248:249]
	v_pk_fma_f32 v[72:73], v[156:157], v[72:73], v[250:251] op_sel:[0,0,1] op_sel_hi:[1,1,1]
	v_pk_fma_f32 v[74:75], v[158:159], v[74:75], v[250:251] op_sel:[0,0,1] op_sel_hi:[1,1,1]
	v_pk_fma_f32 v[76:77], v[160:161], v[76:77], v[250:251] op_sel:[0,0,1] op_sel_hi:[1,1,1]
	v_pk_fma_f32 v[78:79], v[162:163], v[78:79], v[250:251] op_sel:[0,0,1] op_sel_hi:[1,1,1]
	v_pk_fma_f32 v[246:247], v[72:73], v[172:173], v[246:247]
	v_pk_fma_f32 v[248:249], v[74:75], v[174:175], v[248:249]
	v_pk_fma_f32 v[246:247], v[76:77], v[176:177], v[246:247]
	v_pk_fma_f32 v[248:249], v[78:79], v[178:179], v[248:249]
	v_mul_f32_e32 v142, 0xbfb8aa3b, v225
	v_mul_f32_e32 v143, 0xbfb8aa3b, v224
	v_exp_f32_e32 v142, v142
	v_exp_f32_e32 v143, v143
	v_add_f32_e32 v142, 1.0, v142
	v_add_f32_e32 v143, 1.0, v143
	v_rcp_f32_e32 v142, v142
	v_rcp_f32_e32 v143, v143
	v_fma_f32 v142, v131, v142, v130
	v_mul_f32_e32 v143, v143, v224
	v_mul_f32_e32 v132, v132, v142
	ds_write2st64_b32 v134, v142, v143 offset0:0 offset1:1
	v_mov_b32_e32 v182, v143
	s_waitcnt vmcnt(12)
; __device__ __forceinline__ float bf2f(unsigned short b) { return __uint_as_float((unsigned)b << 16); }
; __device__ __forceinline__ unsigned short f2bf(float f) { unsigned u = __float_as_uint(f); u += 0x7FFFu + ((u >> 16) & 1u); return (unsigned short)(u >> 16); }
; __device__ __forceinline__ float sigm(float x) { return __builtin_amdgcn_rcpf(1.0f + __expf(-x)); }
; __device__ __forceinline__ f2 pfma(f2 a, f2 b, f2 c) { return __builtin_elementwise_fma(a, b, c); }
; __device__ __forceinline__ void hgrn_scan(const bf16_t* __restrict__ PH, int t0, int nsteps, int h, int half, int kh, int lane, float lb, f2 (&S)[32], float& cp, bf16_t* __restrict__ OHp, float* __restrict__ ckp, LAS float* L) {
;     ...
;     for (int s = 0; s < nsteps; ++s) {
;         const float ql = bf2f(q1[0]), fz = bf2f(q1[1]), v = bf2f(q1[2]);
; #pragma unroll
;         for (int j = 0; j < 3; ++j) { q1[j] = q2[j]; q2[j] = q3[j]; }
;         { const bf16_t* r = row + (size_t)(s + 3 < nsteps ? s + 3 : nsteps - 1) * 2048; q3[0] = r[0]; q3[1] = r[512]; q3[2] = r[voff]; }
;         const float fl = lb + (1.0f - lb) * sigm(fz);
;         cp *= fl;
;         if (ckp && (s & 31) == 31 && s < 127) ckp[(s >> 5) * 128 + lane] = cp;
;         L[lane] = fl; L[64 + lane] = ql * sigm(ql);
;         f32x4 F[2][4], Q[2][4];
; #pragma unroll
;         for (int i = 0; i < 4; ++i) { F[0][i] = pf[i]; Q[0][i] = pf[16 + i]; }
;         const f2 v2 = {v, v}; f2 o2 = {0.f, 0.f}, o3 = {0.f, 0.f};
; #pragma unroll
;         for (int g = 0; g < 4; ++g) {
;             if (g < 3) {
; #pragma unroll
;                 for (int i = 0; i < 4; ++i) { F[(g + 1) & 1][i] = pf[(g + 1) * 4 + i]; Q[(g + 1) & 1][i] = pf[16 + (g + 1) * 4 + i]; } }
;             __builtin_amdgcn_sched_barrier(0);
; #pragma unroll
;             for (int i = 0; i < 4; ++i) {
;                 const f32x4 f4 = F[g & 1][i], q4 = Q[g & 1][i]; const int idx = (g * 4 + i) * 2;
;                 const f2 f01 = {f4[0], f4[1]}, f23 = {f4[2], f4[3]}, q01 = {q4[0], q4[1]}, q23 = {q4[2], q4[3]};
;                 S[idx] = pfma(f01, S[idx] - v2, v2); o2 = pfma(S[idx], q01, o2);
;                 S[idx + 1] = pfma(f23, S[idx + 1] - v2, v2); o3 = pfma(S[idx + 1], q23, o3);
;             }
;         }
;         OHp[(size_t)(t0 + s) * 512 + h * 128 + half * 64 + lane] = f2bf((o2[0] + o2[1]) + (o3[0] + o3[1]));
;     }
	v_and_b32_e32 v180, s4, v230
	v_and_b32_e32 v181, s4, v231
	v_pk_add_f32 v[252:253], v[254:255], v[180:181] neg_lo:[0,1] neg_hi:[0,1]
	ds_read_b128 v[148:151], v135 offset:640
	ds_read_b128 v[152:155], v135 offset:656
	ds_read_b128 v[156:159], v135 offset:672
	ds_read_b128 v[160:163], v135 offset:688
	ds_read_b128 v[164:167], v135 offset:896
	ds_read_b128 v[168:171], v135 offset:912
	ds_read_b128 v[172:175], v135 offset:928
	ds_read_b128 v[176:179], v135 offset:944
	v_add_f32_dpp v182, v182, v182 quad_perm:[1,0,3,2] row_mask:0xf bank_mask:0xf bound_ctrl:1
	s_waitcnt lgkmcnt(9)
	v_pk_fma_f32 v[16:17], v[192:193], v[16:17], v[250:251] op_sel_hi:[1,1,0]
	v_pk_fma_f32 v[18:19], v[194:195], v[18:19], v[250:251] op_sel_hi:[1,1,0]
	v_pk_fma_f32 v[20:21], v[196:197], v[20:21], v[250:251] op_sel_hi:[1,1,0]
	v_pk_fma_f32 v[22:23], v[198:199], v[22:23], v[250:251] op_sel_hi:[1,1,0]
	v_pk_fma_f32 v[240:241], v[16:17], v[208:209], v[240:241]
	v_pk_fma_f32 v[244:245], v[18:19], v[210:211], v[244:245]
	v_pk_fma_f32 v[240:241], v[20:21], v[212:213], v[240:241]
	v_pk_fma_f32 v[244:245], v[22:23], v[214:215], v[244:245]
	v_pk_fma_f32 v[24:25], v[200:201], v[24:25], v[250:251] op_sel_hi:[1,1,0]
	v_pk_fma_f32 v[26:27], v[202:203], v[26:27], v[250:251] op_sel_hi:[1,1,0]
	v_pk_fma_f32 v[28:29], v[204:205], v[28:29], v[250:251] op_sel_hi:[1,1,0]
	v_pk_fma_f32 v[30:31], v[206:207], v[30:31], v[250:251] op_sel_hi:[1,1,0]
	v_pk_fma_f32 v[240:241], v[24:25], v[216:217], v[240:241]
	v_pk_fma_f32 v[244:245], v[26:27], v[218:219], v[244:245]
	v_pk_fma_f32 v[240:241], v[28:29], v[220:221], v[240:241]
	v_pk_fma_f32 v[244:245], v[30:31], v[222:223], v[244:245]
	v_pk_fma_f32 v[80:81], v[192:193], v[80:81], v[250:251] op_sel:[0,0,1] op_sel_hi:[1,1,1]
	v_pk_fma_f32 v[82:83], v[194:195], v[82:83], v[250:251] op_sel:[0,0,1] op_sel_hi:[1,1,1]
	v_pk_fma_f32 v[84:85], v[196:197], v[84:85], v[250:251] op_sel:[0,0,1] op_sel_hi:[1,1,1]
	v_pk_fma_f32 v[86:87], v[198:199], v[86:87], v[250:251] op_sel:[0,0,1] op_sel_hi:[1,1,1]
	v_pk_fma_f32 v[246:247], v[80:81], v[208:209], v[246:247]
	v_pk_fma_f32 v[248:249], v[82:83], v[210:211], v[248:249]
	v_pk_fma_f32 v[246:247], v[84:85], v[212:213], v[246:247]
	v_pk_fma_f32 v[248:249], v[86:87], v[214:215], v[248:249]
	v_pk_fma_f32 v[88:89], v[200:201], v[88:89], v[250:251] op_sel:[0,0,1] op_sel_hi:[1,1,1]
	v_pk_fma_f32 v[90:91], v[202:203], v[90:91], v[250:251] op_sel:[0,0,1] op_sel_hi:[1,1,1]
	v_pk_fma_f32 v[92:93], v[204:205], v[92:93], v[250:251] op_sel:[0,0,1] op_sel_hi:[1,1,1]
	v_pk_fma_f32 v[94:95], v[206:207], v[94:95], v[250:251] op_sel:[0,0,1] op_sel_hi:[1,1,1]
	v_pk_fma_f32 v[246:247], v[88:89], v[216:217], v[246:247]
	v_pk_fma_f32 v[248:249], v[90:91], v[218:219], v[248:249]
	v_pk_fma_f32 v[246:247], v[92:93], v[220:221], v[246:247]
	v_pk_fma_f32 v[248:249], v[94:95], v[222:223], v[248:249]
	v_add_f32_dpp v182, v182, v182 quad_perm:[2,3,0,1] row_mask:0xf bank_mask:0xf bound_ctrl:1
	ds_read_b128 v[192:195], v135 offset:704
	ds_read_b128 v[196:199], v135 offset:720
	ds_read_b128 v[200:203], v135 offset:736
	ds_read_b128 v[204:207], v135 offset:752
	ds_read_b128 v[208:211], v135 offset:960
	ds_read_b128 v[212:215], v135 offset:976
	ds_read_b128 v[216:219], v135 offset:992
	ds_read_b128 v[220:223], v135 offset:1008
	v_add_f32_dpp v182, v182, v182 row_half_mirror row_mask:0xf bank_mask:0xf bound_ctrl:1
	s_waitcnt lgkmcnt(8)
; __device__ __forceinline__ float bf2f(unsigned short b) { return __uint_as_float((unsigned)b << 16); }
; __device__ __forceinline__ unsigned short f2bf(float f) { unsigned u = __float_as_uint(f); u += 0x7FFFu + ((u >> 16) & 1u); return (unsigned short)(u >> 16); }
; __device__ __forceinline__ float sigm(float x) { return __builtin_amdgcn_rcpf(1.0f + __expf(-x)); }
; __device__ __forceinline__ f2 pfma(f2 a, f2 b, f2 c) { return __builtin_elementwise_fma(a, b, c); }
; __device__ __forceinline__ void hgrn_scan(const bf16_t* __restrict__ PH, int t0, int nsteps, int h, int half, int kh, int lane, float lb, f2 (&S)[32], float& cp, bf16_t* __restrict__ OHp, float* __restrict__ ckp, LAS float* L) {
;     ...
;     for (int s = 0; s < nsteps; ++s) {
;         const float ql = bf2f(q1[0]), fz = bf2f(q1[1]), v = bf2f(q1[2]);
; #pragma unroll
;         for (int j = 0; j < 3; ++j) { q1[j] = q2[j]; q2[j] = q3[j]; }
;         { const bf16_t* r = row + (size_t)(s + 3 < nsteps ? s + 3 : nsteps - 1) * 2048; q3[0] = r[0]; q3[1] = r[512]; q3[2] = r[voff]; }
;         const float fl = lb + (1.0f - lb) * sigm(fz);
;         cp *= fl;
;         if (ckp && (s & 31) == 31 && s < 127) ckp[(s >> 5) * 128 + lane] = cp;
;         L[lane] = fl; L[64 + lane] = ql * sigm(ql);
;         f32x4 F[2][4], Q[2][4];
; #pragma unroll
;         for (int i = 0; i < 4; ++i) { F[0][i] = pf[i]; Q[0][i] = pf[16 + i]; }
;         const f2 v2 = {v, v}; f2 o2 = {0.f, 0.f}, o3 = {0.f, 0.f};
; #pragma unroll
;         for (int g = 0; g < 4; ++g) {
;             if (g < 3) {
; #pragma unroll
;                 for (int i = 0; i < 4; ++i) { F[(g + 1) & 1][i] = pf[(g + 1) * 4 + i]; Q[(g + 1) & 1][i] = pf[16 + (g + 1) * 4 + i]; } }
;             __builtin_amdgcn_sched_barrier(0);
; #pragma unroll
;             for (int i = 0; i < 4; ++i) {
;                 const f32x4 f4 = F[g & 1][i], q4 = Q[g & 1][i]; const int idx = (g * 4 + i) * 2;
;                 const f2 f01 = {f4[0], f4[1]}, f23 = {f4[2], f4[3]}, q01 = {q4[0], q4[1]}, q23 = {q4[2], q4[3]};
;                 S[idx] = pfma(f01, S[idx] - v2, v2); o2 = pfma(S[idx], q01, o2);
;                 S[idx + 1] = pfma(f23, S[idx + 1] - v2, v2); o3 = pfma(S[idx + 1], q23, o3);
;             }
;         }
;         OHp[(size_t)(t0 + s) * 512 + h * 128 + half * 64 + lane] = f2bf((o2[0] + o2[1]) + (o3[0] + o3[1]));
;     }
	v_pk_fma_f32 v[32:33], v[148:149], v[32:33], v[250:251] op_sel_hi:[1,1,0]
	v_pk_fma_f32 v[34:35], v[150:151], v[34:35], v[250:251] op_sel_hi:[1,1,0]
	v_pk_fma_f32 v[36:37], v[152:153], v[36:37], v[250:251] op_sel_hi:[1,1,0]
	v_pk_fma_f32 v[38:39], v[154:155], v[38:39], v[250:251] op_sel_hi:[1,1,0]
	v_pk_fma_f32 v[240:241], v[32:33], v[164:165], v[240:241]
	v_pk_fma_f32 v[244:245], v[34:35], v[166:167], v[244:245]
	v_pk_fma_f32 v[240:241], v[36:37], v[168:169], v[240:241]
	v_pk_fma_f32 v[244:245], v[38:39], v[170:171], v[244:245]
	v_pk_fma_f32 v[40:41], v[156:157], v[40:41], v[250:251] op_sel_hi:[1,1,0]
	v_pk_fma_f32 v[42:43], v[158:159], v[42:43], v[250:251] op_sel_hi:[1,1,0]
	v_pk_fma_f32 v[44:45], v[160:161], v[44:45], v[250:251] op_sel_hi:[1,1,0]
	v_pk_fma_f32 v[46:47], v[162:163], v[46:47], v[250:251] op_sel_hi:[1,1,0]
	v_pk_fma_f32 v[240:241], v[40:41], v[172:173], v[240:241]
	v_pk_fma_f32 v[244:245], v[42:43], v[174:175], v[244:245]
	v_pk_fma_f32 v[240:241], v[44:45], v[176:177], v[240:241]
	v_pk_fma_f32 v[244:245], v[46:47], v[178:179], v[244:245]
	v_pk_fma_f32 v[96:97], v[148:149], v[96:97], v[250:251] op_sel:[0,0,1] op_sel_hi:[1,1,1]
	v_pk_fma_f32 v[98:99], v[150:151], v[98:99], v[250:251] op_sel:[0,0,1] op_sel_hi:[1,1,1]
	v_pk_fma_f32 v[100:101], v[152:153], v[100:101], v[250:251] op_sel:[0,0,1] op_sel_hi:[1,1,1]
	v_pk_fma_f32 v[102:103], v[154:155], v[102:103], v[250:251] op_sel:[0,0,1] op_sel_hi:[1,1,1]
	v_pk_fma_f32 v[246:247], v[96:97], v[164:165], v[246:247]
	v_pk_fma_f32 v[248:249], v[98:99], v[166:167], v[248:249]
	v_pk_fma_f32 v[246:247], v[100:101], v[168:169], v[246:247]
	v_pk_fma_f32 v[248:249], v[102:103], v[170:171], v[248:249]
	v_pk_fma_f32 v[104:105], v[156:157], v[104:105], v[250:251] op_sel:[0,0,1] op_sel_hi:[1,1,1]
	v_pk_fma_f32 v[106:107], v[158:159], v[106:107], v[250:251] op_sel:[0,0,1] op_sel_hi:[1,1,1]
	v_pk_fma_f32 v[108:109], v[160:161], v[108:109], v[250:251] op_sel:[0,0,1] op_sel_hi:[1,1,1]
	v_pk_fma_f32 v[110:111], v[162:163], v[110:111], v[250:251] op_sel:[0,0,1] op_sel_hi:[1,1,1]
	v_pk_fma_f32 v[246:247], v[104:105], v[172:173], v[246:247]
	v_pk_fma_f32 v[248:249], v[106:107], v[174:175], v[248:249]
	v_pk_fma_f32 v[246:247], v[108:109], v[176:177], v[246:247]
	v_pk_fma_f32 v[248:249], v[110:111], v[178:179], v[248:249]
	v_add_f32_dpp v182, v182, v182 row_mirror row_mask:0xf bank_mask:0xf bound_ctrl:1
	ds_read_b128 v[148:151], v135 offset:0
	ds_read_b128 v[152:155], v135 offset:16
	ds_read_b128 v[156:159], v135 offset:32
	ds_read_b128 v[160:163], v135 offset:48
	ds_read_b128 v[164:167], v135 offset:256
	ds_read_b128 v[168:171], v135 offset:272
	ds_read_b128 v[172:175], v135 offset:288
	ds_read_b128 v[176:179], v135 offset:304
	v_readlane_b32 s0, v182, 0
	v_readlane_b32 s1, v182, 16
	v_readlane_b32 s6, v182, 32
	v_readlane_b32 s7, v182, 48
	s_waitcnt lgkmcnt(8)
	v_pk_fma_f32 v[48:49], v[192:193], v[48:49], v[250:251] op_sel_hi:[1,1,0]
	v_pk_fma_f32 v[50:51], v[194:195], v[50:51], v[250:251] op_sel_hi:[1,1,0]
	v_pk_fma_f32 v[52:53], v[196:197], v[52:53], v[250:251] op_sel_hi:[1,1,0]
	v_pk_fma_f32 v[54:55], v[198:199], v[54:55], v[250:251] op_sel_hi:[1,1,0]
	v_pk_fma_f32 v[240:241], v[48:49], v[208:209], v[240:241]
	v_pk_fma_f32 v[244:245], v[50:51], v[210:211], v[244:245]
	v_pk_fma_f32 v[240:241], v[52:53], v[212:213], v[240:241]
	v_pk_fma_f32 v[244:245], v[54:55], v[214:215], v[244:245]
	v_pk_fma_f32 v[56:57], v[200:201], v[56:57], v[250:251] op_sel_hi:[1,1,0]
	v_pk_fma_f32 v[58:59], v[202:203], v[58:59], v[250:251] op_sel_hi:[1,1,0]
	v_pk_fma_f32 v[60:61], v[204:205], v[60:61], v[250:251] op_sel_hi:[1,1,0]
	v_pk_fma_f32 v[62:63], v[206:207], v[62:63], v[250:251] op_sel_hi:[1,1,0]
	v_pk_fma_f32 v[240:241], v[56:57], v[216:217], v[240:241]
	v_pk_fma_f32 v[244:245], v[58:59], v[218:219], v[244:245]
	v_pk_fma_f32 v[240:241], v[60:61], v[220:221], v[240:241]
	v_pk_fma_f32 v[244:245], v[62:63], v[222:223], v[244:245]
	v_pk_fma_f32 v[112:113], v[192:193], v[112:113], v[250:251] op_sel:[0,0,1] op_sel_hi:[1,1,1]
	v_pk_fma_f32 v[114:115], v[194:195], v[114:115], v[250:251] op_sel:[0,0,1] op_sel_hi:[1,1,1]
	v_pk_fma_f32 v[116:117], v[196:197], v[116:117], v[250:251] op_sel:[0,0,1] op_sel_hi:[1,1,1]
	v_pk_fma_f32 v[118:119], v[198:199], v[118:119], v[250:251] op_sel:[0,0,1] op_sel_hi:[1,1,1]
	v_pk_fma_f32 v[246:247], v[112:113], v[208:209], v[246:247]
	v_pk_fma_f32 v[248:249], v[114:115], v[210:211], v[248:249]
	v_pk_fma_f32 v[246:247], v[116:117], v[212:213], v[246:247]
	v_pk_fma_f32 v[248:249], v[118:119], v[214:215], v[248:249]
	v_pk_fma_f32 v[120:121], v[200:201], v[120:121], v[250:251] op_sel:[0,0,1] op_sel_hi:[1,1,1]
	v_pk_fma_f32 v[122:123], v[202:203], v[122:123], v[250:251] op_sel:[0,0,1] op_sel_hi:[1,1,1]
	v_pk_fma_f32 v[124:125], v[204:205], v[124:125], v[250:251] op_sel:[0,0,1] op_sel_hi:[1,1,1]
	v_pk_fma_f32 v[126:127], v[206:207], v[126:127], v[250:251] op_sel:[0,0,1] op_sel_hi:[1,1,1]
	v_pk_fma_f32 v[246:247], v[120:121], v[216:217], v[246:247]
	v_pk_fma_f32 v[248:249], v[122:123], v[218:219], v[248:249]
	v_pk_fma_f32 v[246:247], v[124:125], v[220:221], v[246:247]
	v_pk_fma_f32 v[248:249], v[126:127], v[222:223], v[248:249]
	v_mov_b32_e32 v183, s0
	v_add_f32_e32 v183, s1, v183
	v_add_f32_e32 v183, s6, v183
	v_add_f32_e32 v183, s7, v183
	v_add_f32_e32 v240, v240, v241
	v_add_f32_e32 v244, v244, v245
	v_add_f32_e32 v240, v240, v244
	v_fmac_f32_e32 v240, s2, v254
	v_bfe_u32 v244, v240, 16, 1
	v_add3_u32 v240, v240, v244, s69
	global_store_short_d16_hi v138, v240, s[26:27]
	v_add_f32_e32 v246, v246, v247
	v_add_f32_e32 v248, v248, v249
	v_add_f32_e32 v246, v246, v248
	v_fmac_f32_e32 v246, s2, v255
	v_bfe_u32 v248, v246, 16, 1
	v_add3_u32 v246, v246, v248, s69
	global_store_short_d16_hi v138, v246, s[26:27] offset:128
	v_readfirstlane_b32 s2, v183
	v_mov_b64_e32 v[250:251], v[252:253]
	v_mov_b64_e32 v[254:255], v[180:181]
	v_add_u32_e32 v138, 0x400, v138
	s_add_i32 s37, s37, 1
	s_cmp_lg_u32 s37, s36
	s_cbranch_scc1 .Lhs_m_loop
	s_waitcnt vmcnt(0) lgkmcnt(0)
	s_cmp_eq_u32 s38, 4
	s_cbranch_scc1 .Lhs_store
	global_store_dword v147, v133, s[44:45]

; __device__ __forceinline__ int bidx() { int b = blockIdx.x; asm volatile("" : "+s"(b)); return b; }
; #define INP(p, i) ldp((p).tbl, i)
; __device__ __forceinline__ float bf2f(unsigned short b) { return __uint_as_float((unsigned)b << 16); }
; template <bool ID> __device__ __forceinline__ void rwkv_scan(const bf16_t* __restrict__ R, const bf16_t* __restrict__ EW, const bf16_t* __restrict__ K, const bf16_t* __restrict__ V, ...
;     unsigned short q1[6], q2[6];
;     { unsigned o = base; q1[0] = R[o]; q1[1] = EW[o]; q1[2] = K[o]; q1[3] = V[o]; q1[4] = A[o]; q1[5] = B[o];
;       o = base + 512u; q2[0] = R[o]; q2[1] = EW[o]; q2[2] = K[o]; q2[3] = V[o]; q2[4] = A[o]; q2[5] = B[o]; }
;     const LAS f32x4* pa = (const LAS f32x4*)L;
;     float sav, sai;
;     { L[lane] = bf2f(q1[4]);
;       f2 av = {0.f, 0.f}, ai = {0.f, 0.f};
; #pragma unroll
;       for (int q = 0; q < 16; ++q) { const f32x4 a4 = pa[q]; const f2 a01 = {a4[0], a4[1]}, a23 = {a4[2], a4[3]};
;           av = pfma(Sv[2 * q], a01, av); av = pfma(Sv[2 * q + 1], a23, av); if (ID) { ai = pfma(Si[2 * q], a01, ai); ai = pfma(Si[2 * q + 1], a23, ai); } }
;       sav = av[0] + av[1]; sai = ai[0] + ai[1]; }
; #pragma unroll 1
;     for (int s = 0; s < nsteps; ++s) {
;         L[lane] = bf2f(q2[4]); L[64 + lane] = __expf(-bf2f(q1[1])); L[128 + lane] = bf2f(q1[5]); L[192 + lane] = bf2f(q1[2]); L[256 + lane] = bf2f(q1[0]);
;         const float v = bf2f(q1[3]);
; #pragma unroll
;         for (int j = 0; j < 6; ++j) q1[j] = q2[j];
;         { const unsigned o = base + (unsigned)(s + 2 < nsteps ? s + 2 : nsteps - 1) * 512u; q2[0] = R[o]; q2[1] = EW[o]; q2[2] = K[o]; q2[3] = V[o]; q2[4] = A[o]; q2[5] = B[o]; }
; __device__ void phase_rwkv_scan(const Ctx& p, int l, LAS unsigned char* lds) {
;     ...
;         for (int item = bidx(); item < 256; item += gridDim.x) {
;             const int s = item >> 3, h = item & 7;
;             const size_t so = (((size_t)l * 32 + s) * 8 + h) * 4096 + lane * 64;
;             f2 Sv[32], Si[32];
;             const float* sp = INP(p, 3) + so;
; #pragma unroll
;             for (int i = 0; i < 32; i += 2) { const float4 q = *(const float4*)(sp + 2 * i); Sv[i] = (f2){q.x, q.y}; Sv[i + 1] = (f2){q.z, q.w}; Si[i] = (f2){0.f, 0.f}; Si[i + 1] = (f2){0.f, 0.f}; }
;             rwkv_scan<false>(R, EW, K, V, A, B, (unsigned)((T_P + s * 32) * 512 + h * 64 + lane), 32, Sv, Si, YH, QH, L, lane);
.Lscan_s:
	v_lshrrev_b32_e32 v78, 5, v139
	v_and_b32_e32 v79, 31, v139
	s_mov_b32 s26, -1
	s_mov_b32 s27, 0
	v_mov_b64_e32 v[0:1], s[92:93]
	flat_load_dwordx2 v[0:1], v[0:1] offset:24 sc0 sc1
	s_waitcnt vmcnt(0) lgkmcnt(0)
	v_readfirstlane_b32 s14, v0
	v_readfirstlane_b32 s15, v1
	s_and_b64 s[36:37], s[34:35], exec
	s_cselect_b32 s36, 32, 0
	s_lshr_b32 s37, s90, 3
	s_add_i32 s36, s36, s37
	s_lshl_b32 s36, s36, 17
	s_and_b32 s37, s90, 7
	s_lshl_b32 s37, s37, 14
	s_or_b32 s36, s36, s37
	s_add_u32 s16, s14, s36
	s_addc_u32 s17, s15, 0
	v_readlane_b32 s14, v242, 1
	v_readlane_b32 s15, v242, 2
	s_add_u32 s36, s14, s36
	s_addc_u32 s37, s15, 0
	s_lshr_b32 s14, s90, 3
	s_lshl_b32 s14, s14, 14
	s_and_b32 s15, s90, 7
	s_lshl_b32 s15, s15, 6
	s_or_b32 s14, s14, s15
	s_add_i32 s14, s14, 0x800000
	v_add_lshl_u32 v72, s14, v139, 1
	v_add_lshl_u32 v81, s14, v79, 1
	v_mov_b32_e32 v74, s20
	v_mov_b32_e32 v75, s21
	v_mov_b32_e32 v80, s6
	v_cndmask_b32_e64 v74, v80, v74, s[26:27]
	v_mov_b32_e32 v80, s7
	v_cndmask_b32_e64 v75, v80, v75, s[26:27]
	v_add_co_u32_e32 v74, vcc, v74, v81
	s_nop 1
	v_addc_co_u32_e32 v75, vcc, 0, v75, vcc
	v_lshl_add_u32 v76, v78, 4, s10
	v_lshl_add_u32 v77, v139, 2, s10
	v_lshl_add_u32 v251, v79, 2, s10
	v_mov_b32_e32 v246, 1.0
	v_lshlrev_b32_e32 v81, 2, v78
	v_sub_u32_e32 v81, v79, v81
	global_load_short_d16_hi v254, v72, s[12:13]
	global_load_short_d16_hi v224, v72, s[4:5] offset:0
	global_load_short_d16_hi v225, v72, s[0:1] offset:0
	global_load_short_d16_hi v226, v72, s[12:13] offset:1024
	global_load_short_d16_hi v227, v[74:75], off offset:0
	global_load_short_d16_hi v228, v[74:75], off offset:64
	global_load_short_d16_hi v229, v72, s[2:3] offset:0
	global_load_short_d16_hi v230, v72, s[4:5] offset:1024
	global_load_short_d16_hi v231, v72, s[0:1] offset:1024
	global_load_short_d16_hi v232, v72, s[12:13] offset:2048
	global_load_short_d16_hi v233, v[74:75], off offset:1024
	global_load_short_d16_hi v234, v[74:75], off offset:1088
	global_load_short_d16_hi v235, v72, s[2:3] offset:1024
	global_load_short_d16_hi v82, v72, s[4:5] offset:2048
	global_load_short_d16_hi v83, v72, s[0:1] offset:2048
	global_load_short_d16_hi v84, v72, s[12:13] offset:3072
	global_load_short_d16_hi v85, v[74:75], off offset:2048
	global_load_short_d16_hi v86, v[74:75], off offset:2112
	global_load_short_d16_hi v87, v72, s[2:3] offset:2048
	v_add_u32_e32 v72, 0xc00, v72
	v_lshl_add_u64 v[74:75], v[74:75], 0, s[54:55]
	v_lshl_add_u64 v[74:75], v[74:75], 0, s[54:55]
	v_lshl_add_u64 v[74:75], v[74:75], 0, s[54:55]
	global_load_short_d16_hi v88, v72, s[4:5] offset:0
	global_load_short_d16_hi v89, v72, s[0:1] offset:0
	global_load_short_d16_hi v90, v72, s[12:13] offset:1024
	global_load_short_d16_hi v91, v[74:75], off offset:0
	global_load_short_d16_hi v92, v[74:75], off offset:64
	global_load_short_d16_hi v93, v72, s[2:3] offset:0
	v_add_u32_e32 v72, 0x400, v72
	v_lshl_add_u64 v[74:75], v[74:75], 0, s[54:55]
	v_lshlrev_b32_e32 v252, 8, v79
	v_lshl_add_u32 v252, v78, 4, v252
	v_add_u32_e32 v253, 0x2000, v252
	global_load_dwordx4 v[0:3], v252, s[16:17] offset:0
	global_load_dwordx4 v[4:7], v252, s[16:17] offset:32
	global_load_dwordx4 v[8:11], v252, s[16:17] offset:64
	global_load_dwordx4 v[12:15], v252, s[16:17] offset:96
	global_load_dwordx4 v[16:19], v252, s[16:17] offset:128
	global_load_dwordx4 v[20:23], v252, s[16:17] offset:160
	global_load_dwordx4 v[24:27], v252, s[16:17] offset:192
	global_load_dwordx4 v[28:31], v252, s[16:17] offset:224
	global_load_dwordx4 v[32:35], v253, s[16:17] offset:0
	global_load_dwordx4 v[36:39], v253, s[16:17] offset:32
	global_load_dwordx4 v[40:43], v253, s[16:17] offset:64
	global_load_dwordx4 v[44:47], v253, s[16:17] offset:96
	global_load_dwordx4 v[48:51], v253, s[16:17] offset:128
	global_load_dwordx4 v[52:55], v253, s[16:17] offset:160
	global_load_dwordx4 v[56:59], v253, s[16:17] offset:192
	global_load_dwordx4 v[60:63], v253, s[16:17] offset:224
	s_waitcnt vmcnt(0)
	ds_write_b32 v77, v254 offset:1280
	ds_write_b32 v77, v254 offset:1024
	ds_read_b128 v[148:151], v76 offset:1024
	ds_read_b128 v[152:155], v76 offset:1056
	ds_read_b128 v[156:159], v76 offset:1088
	ds_read_b128 v[160:163], v76 offset:1120
	ds_read_b128 v[164:167], v76 offset:1280
	ds_read_b128 v[168:171], v76 offset:1312
	ds_read_b128 v[172:175], v76 offset:1344
	ds_read_b128 v[176:179], v76 offset:1376
	ds_read_b128 v[192:195], v76 offset:1152
	ds_read_b128 v[196:199], v76 offset:1184
	ds_read_b128 v[200:203], v76 offset:1216
	ds_read_b128 v[204:207], v76 offset:1248
	ds_read_b128 v[208:211], v76 offset:1408
	ds_read_b128 v[212:215], v76 offset:1440
	ds_read_b128 v[216:219], v76 offset:1472
	ds_read_b128 v[220:223], v76 offset:1504
	s_waitcnt lgkmcnt(8)
	v_pk_mul_f32 v[64:65], v[0:1], v[148:149]
	v_pk_mul_f32 v[68:69], v[0:1], v[164:165]
	v_pk_fma_f32 v[64:65], v[2:3], v[150:151], v[64:65]
	v_pk_fma_f32 v[68:69], v[2:3], v[166:167], v[68:69]
	v_pk_fma_f32 v[64:65], v[4:5], v[152:153], v[64:65]
	v_pk_fma_f32 v[68:69], v[4:5], v[168:169], v[68:69]
	v_pk_fma_f32 v[64:65], v[6:7], v[154:155], v[64:65]
	v_pk_fma_f32 v[68:69], v[6:7], v[170:171], v[68:69]
	v_pk_fma_f32 v[64:65], v[8:9], v[156:157], v[64:65]
	v_pk_fma_f32 v[68:69], v[8:9], v[172:173], v[68:69]
	v_pk_fma_f32 v[64:65], v[10:11], v[158:159], v[64:65]
	v_pk_fma_f32 v[68:69], v[10:11], v[174:175], v[68:69]
	v_pk_fma_f32 v[64:65], v[12:13], v[160:161], v[64:65]
	v_pk_fma_f32 v[68:69], v[12:13], v[176:177], v[68:69]
	v_pk_fma_f32 v[64:65], v[14:15], v[162:163], v[64:65]
	v_pk_fma_f32 v[68:69], v[14:15], v[178:179], v[68:69]
	v_pk_mul_f32 v[66:67], v[32:33], v[148:149]
	v_pk_mul_f32 v[70:71], v[32:33], v[164:165]
	v_pk_fma_f32 v[66:67], v[34:35], v[150:151], v[66:67]
	v_pk_fma_f32 v[70:71], v[34:35], v[166:167], v[70:71]
	v_pk_fma_f32 v[66:67], v[36:37], v[152:153], v[66:67]
	v_pk_fma_f32 v[70:71], v[36:37], v[168:169], v[70:71]
	v_pk_fma_f32 v[66:67], v[38:39], v[154:155], v[66:67]
	v_pk_fma_f32 v[70:71], v[38:39], v[170:171], v[70:71]
	v_pk_fma_f32 v[66:67], v[40:41], v[156:157], v[66:67]
	v_pk_fma_f32 v[70:71], v[40:41], v[172:173], v[70:71]
	v_pk_fma_f32 v[66:67], v[42:43], v[158:159], v[66:67]
	v_pk_fma_f32 v[70:71], v[42:43], v[174:175], v[70:71]
	v_pk_fma_f32 v[66:67], v[44:45], v[160:161], v[66:67]
	v_pk_fma_f32 v[70:71], v[44:45], v[176:177], v[70:71]
	v_pk_fma_f32 v[66:67], v[46:47], v[162:163], v[66:67]
	v_pk_fma_f32 v[70:71], v[46:47], v[178:179], v[70:71]
	s_waitcnt lgkmcnt(0)
; template <bool ID> __device__ __forceinline__ void rwkv_scan(const bf16_t* __restrict__ R, const bf16_t* __restrict__ EW, const bf16_t* __restrict__ K, const bf16_t* __restrict__ V, ...
;     ...
; #pragma unroll 1
;     for (int s = 0; s < nsteps; ++s) {
;         L[lane] = bf2f(q2[4]); L[64 + lane] = __expf(-bf2f(q1[1])); L[128 + lane] = bf2f(q1[5]); L[192 + lane] = bf2f(q1[2]); L[256 + lane] = bf2f(q1[0]);
;         const float v = bf2f(q1[3]);
; #pragma unroll
;         for (int j = 0; j < 6; ++j) q1[j] = q2[j];
;         { const unsigned o = base + (unsigned)(s + 2 < nsteps ? s + 2 : nsteps - 1) * 512u; q2[0] = R[o]; q2[1] = EW[o]; q2[2] = K[o]; q2[3] = V[o]; q2[4] = A[o]; q2[5] = B[o]; }
;         const f2 sav2 = {sav, sav}, sai2 = {sai, sai}, v2 = {v, v};
;         f2 yv = {0.f, 0.f}, yi = {0.f, 0.f}, yv1 = {0.f, 0.f}, yi1 = {0.f, 0.f}, nv = {0.f, 0.f}, ni = {0.f, 0.f}, nv1 = {0.f, 0.f}, ni1 = {0.f, 0.f};
;         f32x4 ca = pa[0], cw = pa[16], cb = pa[32], ck = pa[48], cr = pa[64];
; #pragma unroll
;         for (int q = 0; q < 16; ++q) {
;             const f32x4 a4 = ca, w4 = cw, b4 = cb, k4 = ck, r4 = cr;
;             if (q < 15) { ca = pa[1 + q]; cw = pa[17 + q]; cb = pa[33 + q]; ck = pa[49 + q]; cr = pa[65 + q]; }
;             __builtin_amdgcn_sched_barrier(0);
;             { const f2 a2 = {a4[0], a4[1]}, w2 = {w4[0], w4[1]}, b2 = {b4[0], b4[1]}, k2 = {k4[0], k4[1]}, r2 = {r4[0], r4[1]};
;               f2 tv = sav2 * b2; tv = pfma(v2, k2, tv); Sv[2 * q] = pfma(Sv[2 * q], w2, tv); yv = pfma(Sv[2 * q], r2, yv); nv = pfma(Sv[2 * q], a2, nv);
;               if (ID) { const f2 ti = sai2 * b2; Si[2 * q] = pfma(Si[2 * q], w2, ti); yi = pfma(Si[2 * q], r2, yi); ni = pfma(Si[2 * q], a2, ni); } }
;             { const f2 a2 = {a4[2], a4[3]}, w2 = {w4[2], w4[3]}, b2 = {b4[2], b4[3]}, k2 = {k4[2], k4[3]}, r2 = {r4[2], r4[3]};
;               f2 tv = sav2 * b2; tv = pfma(v2, k2, tv); Sv[2 * q + 1] = pfma(Sv[2 * q + 1], w2, tv); yv1 = pfma(Sv[2 * q + 1], r2, yv1); nv1 = pfma(Sv[2 * q + 1], a2, nv1);
;               if (ID) { const f2 ti = sai2 * b2; Si[2 * q + 1] = pfma(Si[2 * q + 1], w2, ti); yi1 = pfma(Si[2 * q + 1], r2, yi1); ni1 = pfma(Si[2 * q + 1], a2, ni1); } }
;         }
;         sav = (nv[0] + nv[1]) + (nv1[0] + nv1[1]); sai = (ni[0] + ni[1]) + (ni1[0] + ni1[1]);
;         const unsigned cbo = base + (unsigned)s * 512u;
	v_pk_fma_f32 v[64:65], v[16:17], v[192:193], v[64:65]
	v_pk_fma_f32 v[68:69], v[16:17], v[208:209], v[68:69]
	v_pk_fma_f32 v[64:65], v[18:19], v[194:195], v[64:65]
	v_pk_fma_f32 v[68:69], v[18:19], v[210:211], v[68:69]
	v_pk_fma_f32 v[64:65], v[20:21], v[196:197], v[64:65]
	v_pk_fma_f32 v[68:69], v[20:21], v[212:213], v[68:69]
	v_pk_fma_f32 v[64:65], v[22:23], v[198:199], v[64:65]
	v_pk_fma_f32 v[68:69], v[22:23], v[214:215], v[68:69]
	v_pk_fma_f32 v[64:65], v[24:25], v[200:201], v[64:65]
	v_pk_fma_f32 v[68:69], v[24:25], v[216:217], v[68:69]
	v_pk_fma_f32 v[64:65], v[26:27], v[202:203], v[64:65]
	v_pk_fma_f32 v[68:69], v[26:27], v[218:219], v[68:69]
	v_pk_fma_f32 v[64:65], v[28:29], v[204:205], v[64:65]
	v_pk_fma_f32 v[68:69], v[28:29], v[220:221], v[68:69]
	v_pk_fma_f32 v[64:65], v[30:31], v[206:207], v[64:65]
	v_pk_fma_f32 v[68:69], v[30:31], v[222:223], v[68:69]
	v_pk_fma_f32 v[66:67], v[48:49], v[192:193], v[66:67]
	v_pk_fma_f32 v[70:71], v[48:49], v[208:209], v[70:71]
	v_pk_fma_f32 v[66:67], v[50:51], v[194:195], v[66:67]
	v_pk_fma_f32 v[70:71], v[50:51], v[210:211], v[70:71]
	v_pk_fma_f32 v[66:67], v[52:53], v[196:197], v[66:67]
	v_pk_fma_f32 v[70:71], v[52:53], v[212:213], v[70:71]
	v_pk_fma_f32 v[66:67], v[54:55], v[198:199], v[66:67]
	v_pk_fma_f32 v[70:71], v[54:55], v[214:215], v[70:71]
	v_pk_fma_f32 v[66:67], v[56:57], v[200:201], v[66:67]
	v_pk_fma_f32 v[70:71], v[56:57], v[216:217], v[70:71]
	v_pk_fma_f32 v[66:67], v[58:59], v[202:203], v[66:67]
	v_pk_fma_f32 v[70:71], v[58:59], v[218:219], v[70:71]
	v_pk_fma_f32 v[66:67], v[60:61], v[204:205], v[66:67]
	v_pk_fma_f32 v[70:71], v[60:61], v[220:221], v[70:71]
	v_pk_fma_f32 v[66:67], v[62:63], v[206:207], v[66:67]
	v_pk_fma_f32 v[70:71], v[62:63], v[222:223], v[70:71]
	v_add_f32_e32 v68, v68, v69
	v_add_f32_e32 v70, v70, v71
	s_nop 0
	s_nop 0
	v_permlane32_swap_b32_e32 v68, v70
	v_add_f32_e32 v255, v68, v70
	v_mul_f32_e32 v78, 0xbfb8aa3b, v224
	v_exp_f32_e32 v78, v78
	s_nop 0
	v_mul_f32_e32 v246, v246, v78
	v_mul_f32_e32 v79, v225, v246
	v_mul_f32_e32 v80, v226, v246
	v_rcp_f32_e32 v248, v246
	s_nop 0
	ds_write2st64_b32 v77, v248, v79 offset0:0 offset1:1
	ds_write_b32 v77, v80 offset:512
	ds_read_b32 v249, v251 offset:0
	ds_read_b32 v250, v251 offset:128
	s_waitcnt lgkmcnt(0)
	v_mul_f32_e32 v240, v227, v249
	v_mul_f32_e32 v241, v228, v250
	v_mov_b32_e32 v244, v255
	v_mov_b32_e32 v245, v229
	s_nop 0
	s_nop 0
	v_permlane32_swap_b32_e32 v244, v245
	s_movk_i32 s41, 0
.Lscan_s_loop:
	ds_read_b128 v[192:195], v76 offset:256
	ds_read_b128 v[196:199], v76 offset:288
	ds_read_b128 v[200:203], v76 offset:320
	ds_read_b128 v[204:207], v76 offset:352
	ds_read_b128 v[208:211], v76 offset:512
	ds_read_b128 v[212:215], v76 offset:544
	ds_read_b128 v[216:219], v76 offset:576
	ds_read_b128 v[220:223], v76 offset:608
	global_load_short_d16_hi v224, v72, s[4:5] offset:0
	global_load_short_d16_hi v225, v72, s[0:1] offset:0
	global_load_short_d16_hi v226, v72, s[12:13] offset:1024
	global_load_short_d16_hi v227, v[74:75], off offset:0
	global_load_short_d16_hi v228, v[74:75], off offset:64
	global_load_short_d16_hi v229, v72, s[2:3] offset:0
	v_mfma_f32_32x32x2_f32 v[0:15], v240, v244, v[0:15]
	v_mfma_f32_32x32x2_f32 v[32:47], v240, v245, v[32:47]
	ds_read_b128 v[148:151], v76 offset:384
	ds_read_b128 v[152:155], v76 offset:416
	ds_read_b128 v[156:159], v76 offset:448
	ds_read_b128 v[160:163], v76 offset:480
	ds_read_b128 v[164:167], v76 offset:640
	ds_read_b128 v[168:171], v76 offset:672
	ds_read_b128 v[172:175], v76 offset:704
	ds_read_b128 v[176:179], v76 offset:736
	v_mfma_f32_32x32x2_f32 v[16:31], v241, v244, v[16:31]
	v_mfma_f32_32x32x2_f32 v[48:63], v241, v245, v[48:63]
	v_mul_f32_e32 v78, 0xbfb8aa3b, v230
	v_exp_f32_e32 v78, v78
	s_nop 0
	v_mul_f32_e32 v246, v246, v78
	v_mul_f32_e32 v79, v231, v246
	v_mul_f32_e32 v80, v232, v246
	v_rcp_f32_e32 v248, v246
	s_nop 0
	ds_write2st64_b32 v77, v248, v79 offset0:3 offset1:4
	ds_write_b32 v77, v80 offset:1280
	s_waitcnt lgkmcnt(10)
	v_pk_mul_f32 v[64:65], v[0:1], v[192:193]
	v_pk_mul_f32 v[68:69], v[0:1], v[208:209]
	v_pk_fma_f32 v[64:65], v[2:3], v[194:195], v[64:65]
	v_pk_fma_f32 v[68:69], v[2:3], v[210:211], v[68:69]
	v_pk_fma_f32 v[64:65], v[4:5], v[196:197], v[64:65]
	v_pk_fma_f32 v[68:69], v[4:5], v[212:213], v[68:69]
	v_pk_fma_f32 v[64:65], v[6:7], v[198:199], v[64:65]
	v_pk_fma_f32 v[68:69], v[6:7], v[214:215], v[68:69]
	v_pk_fma_f32 v[64:65], v[8:9], v[200:201], v[64:65]
	v_pk_fma_f32 v[68:69], v[8:9], v[216:217], v[68:69]
	v_pk_fma_f32 v[64:65], v[10:11], v[202:203], v[64:65]
	v_pk_fma_f32 v[68:69], v[10:11], v[218:219], v[68:69]
	v_pk_fma_f32 v[64:65], v[12:13], v[204:205], v[64:65]
	v_pk_fma_f32 v[68:69], v[12:13], v[220:221], v[68:69]
	v_pk_fma_f32 v[64:65], v[14:15], v[206:207], v[64:65]
	v_pk_fma_f32 v[68:69], v[14:15], v[222:223], v[68:69]
	v_pk_mul_f32 v[66:67], v[32:33], v[192:193]
	v_pk_mul_f32 v[70:71], v[32:33], v[208:209]
	v_pk_fma_f32 v[66:67], v[34:35], v[194:195], v[66:67]
	v_pk_fma_f32 v[70:71], v[34:35], v[210:211], v[70:71]
	v_pk_fma_f32 v[66:67], v[36:37], v[196:197], v[66:67]
	v_pk_fma_f32 v[70:71], v[36:37], v[212:213], v[70:71]
	v_pk_fma_f32 v[66:67], v[38:39], v[198:199], v[66:67]
	v_pk_fma_f32 v[70:71], v[38:39], v[214:215], v[70:71]
	v_pk_fma_f32 v[66:67], v[40:41], v[200:201], v[66:67]
	v_pk_fma_f32 v[70:71], v[40:41], v[216:217], v[70:71]
	v_pk_fma_f32 v[66:67], v[42:43], v[202:203], v[66:67]
	v_pk_fma_f32 v[70:71], v[42:43], v[218:219], v[70:71]
	v_pk_fma_f32 v[66:67], v[44:45], v[204:205], v[66:67]
	v_pk_fma_f32 v[70:71], v[44:45], v[220:221], v[70:71]
	v_pk_fma_f32 v[66:67], v[46:47], v[206:207], v[66:67]
	v_pk_fma_f32 v[70:71], v[46:47], v[222:223], v[70:71]
	s_waitcnt lgkmcnt(2)
; template <bool ID> __device__ __forceinline__ void rwkv_scan(const bf16_t* __restrict__ R, const bf16_t* __restrict__ EW, const bf16_t* __restrict__ K, const bf16_t* __restrict__ V, ...
;     ...
; #pragma unroll 1
;     for (int s = 0; s < nsteps; ++s) {
;         L[lane] = bf2f(q2[4]); L[64 + lane] = __expf(-bf2f(q1[1])); L[128 + lane] = bf2f(q1[5]); L[192 + lane] = bf2f(q1[2]); L[256 + lane] = bf2f(q1[0]);
;         const float v = bf2f(q1[3]);
; #pragma unroll
;         for (int j = 0; j < 6; ++j) q1[j] = q2[j];
;         { const unsigned o = base + (unsigned)(s + 2 < nsteps ? s + 2 : nsteps - 1) * 512u; q2[0] = R[o]; q2[1] = EW[o]; q2[2] = K[o]; q2[3] = V[o]; q2[4] = A[o]; q2[5] = B[o]; }
;         const f2 sav2 = {sav, sav}, sai2 = {sai, sai}, v2 = {v, v};
;         f2 yv = {0.f, 0.f}, yi = {0.f, 0.f}, yv1 = {0.f, 0.f}, yi1 = {0.f, 0.f}, nv = {0.f, 0.f}, ni = {0.f, 0.f}, nv1 = {0.f, 0.f}, ni1 = {0.f, 0.f};
;         f32x4 ca = pa[0], cw = pa[16], cb = pa[32], ck = pa[48], cr = pa[64];
; #pragma unroll
;         for (int q = 0; q < 16; ++q) {
;             const f32x4 a4 = ca, w4 = cw, b4 = cb, k4 = ck, r4 = cr;
;             if (q < 15) { ca = pa[1 + q]; cw = pa[17 + q]; cb = pa[33 + q]; ck = pa[49 + q]; cr = pa[65 + q]; }
;             __builtin_amdgcn_sched_barrier(0);
;             { const f2 a2 = {a4[0], a4[1]}, w2 = {w4[0], w4[1]}, b2 = {b4[0], b4[1]}, k2 = {k4[0], k4[1]}, r2 = {r4[0], r4[1]};
;               f2 tv = sav2 * b2; tv = pfma(v2, k2, tv); Sv[2 * q] = pfma(Sv[2 * q], w2, tv); yv = pfma(Sv[2 * q], r2, yv); nv = pfma(Sv[2 * q], a2, nv);
;               if (ID) { const f2 ti = sai2 * b2; Si[2 * q] = pfma(Si[2 * q], w2, ti); yi = pfma(Si[2 * q], r2, yi); ni = pfma(Si[2 * q], a2, ni); } }
;             { const f2 a2 = {a4[2], a4[3]}, w2 = {w4[2], w4[3]}, b2 = {b4[2], b4[3]}, k2 = {k4[2], k4[3]}, r2 = {r4[2], r4[3]};
;               f2 tv = sav2 * b2; tv = pfma(v2, k2, tv); Sv[2 * q + 1] = pfma(Sv[2 * q + 1], w2, tv); yv1 = pfma(Sv[2 * q + 1], r2, yv1); nv1 = pfma(Sv[2 * q + 1], a2, nv1);
;               if (ID) { const f2 ti = sai2 * b2; Si[2 * q + 1] = pfma(Si[2 * q + 1], w2, ti); yi1 = pfma(Si[2 * q + 1], r2, yi1); ni1 = pfma(Si[2 * q + 1], a2, ni1); } }
;         }
;         sav = (nv[0] + nv[1]) + (nv1[0] + nv1[1]); sai = (ni[0] + ni[1]) + (ni1[0] + ni1[1]);
;         const unsigned cbo = base + (unsigned)s * 512u;
	v_pk_fma_f32 v[64:65], v[16:17], v[148:149], v[64:65]
	v_pk_fma_f32 v[68:69], v[16:17], v[164:165], v[68:69]
	v_pk_fma_f32 v[64:65], v[18:19], v[150:151], v[64:65]
	v_pk_fma_f32 v[68:69], v[18:19], v[166:167], v[68:69]
	v_pk_fma_f32 v[64:65], v[20:21], v[152:153], v[64:65]
	v_pk_fma_f32 v[68:69], v[20:21], v[168:169], v[68:69]
	v_pk_fma_f32 v[64:65], v[22:23], v[154:155], v[64:65]
	v_pk_fma_f32 v[68:69], v[22:23], v[170:171], v[68:69]
	v_pk_fma_f32 v[64:65], v[24:25], v[156:157], v[64:65]
	v_pk_fma_f32 v[68:69], v[24:25], v[172:173], v[68:69]
	v_pk_fma_f32 v[64:65], v[26:27], v[158:159], v[64:65]
	v_pk_fma_f32 v[68:69], v[26:27], v[174:175], v[68:69]
	v_pk_fma_f32 v[64:65], v[28:29], v[160:161], v[64:65]
	v_pk_fma_f32 v[68:69], v[28:29], v[176:177], v[68:69]
	v_pk_fma_f32 v[64:65], v[30:31], v[162:163], v[64:65]
	v_pk_fma_f32 v[68:69], v[30:31], v[178:179], v[68:69]
	v_pk_fma_f32 v[66:67], v[48:49], v[148:149], v[66:67]
	v_pk_fma_f32 v[70:71], v[48:49], v[164:165], v[70:71]
	v_pk_fma_f32 v[66:67], v[50:51], v[150:151], v[66:67]
	v_pk_fma_f32 v[70:71], v[50:51], v[166:167], v[70:71]
	v_pk_fma_f32 v[66:67], v[52:53], v[152:153], v[66:67]
	v_pk_fma_f32 v[70:71], v[52:53], v[168:169], v[70:71]
	v_pk_fma_f32 v[66:67], v[54:55], v[154:155], v[66:67]
	v_pk_fma_f32 v[70:71], v[54:55], v[170:171], v[70:71]
	v_pk_fma_f32 v[66:67], v[56:57], v[156:157], v[66:67]
	v_pk_fma_f32 v[70:71], v[56:57], v[172:173], v[70:71]
	v_pk_fma_f32 v[66:67], v[58:59], v[158:159], v[66:67]
	v_pk_fma_f32 v[70:71], v[58:59], v[174:175], v[70:71]
	v_pk_fma_f32 v[66:67], v[60:61], v[160:161], v[66:67]
	v_pk_fma_f32 v[70:71], v[60:61], v[176:177], v[70:71]
	v_pk_fma_f32 v[66:67], v[62:63], v[162:163], v[66:67]
	v_pk_fma_f32 v[70:71], v[62:63], v[178:179], v[70:71]
	ds_read_b32 v249, v251 offset:768
	ds_read_b32 v250, v251 offset:896
	s_waitcnt lgkmcnt(0)
	v_mul_f32_e32 v240, v233, v249
	v_mul_f32_e32 v241, v234, v250
	v_add_f32_e32 v68, v68, v69
	v_add_f32_e32 v70, v70, v71
	v_add_f32_e32 v64, v64, v65
	v_add_f32_e32 v66, v66, v67
	v_mov_b32_e32 v245, v235
	v_permlane32_swap_b32_e32 v68, v70
	v_permlane32_swap_b32_e32 v64, v66
	v_add_f32_e32 v244, v68, v70
	v_add_f32_e32 v64, v64, v66
	v_bfe_u32 v66, v64, 16, 1
	v_add3_u32 v66, v64, v66, s69
	v_permlane32_swap_b32_e32 v244, v245
	global_store_short_d16_hi v72, v66, s[22:23] offset:-4096
	v_add_u32_e32 v72, 0x400, v72
	v_lshl_add_u64 v[74:75], v[74:75], 0, s[54:55]
	ds_read_b128 v[148:151], v76 offset:1024
	ds_read_b128 v[152:155], v76 offset:1056
	ds_read_b128 v[156:159], v76 offset:1088
	ds_read_b128 v[160:163], v76 offset:1120
	ds_read_b128 v[164:167], v76 offset:1280
	ds_read_b128 v[168:171], v76 offset:1312
	ds_read_b128 v[172:175], v76 offset:1344
	ds_read_b128 v[176:179], v76 offset:1376
	global_load_short_d16_hi v230, v72, s[4:5] offset:0
	global_load_short_d16_hi v231, v72, s[0:1] offset:0
	global_load_short_d16_hi v232, v72, s[12:13] offset:1024
	global_load_short_d16_hi v233, v[74:75], off offset:0
	global_load_short_d16_hi v234, v[74:75], off offset:64
	global_load_short_d16_hi v235, v72, s[2:3] offset:0
	v_mfma_f32_32x32x2_f32 v[0:15], v240, v244, v[0:15]
	v_mfma_f32_32x32x2_f32 v[32:47], v240, v245, v[32:47]
	ds_read_b128 v[192:195], v76 offset:1152
	ds_read_b128 v[196:199], v76 offset:1184
	ds_read_b128 v[200:203], v76 offset:1216
	ds_read_b128 v[204:207], v76 offset:1248
	ds_read_b128 v[208:211], v76 offset:1408
	ds_read_b128 v[212:215], v76 offset:1440
	ds_read_b128 v[216:219], v76 offset:1472
	ds_read_b128 v[220:223], v76 offset:1504
	v_mfma_f32_32x32x2_f32 v[16:31], v241, v244, v[16:31]
	v_mfma_f32_32x32x2_f32 v[48:63], v241, v245, v[48:63]
	v_mul_f32_e32 v78, 0xbfb8aa3b, v82
	v_exp_f32_e32 v78, v78
	s_nop 0
	v_mul_f32_e32 v246, v246, v78
	v_mul_f32_e32 v79, v83, v246
	v_mul_f32_e32 v80, v84, v246
	v_rcp_f32_e32 v248, v246
	s_nop 0
	ds_write2st64_b32 v77, v248, v79 offset0:0 offset1:1
	ds_write_b32 v77, v80 offset:512
	s_waitcnt lgkmcnt(10)
	v_pk_mul_f32 v[64:65], v[0:1], v[148:149]
	v_pk_mul_f32 v[68:69], v[0:1], v[164:165]
	v_pk_fma_f32 v[64:65], v[2:3], v[150:151], v[64:65]
	v_pk_fma_f32 v[68:69], v[2:3], v[166:167], v[68:69]
	v_pk_fma_f32 v[64:65], v[4:5], v[152:153], v[64:65]
	v_pk_fma_f32 v[68:69], v[4:5], v[168:169], v[68:69]
	v_pk_fma_f32 v[64:65], v[6:7], v[154:155], v[64:65]
	v_pk_fma_f32 v[68:69], v[6:7], v[170:171], v[68:69]
	v_pk_fma_f32 v[64:65], v[8:9], v[156:157], v[64:65]
	v_pk_fma_f32 v[68:69], v[8:9], v[172:173], v[68:69]
	v_pk_fma_f32 v[64:65], v[10:11], v[158:159], v[64:65]
	v_pk_fma_f32 v[68:69], v[10:11], v[174:175], v[68:69]
	v_pk_fma_f32 v[64:65], v[12:13], v[160:161], v[64:65]
	v_pk_fma_f32 v[68:69], v[12:13], v[176:177], v[68:69]
	v_pk_fma_f32 v[64:65], v[14:15], v[162:163], v[64:65]
	v_pk_fma_f32 v[68:69], v[14:15], v[178:179], v[68:69]
	v_pk_mul_f32 v[66:67], v[32:33], v[148:149]
	v_pk_mul_f32 v[70:71], v[32:33], v[164:165]
	v_pk_fma_f32 v[66:67], v[34:35], v[150:151], v[66:67]
	v_pk_fma_f32 v[70:71], v[34:35], v[166:167], v[70:71]
	v_pk_fma_f32 v[66:67], v[36:37], v[152:153], v[66:67]
	v_pk_fma_f32 v[70:71], v[36:37], v[168:169], v[70:71]
	v_pk_fma_f32 v[66:67], v[38:39], v[154:155], v[66:67]
	v_pk_fma_f32 v[70:71], v[38:39], v[170:171], v[70:71]
	v_pk_fma_f32 v[66:67], v[40:41], v[156:157], v[66:67]
	v_pk_fma_f32 v[70:71], v[40:41], v[172:173], v[70:71]
	v_pk_fma_f32 v[66:67], v[42:43], v[158:159], v[66:67]
	v_pk_fma_f32 v[70:71], v[42:43], v[174:175], v[70:71]
	v_pk_fma_f32 v[66:67], v[44:45], v[160:161], v[66:67]
	v_pk_fma_f32 v[70:71], v[44:45], v[176:177], v[70:71]
	v_pk_fma_f32 v[66:67], v[46:47], v[162:163], v[66:67]
	v_pk_fma_f32 v[70:71], v[46:47], v[178:179], v[70:71]
	s_waitcnt lgkmcnt(2)
; template <bool ID> __device__ __forceinline__ void rwkv_scan(const bf16_t* __restrict__ R, const bf16_t* __restrict__ EW, const bf16_t* __restrict__ K, const bf16_t* __restrict__ V, ...
;     ...
;     for (int s = 0; s < nsteps; ++s) {
;         L[lane] = bf2f(q2[4]); L[64 + lane] = __expf(-bf2f(q1[1])); L[128 + lane] = bf2f(q1[5]); L[192 + lane] = bf2f(q1[2]); L[256 + lane] = bf2f(q1[0]);
;         const float v = bf2f(q1[3]);
; #pragma unroll
;         for (int j = 0; j < 6; ++j) q1[j] = q2[j];
;         { const unsigned o = base + (unsigned)(s + 2 < nsteps ? s + 2 : nsteps - 1) * 512u; q2[0] = R[o]; q2[1] = EW[o]; q2[2] = K[o]; q2[3] = V[o]; q2[4] = A[o]; q2[5] = B[o]; }
;         const f2 sav2 = {sav, sav}, sai2 = {sai, sai}, v2 = {v, v};
;         f2 yv = {0.f, 0.f}, yi = {0.f, 0.f}, yv1 = {0.f, 0.f}, yi1 = {0.f, 0.f}, nv = {0.f, 0.f}, ni = {0.f, 0.f}, nv1 = {0.f, 0.f}, ni1 = {0.f, 0.f};
;         f32x4 ca = pa[0], cw = pa[16], cb = pa[32], ck = pa[48], cr = pa[64];
; #pragma unroll
;         for (int q = 0; q < 16; ++q) {
;             const f32x4 a4 = ca, w4 = cw, b4 = cb, k4 = ck, r4 = cr;
;             if (q < 15) { ca = pa[1 + q]; cw = pa[17 + q]; cb = pa[33 + q]; ck = pa[49 + q]; cr = pa[65 + q]; }
;             __builtin_amdgcn_sched_barrier(0);
;             { const f2 a2 = {a4[0], a4[1]}, w2 = {w4[0], w4[1]}, b2 = {b4[0], b4[1]}, k2 = {k4[0], k4[1]}, r2 = {r4[0], r4[1]};
;               f2 tv = sav2 * b2; tv = pfma(v2, k2, tv); Sv[2 * q] = pfma(Sv[2 * q], w2, tv); yv = pfma(Sv[2 * q], r2, yv); nv = pfma(Sv[2 * q], a2, nv);
;               if (ID) { const f2 ti = sai2 * b2; Si[2 * q] = pfma(Si[2 * q], w2, ti); yi = pfma(Si[2 * q], r2, yi); ni = pfma(Si[2 * q], a2, ni); } }
;             { const f2 a2 = {a4[2], a4[3]}, w2 = {w4[2], w4[3]}, b2 = {b4[2], b4[3]}, k2 = {k4[2], k4[3]}, r2 = {r4[2], r4[3]};
;               f2 tv = sav2 * b2; tv = pfma(v2, k2, tv); Sv[2 * q + 1] = pfma(Sv[2 * q + 1], w2, tv); yv1 = pfma(Sv[2 * q + 1], r2, yv1); nv1 = pfma(Sv[2 * q + 1], a2, nv1);
;               if (ID) { const f2 ti = sai2 * b2; Si[2 * q + 1] = pfma(Si[2 * q + 1], w2, ti); yi1 = pfma(Si[2 * q + 1], r2, yi1); ni1 = pfma(Si[2 * q + 1], a2, ni1); } }
;         }
;         sav = (nv[0] + nv[1]) + (nv1[0] + nv1[1]); sai = (ni[0] + ni[1]) + (ni1[0] + ni1[1]);
;         const unsigned cbo = base + (unsigned)s * 512u;
	v_pk_fma_f32 v[64:65], v[16:17], v[192:193], v[64:65]
	v_pk_fma_f32 v[68:69], v[16:17], v[208:209], v[68:69]
	v_pk_fma_f32 v[64:65], v[18:19], v[194:195], v[64:65]
	v_pk_fma_f32 v[68:69], v[18:19], v[210:211], v[68:69]
	v_pk_fma_f32 v[64:65], v[20:21], v[196:197], v[64:65]
	v_pk_fma_f32 v[68:69], v[20:21], v[212:213], v[68:69]
	v_pk_fma_f32 v[64:65], v[22:23], v[198:199], v[64:65]
	v_pk_fma_f32 v[68:69], v[22:23], v[214:215], v[68:69]
	v_pk_fma_f32 v[64:65], v[24:25], v[200:201], v[64:65]
	v_pk_fma_f32 v[68:69], v[24:25], v[216:217], v[68:69]
	v_pk_fma_f32 v[64:65], v[26:27], v[202:203], v[64:65]
	v_pk_fma_f32 v[68:69], v[26:27], v[218:219], v[68:69]
	v_pk_fma_f32 v[64:65], v[28:29], v[204:205], v[64:65]
	v_pk_fma_f32 v[68:69], v[28:29], v[220:221], v[68:69]
	v_pk_fma_f32 v[64:65], v[30:31], v[206:207], v[64:65]
	v_pk_fma_f32 v[68:69], v[30:31], v[222:223], v[68:69]
	v_pk_fma_f32 v[66:67], v[48:49], v[192:193], v[66:67]
	v_pk_fma_f32 v[70:71], v[48:49], v[208:209], v[70:71]
	v_pk_fma_f32 v[66:67], v[50:51], v[194:195], v[66:67]
	v_pk_fma_f32 v[70:71], v[50:51], v[210:211], v[70:71]
	v_pk_fma_f32 v[66:67], v[52:53], v[196:197], v[66:67]
	v_pk_fma_f32 v[70:71], v[52:53], v[212:213], v[70:71]
	v_pk_fma_f32 v[66:67], v[54:55], v[198:199], v[66:67]
	v_pk_fma_f32 v[70:71], v[54:55], v[214:215], v[70:71]
	v_pk_fma_f32 v[66:67], v[56:57], v[200:201], v[66:67]
	v_pk_fma_f32 v[70:71], v[56:57], v[216:217], v[70:71]
	v_pk_fma_f32 v[66:67], v[58:59], v[202:203], v[66:67]
	v_pk_fma_f32 v[70:71], v[58:59], v[218:219], v[70:71]
	v_pk_fma_f32 v[66:67], v[60:61], v[204:205], v[66:67]
	v_pk_fma_f32 v[70:71], v[60:61], v[220:221], v[70:71]
	v_pk_fma_f32 v[66:67], v[62:63], v[206:207], v[66:67]
	v_pk_fma_f32 v[70:71], v[62:63], v[222:223], v[70:71]
	ds_read_b32 v249, v251 offset:0
	ds_read_b32 v250, v251 offset:128
	s_waitcnt lgkmcnt(0)
	v_mul_f32_e32 v240, v85, v249
	v_mul_f32_e32 v241, v86, v250
	v_add_f32_e32 v68, v68, v69
	v_add_f32_e32 v70, v70, v71
	v_add_f32_e32 v64, v64, v65
	v_add_f32_e32 v66, v66, v67
	v_mov_b32_e32 v245, v87
	v_permlane32_swap_b32_e32 v68, v70
	v_permlane32_swap_b32_e32 v64, v66
	v_add_f32_e32 v244, v68, v70
	v_add_f32_e32 v64, v64, v66
	v_bfe_u32 v66, v64, 16, 1
	v_add3_u32 v66, v64, v66, s69
	v_permlane32_swap_b32_e32 v244, v245
	global_store_short_d16_hi v72, v66, s[22:23] offset:-4096
	v_add_u32_e32 v72, 0x400, v72
	v_lshl_add_u64 v[74:75], v[74:75], 0, s[54:55]
	ds_read_b128 v[192:195], v76 offset:256
	ds_read_b128 v[196:199], v76 offset:288
	ds_read_b128 v[200:203], v76 offset:320
	ds_read_b128 v[204:207], v76 offset:352
	ds_read_b128 v[208:211], v76 offset:512
	ds_read_b128 v[212:215], v76 offset:544
	ds_read_b128 v[216:219], v76 offset:576
	ds_read_b128 v[220:223], v76 offset:608
	global_load_short_d16_hi v82, v72, s[4:5] offset:0
	global_load_short_d16_hi v83, v72, s[0:1] offset:0
	global_load_short_d16_hi v84, v72, s[12:13] offset:1024
	global_load_short_d16_hi v85, v[74:75], off offset:0
	global_load_short_d16_hi v86, v[74:75], off offset:64
	global_load_short_d16_hi v87, v72, s[2:3] offset:0
	v_mfma_f32_32x32x2_f32 v[0:15], v240, v244, v[0:15]
	v_mfma_f32_32x32x2_f32 v[32:47], v240, v245, v[32:47]
	ds_read_b128 v[148:151], v76 offset:384
	ds_read_b128 v[152:155], v76 offset:416
	ds_read_b128 v[156:159], v76 offset:448
	ds_read_b128 v[160:163], v76 offset:480
	ds_read_b128 v[164:167], v76 offset:640
	ds_read_b128 v[168:171], v76 offset:672
	ds_read_b128 v[172:175], v76 offset:704
	ds_read_b128 v[176:179], v76 offset:736
	v_mfma_f32_32x32x2_f32 v[16:31], v241, v244, v[16:31]
	v_mfma_f32_32x32x2_f32 v[48:63], v241, v245, v[48:63]
	v_mul_f32_e32 v78, 0xbfb8aa3b, v88
	v_exp_f32_e32 v78, v78
	s_nop 0
	v_mul_f32_e32 v246, v246, v78
	v_mul_f32_e32 v79, v89, v246
	v_mul_f32_e32 v80, v90, v246
	v_rcp_f32_e32 v248, v246
	s_nop 0
	ds_write2st64_b32 v77, v248, v79 offset0:3 offset1:4
	ds_write_b32 v77, v80 offset:1280
	s_waitcnt lgkmcnt(10)
	v_pk_mul_f32 v[64:65], v[0:1], v[192:193]
	v_pk_mul_f32 v[68:69], v[0:1], v[208:209]
	v_pk_fma_f32 v[64:65], v[2:3], v[194:195], v[64:65]
	v_pk_fma_f32 v[68:69], v[2:3], v[210:211], v[68:69]
	v_pk_fma_f32 v[64:65], v[4:5], v[196:197], v[64:65]
	v_pk_fma_f32 v[68:69], v[4:5], v[212:213], v[68:69]
	v_pk_fma_f32 v[64:65], v[6:7], v[198:199], v[64:65]
	v_pk_fma_f32 v[68:69], v[6:7], v[214:215], v[68:69]
	v_pk_fma_f32 v[64:65], v[8:9], v[200:201], v[64:65]
	v_pk_fma_f32 v[68:69], v[8:9], v[216:217], v[68:69]
	v_pk_fma_f32 v[64:65], v[10:11], v[202:203], v[64:65]
	v_pk_fma_f32 v[68:69], v[10:11], v[218:219], v[68:69]
	v_pk_fma_f32 v[64:65], v[12:13], v[204:205], v[64:65]
	v_pk_fma_f32 v[68:69], v[12:13], v[220:221], v[68:69]
	v_pk_fma_f32 v[64:65], v[14:15], v[206:207], v[64:65]
	v_pk_fma_f32 v[68:69], v[14:15], v[222:223], v[68:69]
	v_pk_mul_f32 v[66:67], v[32:33], v[192:193]
	v_pk_mul_f32 v[70:71], v[32:33], v[208:209]
	v_pk_fma_f32 v[66:67], v[34:35], v[194:195], v[66:67]
	v_pk_fma_f32 v[70:71], v[34:35], v[210:211], v[70:71]
	v_pk_fma_f32 v[66:67], v[36:37], v[196:197], v[66:67]
	v_pk_fma_f32 v[70:71], v[36:37], v[212:213], v[70:71]
	v_pk_fma_f32 v[66:67], v[38:39], v[198:199], v[66:67]
	v_pk_fma_f32 v[70:71], v[38:39], v[214:215], v[70:71]
	v_pk_fma_f32 v[66:67], v[40:41], v[200:201], v[66:67]
	v_pk_fma_f32 v[70:71], v[40:41], v[216:217], v[70:71]
	v_pk_fma_f32 v[66:67], v[42:43], v[202:203], v[66:67]
	v_pk_fma_f32 v[70:71], v[42:43], v[218:219], v[70:71]
	v_pk_fma_f32 v[66:67], v[44:45], v[204:205], v[66:67]
	v_pk_fma_f32 v[70:71], v[44:45], v[220:221], v[70:71]
	v_pk_fma_f32 v[66:67], v[46:47], v[206:207], v[66:67]
	v_pk_fma_f32 v[70:71], v[46:47], v[222:223], v[70:71]
	s_waitcnt lgkmcnt(2)
; template <bool ID> __device__ __forceinline__ void rwkv_scan(const bf16_t* __restrict__ R, const bf16_t* __restrict__ EW, const bf16_t* __restrict__ K, const bf16_t* __restrict__ V, ...
;     ...
;     for (int s = 0; s < nsteps; ++s) {
;         L[lane] = bf2f(q2[4]); L[64 + lane] = __expf(-bf2f(q1[1])); L[128 + lane] = bf2f(q1[5]); L[192 + lane] = bf2f(q1[2]); L[256 + lane] = bf2f(q1[0]);
;         const float v = bf2f(q1[3]);
; #pragma unroll
;         for (int j = 0; j < 6; ++j) q1[j] = q2[j];
;         { const unsigned o = base + (unsigned)(s + 2 < nsteps ? s + 2 : nsteps - 1) * 512u; q2[0] = R[o]; q2[1] = EW[o]; q2[2] = K[o]; q2[3] = V[o]; q2[4] = A[o]; q2[5] = B[o]; }
;         const f2 sav2 = {sav, sav}, sai2 = {sai, sai}, v2 = {v, v};
;         f2 yv = {0.f, 0.f}, yi = {0.f, 0.f}, yv1 = {0.f, 0.f}, yi1 = {0.f, 0.f}, nv = {0.f, 0.f}, ni = {0.f, 0.f}, nv1 = {0.f, 0.f}, ni1 = {0.f, 0.f};
;         f32x4 ca = pa[0], cw = pa[16], cb = pa[32], ck = pa[48], cr = pa[64];
; #pragma unroll
;         for (int q = 0; q < 16; ++q) {
;             const f32x4 a4 = ca, w4 = cw, b4 = cb, k4 = ck, r4 = cr;
;             if (q < 15) { ca = pa[1 + q]; cw = pa[17 + q]; cb = pa[33 + q]; ck = pa[49 + q]; cr = pa[65 + q]; }
;             __builtin_amdgcn_sched_barrier(0);
;             { const f2 a2 = {a4[0], a4[1]}, w2 = {w4[0], w4[1]}, b2 = {b4[0], b4[1]}, k2 = {k4[0], k4[1]}, r2 = {r4[0], r4[1]};
;               f2 tv = sav2 * b2; tv = pfma(v2, k2, tv); Sv[2 * q] = pfma(Sv[2 * q], w2, tv); yv = pfma(Sv[2 * q], r2, yv); nv = pfma(Sv[2 * q], a2, nv);
;               if (ID) { const f2 ti = sai2 * b2; Si[2 * q] = pfma(Si[2 * q], w2, ti); yi = pfma(Si[2 * q], r2, yi); ni = pfma(Si[2 * q], a2, ni); } }
;             { const f2 a2 = {a4[2], a4[3]}, w2 = {w4[2], w4[3]}, b2 = {b4[2], b4[3]}, k2 = {k4[2], k4[3]}, r2 = {r4[2], r4[3]};
;               f2 tv = sav2 * b2; tv = pfma(v2, k2, tv); Sv[2 * q + 1] = pfma(Sv[2 * q + 1], w2, tv); yv1 = pfma(Sv[2 * q + 1], r2, yv1); nv1 = pfma(Sv[2 * q + 1], a2, nv1);
;               if (ID) { const f2 ti = sai2 * b2; Si[2 * q + 1] = pfma(Si[2 * q + 1], w2, ti); yi1 = pfma(Si[2 * q + 1], r2, yi1); ni1 = pfma(Si[2 * q + 1], a2, ni1); } }
;         }
;         sav = (nv[0] + nv[1]) + (nv1[0] + nv1[1]); sai = (ni[0] + ni[1]) + (ni1[0] + ni1[1]);
;         const unsigned cbo = base + (unsigned)s * 512u;
	v_pk_fma_f32 v[64:65], v[16:17], v[148:149], v[64:65]
	v_pk_fma_f32 v[68:69], v[16:17], v[164:165], v[68:69]
	v_pk_fma_f32 v[64:65], v[18:19], v[150:151], v[64:65]
	v_pk_fma_f32 v[68:69], v[18:19], v[166:167], v[68:69]
	v_pk_fma_f32 v[64:65], v[20:21], v[152:153], v[64:65]
	v_pk_fma_f32 v[68:69], v[20:21], v[168:169], v[68:69]
	v_pk_fma_f32 v[64:65], v[22:23], v[154:155], v[64:65]
	v_pk_fma_f32 v[68:69], v[22:23], v[170:171], v[68:69]
	v_pk_fma_f32 v[64:65], v[24:25], v[156:157], v[64:65]
	v_pk_fma_f32 v[68:69], v[24:25], v[172:173], v[68:69]
	v_pk_fma_f32 v[64:65], v[26:27], v[158:159], v[64:65]
	v_pk_fma_f32 v[68:69], v[26:27], v[174:175], v[68:69]
	v_pk_fma_f32 v[64:65], v[28:29], v[160:161], v[64:65]
	v_pk_fma_f32 v[68:69], v[28:29], v[176:177], v[68:69]
	v_pk_fma_f32 v[64:65], v[30:31], v[162:163], v[64:65]
	v_pk_fma_f32 v[68:69], v[30:31], v[178:179], v[68:69]
	v_pk_fma_f32 v[66:67], v[48:49], v[148:149], v[66:67]
	v_pk_fma_f32 v[70:71], v[48:49], v[164:165], v[70:71]
	v_pk_fma_f32 v[66:67], v[50:51], v[150:151], v[66:67]
	v_pk_fma_f32 v[70:71], v[50:51], v[166:167], v[70:71]
	v_pk_fma_f32 v[66:67], v[52:53], v[152:153], v[66:67]
	v_pk_fma_f32 v[70:71], v[52:53], v[168:169], v[70:71]
	v_pk_fma_f32 v[66:67], v[54:55], v[154:155], v[66:67]
	v_pk_fma_f32 v[70:71], v[54:55], v[170:171], v[70:71]
	v_pk_fma_f32 v[66:67], v[56:57], v[156:157], v[66:67]
	v_pk_fma_f32 v[70:71], v[56:57], v[172:173], v[70:71]
	v_pk_fma_f32 v[66:67], v[58:59], v[158:159], v[66:67]
	v_pk_fma_f32 v[70:71], v[58:59], v[174:175], v[70:71]
	v_pk_fma_f32 v[66:67], v[60:61], v[160:161], v[66:67]
	v_pk_fma_f32 v[70:71], v[60:61], v[176:177], v[70:71]
	v_pk_fma_f32 v[66:67], v[62:63], v[162:163], v[66:67]
	v_pk_fma_f32 v[70:71], v[62:63], v[178:179], v[70:71]
	ds_read_b32 v249, v251 offset:768
	ds_read_b32 v250, v251 offset:896
	s_waitcnt lgkmcnt(0)
	v_mul_f32_e32 v240, v91, v249
	v_mul_f32_e32 v241, v92, v250
	v_add_f32_e32 v68, v68, v69
	v_add_f32_e32 v70, v70, v71
	v_add_f32_e32 v64, v64, v65
	v_add_f32_e32 v66, v66, v67
	v_mov_b32_e32 v245, v93
	v_permlane32_swap_b32_e32 v68, v70
	v_permlane32_swap_b32_e32 v64, v66
	v_add_f32_e32 v244, v68, v70
	v_add_f32_e32 v64, v64, v66
	v_bfe_u32 v66, v64, 16, 1
	v_add3_u32 v66, v64, v66, s69
	v_permlane32_swap_b32_e32 v244, v245
	global_store_short_d16_hi v72, v66, s[22:23] offset:-4096
	v_add_u32_e32 v72, 0x400, v72
	v_lshl_add_u64 v[74:75], v[74:75], 0, s[54:55]
	s_and_b32 s14, s41, 7
	s_cmp_eq_u32 s14, 7
	s_cbranch_scc1 .Lscan_s_s3x
	ds_read_b128 v[148:151], v76 offset:1024
	ds_read_b128 v[152:155], v76 offset:1056
	ds_read_b128 v[156:159], v76 offset:1088
	ds_read_b128 v[160:163], v76 offset:1120
	ds_read_b128 v[164:167], v76 offset:1280
	ds_read_b128 v[168:171], v76 offset:1312
	ds_read_b128 v[172:175], v76 offset:1344
	ds_read_b128 v[176:179], v76 offset:1376
	global_load_short_d16_hi v88, v72, s[4:5] offset:0
	global_load_short_d16_hi v89, v72, s[0:1] offset:0
	global_load_short_d16_hi v90, v72, s[12:13] offset:1024
	global_load_short_d16_hi v91, v[74:75], off offset:0
	global_load_short_d16_hi v92, v[74:75], off offset:64
	global_load_short_d16_hi v93, v72, s[2:3] offset:0
	v_mfma_f32_32x32x2_f32 v[0:15], v240, v244, v[0:15]
	v_mfma_f32_32x32x2_f32 v[32:47], v240, v245, v[32:47]
	ds_read_b128 v[192:195], v76 offset:1152
	ds_read_b128 v[196:199], v76 offset:1184
	ds_read_b128 v[200:203], v76 offset:1216
	ds_read_b128 v[204:207], v76 offset:1248
	ds_read_b128 v[208:211], v76 offset:1408
	ds_read_b128 v[212:215], v76 offset:1440
	ds_read_b128 v[216:219], v76 offset:1472
	ds_read_b128 v[220:223], v76 offset:1504
	v_mfma_f32_32x32x2_f32 v[16:31], v241, v244, v[16:31]
	v_mfma_f32_32x32x2_f32 v[48:63], v241, v245, v[48:63]
	s_waitcnt vmcnt(21)
	v_mul_f32_e32 v78, 0xbfb8aa3b, v224
	v_exp_f32_e32 v78, v78
	s_nop 0
	v_mul_f32_e32 v246, v246, v78
	v_mul_f32_e32 v79, v225, v246
	v_mul_f32_e32 v80, v226, v246
	v_rcp_f32_e32 v248, v246
	s_nop 0
	ds_write2st64_b32 v77, v248, v79 offset0:0 offset1:1
	ds_write_b32 v77, v80 offset:512
	s_waitcnt lgkmcnt(10)
	v_pk_mul_f32 v[64:65], v[0:1], v[148:149]
	v_pk_mul_f32 v[68:69], v[0:1], v[164:165]
	v_pk_fma_f32 v[64:65], v[2:3], v[150:151], v[64:65]
	v_pk_fma_f32 v[68:69], v[2:3], v[166:167], v[68:69]
	v_pk_fma_f32 v[64:65], v[4:5], v[152:153], v[64:65]
	v_pk_fma_f32 v[68:69], v[4:5], v[168:169], v[68:69]
	v_pk_fma_f32 v[64:65], v[6:7], v[154:155], v[64:65]
	v_pk_fma_f32 v[68:69], v[6:7], v[170:171], v[68:69]
	v_pk_fma_f32 v[64:65], v[8:9], v[156:157], v[64:65]
	v_pk_fma_f32 v[68:69], v[8:9], v[172:173], v[68:69]
	v_pk_fma_f32 v[64:65], v[10:11], v[158:159], v[64:65]
	v_pk_fma_f32 v[68:69], v[10:11], v[174:175], v[68:69]
	v_pk_fma_f32 v[64:65], v[12:13], v[160:161], v[64:65]
	v_pk_fma_f32 v[68:69], v[12:13], v[176:177], v[68:69]
	v_pk_fma_f32 v[64:65], v[14:15], v[162:163], v[64:65]
	v_pk_fma_f32 v[68:69], v[14:15], v[178:179], v[68:69]
	v_pk_mul_f32 v[66:67], v[32:33], v[148:149]
	v_pk_mul_f32 v[70:71], v[32:33], v[164:165]
	v_pk_fma_f32 v[66:67], v[34:35], v[150:151], v[66:67]
	v_pk_fma_f32 v[70:71], v[34:35], v[166:167], v[70:71]
	v_pk_fma_f32 v[66:67], v[36:37], v[152:153], v[66:67]
	v_pk_fma_f32 v[70:71], v[36:37], v[168:169], v[70:71]
	v_pk_fma_f32 v[66:67], v[38:39], v[154:155], v[66:67]
	v_pk_fma_f32 v[70:71], v[38:39], v[170:171], v[70:71]
	v_pk_fma_f32 v[66:67], v[40:41], v[156:157], v[66:67]
	v_pk_fma_f32 v[70:71], v[40:41], v[172:173], v[70:71]
	v_pk_fma_f32 v[66:67], v[42:43], v[158:159], v[66:67]
	v_pk_fma_f32 v[70:71], v[42:43], v[174:175], v[70:71]
	v_pk_fma_f32 v[66:67], v[44:45], v[160:161], v[66:67]
	v_pk_fma_f32 v[70:71], v[44:45], v[176:177], v[70:71]
	v_pk_fma_f32 v[66:67], v[46:47], v[162:163], v[66:67]
	v_pk_fma_f32 v[70:71], v[46:47], v[178:179], v[70:71]
	s_waitcnt lgkmcnt(2)
; template <bool ID> __device__ __forceinline__ void rwkv_scan(const bf16_t* __restrict__ R, const bf16_t* __restrict__ EW, const bf16_t* __restrict__ K, const bf16_t* __restrict__ V, ...
;     ...
;     for (int s = 0; s < nsteps; ++s) {
;         L[lane] = bf2f(q2[4]); L[64 + lane] = __expf(-bf2f(q1[1])); L[128 + lane] = bf2f(q1[5]); L[192 + lane] = bf2f(q1[2]); L[256 + lane] = bf2f(q1[0]);
;         const float v = bf2f(q1[3]);
; #pragma unroll
;         for (int j = 0; j < 6; ++j) q1[j] = q2[j];
;         { const unsigned o = base + (unsigned)(s + 2 < nsteps ? s + 2 : nsteps - 1) * 512u; q2[0] = R[o]; q2[1] = EW[o]; q2[2] = K[o]; q2[3] = V[o]; q2[4] = A[o]; q2[5] = B[o]; }
;         const f2 sav2 = {sav, sav}, sai2 = {sai, sai}, v2 = {v, v};
;         f2 yv = {0.f, 0.f}, yi = {0.f, 0.f}, yv1 = {0.f, 0.f}, yi1 = {0.f, 0.f}, nv = {0.f, 0.f}, ni = {0.f, 0.f}, nv1 = {0.f, 0.f}, ni1 = {0.f, 0.f};
;         f32x4 ca = pa[0], cw = pa[16], cb = pa[32], ck = pa[48], cr = pa[64];
; #pragma unroll
;         for (int q = 0; q < 16; ++q) {
;             const f32x4 a4 = ca, w4 = cw, b4 = cb, k4 = ck, r4 = cr;
;             if (q < 15) { ca = pa[1 + q]; cw = pa[17 + q]; cb = pa[33 + q]; ck = pa[49 + q]; cr = pa[65 + q]; }
;             __builtin_amdgcn_sched_barrier(0);
;             { const f2 a2 = {a4[0], a4[1]}, w2 = {w4[0], w4[1]}, b2 = {b4[0], b4[1]}, k2 = {k4[0], k4[1]}, r2 = {r4[0], r4[1]};
;               f2 tv = sav2 * b2; tv = pfma(v2, k2, tv); Sv[2 * q] = pfma(Sv[2 * q], w2, tv); yv = pfma(Sv[2 * q], r2, yv); nv = pfma(Sv[2 * q], a2, nv);
;               if (ID) { const f2 ti = sai2 * b2; Si[2 * q] = pfma(Si[2 * q], w2, ti); yi = pfma(Si[2 * q], r2, yi); ni = pfma(Si[2 * q], a2, ni); } }
;             { const f2 a2 = {a4[2], a4[3]}, w2 = {w4[2], w4[3]}, b2 = {b4[2], b4[3]}, k2 = {k4[2], k4[3]}, r2 = {r4[2], r4[3]};
;               f2 tv = sav2 * b2; tv = pfma(v2, k2, tv); Sv[2 * q + 1] = pfma(Sv[2 * q + 1], w2, tv); yv1 = pfma(Sv[2 * q + 1], r2, yv1); nv1 = pfma(Sv[2 * q + 1], a2, nv1);
;               if (ID) { const f2 ti = sai2 * b2; Si[2 * q + 1] = pfma(Si[2 * q + 1], w2, ti); yi1 = pfma(Si[2 * q + 1], r2, yi1); ni1 = pfma(Si[2 * q + 1], a2, ni1); } }
;         }
;         sav = (nv[0] + nv[1]) + (nv1[0] + nv1[1]); sai = (ni[0] + ni[1]) + (ni1[0] + ni1[1]);
;         const unsigned cbo = base + (unsigned)s * 512u;
	v_pk_fma_f32 v[64:65], v[16:17], v[192:193], v[64:65]
	v_pk_fma_f32 v[68:69], v[16:17], v[208:209], v[68:69]
	v_pk_fma_f32 v[64:65], v[18:19], v[194:195], v[64:65]
	v_pk_fma_f32 v[68:69], v[18:19], v[210:211], v[68:69]
	v_pk_fma_f32 v[64:65], v[20:21], v[196:197], v[64:65]
	v_pk_fma_f32 v[68:69], v[20:21], v[212:213], v[68:69]
	v_pk_fma_f32 v[64:65], v[22:23], v[198:199], v[64:65]
	v_pk_fma_f32 v[68:69], v[22:23], v[214:215], v[68:69]
	v_pk_fma_f32 v[64:65], v[24:25], v[200:201], v[64:65]
	v_pk_fma_f32 v[68:69], v[24:25], v[216:217], v[68:69]
	v_pk_fma_f32 v[64:65], v[26:27], v[202:203], v[64:65]
	v_pk_fma_f32 v[68:69], v[26:27], v[218:219], v[68:69]
	v_pk_fma_f32 v[64:65], v[28:29], v[204:205], v[64:65]
	v_pk_fma_f32 v[68:69], v[28:29], v[220:221], v[68:69]
	v_pk_fma_f32 v[64:65], v[30:31], v[206:207], v[64:65]
	v_pk_fma_f32 v[68:69], v[30:31], v[222:223], v[68:69]
	v_pk_fma_f32 v[66:67], v[48:49], v[192:193], v[66:67]
	v_pk_fma_f32 v[70:71], v[48:49], v[208:209], v[70:71]
	v_pk_fma_f32 v[66:67], v[50:51], v[194:195], v[66:67]
	v_pk_fma_f32 v[70:71], v[50:51], v[210:211], v[70:71]
	v_pk_fma_f32 v[66:67], v[52:53], v[196:197], v[66:67]
	v_pk_fma_f32 v[70:71], v[52:53], v[212:213], v[70:71]
	v_pk_fma_f32 v[66:67], v[54:55], v[198:199], v[66:67]
	v_pk_fma_f32 v[70:71], v[54:55], v[214:215], v[70:71]
	v_pk_fma_f32 v[66:67], v[56:57], v[200:201], v[66:67]
	v_pk_fma_f32 v[70:71], v[56:57], v[216:217], v[70:71]
	v_pk_fma_f32 v[66:67], v[58:59], v[202:203], v[66:67]
	v_pk_fma_f32 v[70:71], v[58:59], v[218:219], v[70:71]
	v_pk_fma_f32 v[66:67], v[60:61], v[204:205], v[66:67]
	v_pk_fma_f32 v[70:71], v[60:61], v[220:221], v[70:71]
	v_pk_fma_f32 v[66:67], v[62:63], v[206:207], v[66:67]
	v_pk_fma_f32 v[70:71], v[62:63], v[222:223], v[70:71]
	ds_read_b32 v249, v251 offset:0
	ds_read_b32 v250, v251 offset:128
	s_waitcnt lgkmcnt(0)
	v_mul_f32_e32 v240, v227, v249
	v_mul_f32_e32 v241, v228, v250
	v_add_f32_e32 v68, v68, v69
	v_add_f32_e32 v70, v70, v71
	v_add_f32_e32 v64, v64, v65
	v_add_f32_e32 v66, v66, v67
	v_mov_b32_e32 v245, v229
	v_permlane32_swap_b32_e32 v68, v70
	v_permlane32_swap_b32_e32 v64, v66
	v_add_f32_e32 v244, v68, v70
	v_add_f32_e32 v64, v64, v66
	v_bfe_u32 v66, v64, 16, 1
	v_add3_u32 v66, v64, v66, s69
	v_permlane32_swap_b32_e32 v244, v245
	global_store_short_d16_hi v72, v66, s[22:23] offset:-4096
	v_add_u32_e32 v72, 0x400, v72
	v_lshl_add_u64 v[74:75], v[74:75], 0, s[54:55]
	s_branch .Lscan_s_s3e
.Lscan_s_s3x:
	ds_read_b128 v[148:151], v76 offset:1024
	ds_read_b128 v[152:155], v76 offset:1056
	ds_read_b128 v[156:159], v76 offset:1088
	ds_read_b128 v[160:163], v76 offset:1120
	ds_read_b128 v[164:167], v76 offset:1280
	ds_read_b128 v[168:171], v76 offset:1312
	ds_read_b128 v[172:175], v76 offset:1344
	ds_read_b128 v[176:179], v76 offset:1376
	global_load_short_d16_hi v88, v72, s[4:5] offset:0
	global_load_short_d16_hi v89, v72, s[0:1] offset:0
	global_load_short_d16_hi v90, v72, s[12:13] offset:1024
	global_load_short_d16_hi v91, v[74:75], off offset:0
	global_load_short_d16_hi v92, v[74:75], off offset:64
	global_load_short_d16_hi v93, v72, s[2:3] offset:0
	v_mfma_f32_32x32x2_f32 v[0:15], v240, v244, v[0:15]
	v_mfma_f32_32x32x2_f32 v[32:47], v240, v245, v[32:47]
	ds_read_b128 v[192:195], v76 offset:1152
	ds_read_b128 v[196:199], v76 offset:1184
	ds_read_b128 v[200:203], v76 offset:1216
	ds_read_b128 v[204:207], v76 offset:1248
	ds_read_b128 v[208:211], v76 offset:1408
	ds_read_b128 v[212:215], v76 offset:1440
	ds_read_b128 v[216:219], v76 offset:1472
	ds_read_b128 v[220:223], v76 offset:1504
	v_mfma_f32_32x32x2_f32 v[16:31], v241, v244, v[16:31]
	v_mfma_f32_32x32x2_f32 v[48:63], v241, v245, v[48:63]
	s_waitcnt vmcnt(21)
	s_waitcnt lgkmcnt(8)
	s_nop 4
	v_pk_mul_f32 v[64:65], v[0:1], v[148:149]
	v_pk_mul_f32 v[68:69], v[0:1], v[164:165]
	v_pk_fma_f32 v[64:65], v[2:3], v[150:151], v[64:65]
	v_pk_fma_f32 v[68:69], v[2:3], v[166:167], v[68:69]
	v_pk_fma_f32 v[64:65], v[4:5], v[152:153], v[64:65]
	v_pk_fma_f32 v[68:69], v[4:5], v[168:169], v[68:69]
	v_pk_fma_f32 v[64:65], v[6:7], v[154:155], v[64:65]
	v_pk_fma_f32 v[68:69], v[6:7], v[170:171], v[68:69]
	v_pk_fma_f32 v[64:65], v[8:9], v[156:157], v[64:65]
	v_pk_fma_f32 v[68:69], v[8:9], v[172:173], v[68:69]
	v_pk_fma_f32 v[64:65], v[10:11], v[158:159], v[64:65]
	v_pk_fma_f32 v[68:69], v[10:11], v[174:175], v[68:69]
	v_pk_fma_f32 v[64:65], v[12:13], v[160:161], v[64:65]
	v_pk_fma_f32 v[68:69], v[12:13], v[176:177], v[68:69]
	v_pk_fma_f32 v[64:65], v[14:15], v[162:163], v[64:65]
	v_pk_fma_f32 v[68:69], v[14:15], v[178:179], v[68:69]
	v_pk_mul_f32 v[66:67], v[32:33], v[148:149]
	v_pk_mul_f32 v[70:71], v[32:33], v[164:165]
	v_pk_fma_f32 v[66:67], v[34:35], v[150:151], v[66:67]
	v_pk_fma_f32 v[70:71], v[34:35], v[166:167], v[70:71]
	v_pk_fma_f32 v[66:67], v[36:37], v[152:153], v[66:67]
	v_pk_fma_f32 v[70:71], v[36:37], v[168:169], v[70:71]
	v_pk_fma_f32 v[66:67], v[38:39], v[154:155], v[66:67]
	v_pk_fma_f32 v[70:71], v[38:39], v[170:171], v[70:71]
	v_pk_fma_f32 v[66:67], v[40:41], v[156:157], v[66:67]
	v_pk_fma_f32 v[70:71], v[40:41], v[172:173], v[70:71]
	v_pk_fma_f32 v[66:67], v[42:43], v[158:159], v[66:67]
	v_pk_fma_f32 v[70:71], v[42:43], v[174:175], v[70:71]
	v_pk_fma_f32 v[66:67], v[44:45], v[160:161], v[66:67]
	v_pk_fma_f32 v[70:71], v[44:45], v[176:177], v[70:71]
	v_pk_fma_f32 v[66:67], v[46:47], v[162:163], v[66:67]
	v_pk_fma_f32 v[70:71], v[46:47], v[178:179], v[70:71]
	s_waitcnt lgkmcnt(0)
; template <bool ID> __device__ __forceinline__ void rwkv_scan(const bf16_t* __restrict__ R, const bf16_t* __restrict__ EW, const bf16_t* __restrict__ K, const bf16_t* __restrict__ V, ...
;     ...
;     for (int s = 0; s < nsteps; ++s) {
;         L[lane] = bf2f(q2[4]); L[64 + lane] = __expf(-bf2f(q1[1])); L[128 + lane] = bf2f(q1[5]); L[192 + lane] = bf2f(q1[2]); L[256 + lane] = bf2f(q1[0]);
;         const float v = bf2f(q1[3]);
; #pragma unroll
;         for (int j = 0; j < 6; ++j) q1[j] = q2[j];
;         { const unsigned o = base + (unsigned)(s + 2 < nsteps ? s + 2 : nsteps - 1) * 512u; q2[0] = R[o]; q2[1] = EW[o]; q2[2] = K[o]; q2[3] = V[o]; q2[4] = A[o]; q2[5] = B[o]; }
;         const f2 sav2 = {sav, sav}, sai2 = {sai, sai}, v2 = {v, v};
;         f2 yv = {0.f, 0.f}, yi = {0.f, 0.f}, yv1 = {0.f, 0.f}, yi1 = {0.f, 0.f}, nv = {0.f, 0.f}, ni = {0.f, 0.f}, nv1 = {0.f, 0.f}, ni1 = {0.f, 0.f};
;         f32x4 ca = pa[0], cw = pa[16], cb = pa[32], ck = pa[48], cr = pa[64];
; #pragma unroll
;         for (int q = 0; q < 16; ++q) {
;             const f32x4 a4 = ca, w4 = cw, b4 = cb, k4 = ck, r4 = cr;
;             if (q < 15) { ca = pa[1 + q]; cw = pa[17 + q]; cb = pa[33 + q]; ck = pa[49 + q]; cr = pa[65 + q]; }
;             __builtin_amdgcn_sched_barrier(0);
;             { const f2 a2 = {a4[0], a4[1]}, w2 = {w4[0], w4[1]}, b2 = {b4[0], b4[1]}, k2 = {k4[0], k4[1]}, r2 = {r4[0], r4[1]};
;               f2 tv = sav2 * b2; tv = pfma(v2, k2, tv); Sv[2 * q] = pfma(Sv[2 * q], w2, tv); yv = pfma(Sv[2 * q], r2, yv); nv = pfma(Sv[2 * q], a2, nv);
;               if (ID) { const f2 ti = sai2 * b2; Si[2 * q] = pfma(Si[2 * q], w2, ti); yi = pfma(Si[2 * q], r2, yi); ni = pfma(Si[2 * q], a2, ni); } }
;             { const f2 a2 = {a4[2], a4[3]}, w2 = {w4[2], w4[3]}, b2 = {b4[2], b4[3]}, k2 = {k4[2], k4[3]}, r2 = {r4[2], r4[3]};
;               f2 tv = sav2 * b2; tv = pfma(v2, k2, tv); Sv[2 * q + 1] = pfma(Sv[2 * q + 1], w2, tv); yv1 = pfma(Sv[2 * q + 1], r2, yv1); nv1 = pfma(Sv[2 * q + 1], a2, nv1);
;               if (ID) { const f2 ti = sai2 * b2; Si[2 * q + 1] = pfma(Si[2 * q + 1], w2, ti); yi1 = pfma(Si[2 * q + 1], r2, yi1); ni1 = pfma(Si[2 * q + 1], a2, ni1); } }
;         }
;         sav = (nv[0] + nv[1]) + (nv1[0] + nv1[1]); sai = (ni[0] + ni[1]) + (ni1[0] + ni1[1]);
;         const unsigned cbo = base + (unsigned)s * 512u;
	v_pk_fma_f32 v[64:65], v[16:17], v[192:193], v[64:65]
	v_pk_fma_f32 v[68:69], v[16:17], v[208:209], v[68:69]
	v_pk_fma_f32 v[64:65], v[18:19], v[194:195], v[64:65]
	v_pk_fma_f32 v[68:69], v[18:19], v[210:211], v[68:69]
	v_pk_fma_f32 v[64:65], v[20:21], v[196:197], v[64:65]
	v_pk_fma_f32 v[68:69], v[20:21], v[212:213], v[68:69]
	v_pk_fma_f32 v[64:65], v[22:23], v[198:199], v[64:65]
	v_pk_fma_f32 v[68:69], v[22:23], v[214:215], v[68:69]
	v_pk_fma_f32 v[64:65], v[24:25], v[200:201], v[64:65]
	v_pk_fma_f32 v[68:69], v[24:25], v[216:217], v[68:69]
	v_pk_fma_f32 v[64:65], v[26:27], v[202:203], v[64:65]
	v_pk_fma_f32 v[68:69], v[26:27], v[218:219], v[68:69]
	v_pk_fma_f32 v[64:65], v[28:29], v[204:205], v[64:65]
	v_pk_fma_f32 v[68:69], v[28:29], v[220:221], v[68:69]
	v_pk_fma_f32 v[64:65], v[30:31], v[206:207], v[64:65]
	v_pk_fma_f32 v[68:69], v[30:31], v[222:223], v[68:69]
	v_pk_fma_f32 v[66:67], v[48:49], v[192:193], v[66:67]
	v_pk_fma_f32 v[70:71], v[48:49], v[208:209], v[70:71]
	v_pk_fma_f32 v[66:67], v[50:51], v[194:195], v[66:67]
	v_pk_fma_f32 v[70:71], v[50:51], v[210:211], v[70:71]
	v_pk_fma_f32 v[66:67], v[52:53], v[196:197], v[66:67]
	v_pk_fma_f32 v[70:71], v[52:53], v[212:213], v[70:71]
	v_pk_fma_f32 v[66:67], v[54:55], v[198:199], v[66:67]
	v_pk_fma_f32 v[70:71], v[54:55], v[214:215], v[70:71]
	v_pk_fma_f32 v[66:67], v[56:57], v[200:201], v[66:67]
	v_pk_fma_f32 v[70:71], v[56:57], v[216:217], v[70:71]
	v_pk_fma_f32 v[66:67], v[58:59], v[202:203], v[66:67]
	v_pk_fma_f32 v[70:71], v[58:59], v[218:219], v[70:71]
	v_pk_fma_f32 v[66:67], v[60:61], v[204:205], v[66:67]
	v_pk_fma_f32 v[70:71], v[60:61], v[220:221], v[70:71]
	v_pk_fma_f32 v[66:67], v[62:63], v[206:207], v[66:67]
	v_pk_fma_f32 v[70:71], v[62:63], v[222:223], v[70:71]
	v_add_f32_e32 v68, v68, v69
	v_add_f32_e32 v70, v70, v71
	v_add_f32_e32 v64, v64, v65
	v_add_f32_e32 v66, v66, v67
	v_mov_b32_e32 v245, v229
	v_permlane32_swap_b32_e32 v68, v70
	v_permlane32_swap_b32_e32 v64, v66
	v_add_f32_e32 v244, v68, v70
	v_add_f32_e32 v64, v64, v66
	v_bfe_u32 v66, v64, 16, 1
	v_add3_u32 v66, v64, v66, s69
	v_permlane32_swap_b32_e32 v244, v245
	global_store_short_d16_hi v72, v66, s[22:23] offset:-4096
	ds_write_b32 v77, v246 offset:0
	ds_read_b128 v[148:151], v76 offset:0
	ds_read_b128 v[152:155], v76 offset:32
	ds_read_b128 v[156:159], v76 offset:64
	ds_read_b128 v[160:163], v76 offset:96
	ds_read_b128 v[164:167], v76 offset:128
	ds_read_b128 v[168:171], v76 offset:160
	ds_read_b128 v[172:175], v76 offset:192
	ds_read_b128 v[176:179], v76 offset:224
	s_waitcnt lgkmcnt(0)
	v_pk_mul_f32 v[0:1], v[0:1], v[148:149]
	v_pk_mul_f32 v[2:3], v[2:3], v[150:151]
	v_pk_mul_f32 v[4:5], v[4:5], v[152:153]
	v_pk_mul_f32 v[6:7], v[6:7], v[154:155]
	v_pk_mul_f32 v[8:9], v[8:9], v[156:157]
	v_pk_mul_f32 v[10:11], v[10:11], v[158:159]
	v_pk_mul_f32 v[12:13], v[12:13], v[160:161]
	v_pk_mul_f32 v[14:15], v[14:15], v[162:163]
	v_pk_mul_f32 v[16:17], v[16:17], v[164:165]
	v_pk_mul_f32 v[18:19], v[18:19], v[166:167]
	v_pk_mul_f32 v[20:21], v[20:21], v[168:169]
	v_pk_mul_f32 v[22:23], v[22:23], v[170:171]
	v_pk_mul_f32 v[24:25], v[24:25], v[172:173]
	v_pk_mul_f32 v[26:27], v[26:27], v[174:175]
	v_pk_mul_f32 v[28:29], v[28:29], v[176:177]
	v_pk_mul_f32 v[30:31], v[30:31], v[178:179]
	v_pk_mul_f32 v[32:33], v[32:33], v[148:149]
	v_pk_mul_f32 v[34:35], v[34:35], v[150:151]
	v_pk_mul_f32 v[36:37], v[36:37], v[152:153]
	v_pk_mul_f32 v[38:39], v[38:39], v[154:155]
	v_pk_mul_f32 v[40:41], v[40:41], v[156:157]
	v_pk_mul_f32 v[42:43], v[42:43], v[158:159]
	v_pk_mul_f32 v[44:45], v[44:45], v[160:161]
	v_pk_mul_f32 v[46:47], v[46:47], v[162:163]
	v_pk_mul_f32 v[48:49], v[48:49], v[164:165]
	v_pk_mul_f32 v[50:51], v[50:51], v[166:167]
	v_pk_mul_f32 v[52:53], v[52:53], v[168:169]
	v_pk_mul_f32 v[54:55], v[54:55], v[170:171]
	v_pk_mul_f32 v[56:57], v[56:57], v[172:173]
	v_pk_mul_f32 v[58:59], v[58:59], v[174:175]
	v_pk_mul_f32 v[60:61], v[60:61], v[176:177]
	v_pk_mul_f32 v[62:63], v[62:63], v[178:179]
	v_mov_b32_e32 v246, 1.0
	v_mul_f32_e32 v78, 0xbfb8aa3b, v224
	v_exp_f32_e32 v78, v78
	s_nop 0
	v_mul_f32_e32 v246, v246, v78
	v_mul_f32_e32 v79, v225, v246
	v_mul_f32_e32 v80, v226, v246
	v_rcp_f32_e32 v248, v246
	s_nop 0
	ds_write2st64_b32 v77, v248, v79 offset0:0 offset1:1
	ds_write_b32 v77, v80 offset:512
	ds_read_b32 v249, v251 offset:0
	ds_read_b32 v250, v251 offset:128
	s_waitcnt lgkmcnt(0)
	v_mul_f32_e32 v240, v227, v249
	v_mul_f32_e32 v241, v228, v250
	s_waitcnt lgkmcnt(0)
	v_add_u32_e32 v72, 0x400, v72
	v_lshl_add_u64 v[74:75], v[74:75], 0, s[54:55]

; __device__ __forceinline__ int tidx() { int t = threadIdx.x; asm volatile("" : "+v"(t)); return t; }
; __device__ __forceinline__ int bidx() { int b = blockIdx.x; asm volatile("" : "+s"(b)); return b; }
; __device__ __forceinline__ float bf2f(unsigned short b) { return __uint_as_float((unsigned)b << 16); }
; __device__ __forceinline__ f2 pfma(f2 a, f2 b, f2 c) { return __builtin_elementwise_fma(a, b, c); }
; template <bool ID> __device__ __forceinline__ void rwkv_scan(const bf16_t* __restrict__ R, const bf16_t* __restrict__ EW, const bf16_t* __restrict__ K, const bf16_t* __restrict__ V, ...
;     ...
;     { unsigned o = base; q1[0] = R[o]; q1[1] = EW[o]; q1[2] = K[o]; q1[3] = V[o]; q1[4] = A[o]; q1[5] = B[o];
;       o = base + 512u; q2[0] = R[o]; q2[1] = EW[o]; q2[2] = K[o]; q2[3] = V[o]; q2[4] = A[o]; q2[5] = B[o]; }
;     const LAS f32x4* pa = (const LAS f32x4*)L;
;     float sav, sai;
;     { L[lane] = bf2f(q1[4]);
;       f2 av = {0.f, 0.f}, ai = {0.f, 0.f};
; #pragma unroll
;       for (int q = 0; q < 16; ++q) { const f32x4 a4 = pa[q]; const f2 a01 = {a4[0], a4[1]}, a23 = {a4[2], a4[3]};
;           av = pfma(Sv[2 * q], a01, av); av = pfma(Sv[2 * q + 1], a23, av); if (ID) { ai = pfma(Si[2 * q], a01, ai); ai = pfma(Si[2 * q + 1], a23, ai); } }
;       sav = av[0] + av[1]; sai = ai[0] + ai[1]; }
; __device__ void phase_rwkv_scan(const Ctx& p, int l, LAS unsigned char* lds) {
;     ...
;         for (int item = bidx() * 4 + wave; item < 1024; item += gridDim.x * 4) {
;             const int b = item >> 9, c = (item >> 3) & 63, h = item & 7;
;             f2 Sv[32], Si[32]; const int li = tidx() & 63;
; #pragma unroll
;             for (int i = 0; i < 32; ++i) { Sv[i] = (f2){0.f, 0.f}; Si[i] = (f2){(2 * i == li) ? 1.f : 0.f, (2 * i + 1 == li) ? 1.f : 0.f}; }
;             rwkv_scan<true>(R, EW, K, V, A, B, (unsigned)((b * 8192 + c * 128) * 512 + h * 64 + lane), 128, Sv, Si, YH, QH, L, lane);
.Lscan_v:
	v_lshrrev_b32_e32 v78, 5, v139
	v_and_b32_e32 v79, 31, v139
	s_mov_b32 s26, -1
	s_mov_b32 s27, 0
	s_lshl_b32 s14, s36, 13
	s_and_b32 s14, s14, 0xffff0000
	s_lshl_b32 s15, s36, 6
	s_and_b32 s15, s15, 0x1c0
	s_or_b32 s14, s14, s15
	v_add_lshl_u32 v72, s14, v139, 1
	v_add_lshl_u32 v81, s14, v79, 1
	v_mov_b32_e32 v74, s20
	v_mov_b32_e32 v75, s21
	v_mov_b32_e32 v80, s6
	v_cndmask_b32_e64 v74, v80, v74, s[26:27]
	v_mov_b32_e32 v80, s7
	v_cndmask_b32_e64 v75, v80, v75, s[26:27]
	v_add_co_u32_e32 v74, vcc, v74, v81
	s_nop 1
	v_addc_co_u32_e32 v75, vcc, 0, v75, vcc
	v_lshl_add_u32 v76, v78, 4, s10
	v_lshl_add_u32 v77, v139, 2, s10
	v_lshl_add_u32 v251, v79, 2, s10
	v_mov_b32_e32 v246, 1.0
	v_lshlrev_b32_e32 v81, 2, v78
	v_sub_u32_e32 v81, v79, v81
	global_load_short_d16_hi v224, v72, s[4:5] offset:0
	global_load_short_d16_hi v225, v72, s[0:1] offset:0
	global_load_short_d16_hi v226, v72, s[12:13] offset:1024
	global_load_short_d16_hi v227, v[74:75], off offset:0
	global_load_short_d16_hi v228, v[74:75], off offset:64
	global_load_short_d16_hi v229, v72, s[2:3] offset:0
	global_load_short_d16_hi v230, v72, s[4:5] offset:1024
	global_load_short_d16_hi v231, v72, s[0:1] offset:1024
	global_load_short_d16_hi v232, v72, s[12:13] offset:2048
	global_load_short_d16_hi v233, v[74:75], off offset:1024
	global_load_short_d16_hi v234, v[74:75], off offset:1088
	global_load_short_d16_hi v235, v72, s[2:3] offset:1024
	global_load_short_d16_hi v82, v72, s[4:5] offset:2048
	global_load_short_d16_hi v83, v72, s[0:1] offset:2048
	global_load_short_d16_hi v84, v72, s[12:13] offset:3072
	global_load_short_d16_hi v85, v[74:75], off offset:2048
	global_load_short_d16_hi v86, v[74:75], off offset:2112
	global_load_short_d16_hi v87, v72, s[2:3] offset:2048
	v_add_u32_e32 v72, 0xc00, v72
	v_lshl_add_u64 v[74:75], v[74:75], 0, s[54:55]
	v_lshl_add_u64 v[74:75], v[74:75], 0, s[54:55]
	v_lshl_add_u64 v[74:75], v[74:75], 0, s[54:55]
	global_load_short_d16_hi v88, v72, s[4:5] offset:0
	global_load_short_d16_hi v89, v72, s[0:1] offset:0
	global_load_short_d16_hi v90, v72, s[12:13] offset:1024
	global_load_short_d16_hi v91, v[74:75], off offset:0
	global_load_short_d16_hi v92, v[74:75], off offset:64
	global_load_short_d16_hi v93, v72, s[2:3] offset:0
	v_add_u32_e32 v72, 0x400, v72
	v_lshl_add_u64 v[74:75], v[74:75], 0, s[54:55]
	v_mov_b32_e32 v0, 0
	v_mov_b32_e32 v1, 0
	v_mov_b32_e32 v2, 0
	v_mov_b32_e32 v3, 0
	v_mov_b32_e32 v4, 0
	v_mov_b32_e32 v5, 0
	v_mov_b32_e32 v6, 0
	v_mov_b32_e32 v7, 0
	v_mov_b32_e32 v8, 0
	v_mov_b32_e32 v9, 0
	v_mov_b32_e32 v10, 0
	v_mov_b32_e32 v11, 0
	v_mov_b32_e32 v12, 0
	v_mov_b32_e32 v13, 0
	v_mov_b32_e32 v14, 0
	v_mov_b32_e32 v15, 0
	v_mov_b32_e32 v16, 0
	v_mov_b32_e32 v17, 0
	v_mov_b32_e32 v18, 0
	v_mov_b32_e32 v19, 0
	v_mov_b32_e32 v20, 0
	v_mov_b32_e32 v21, 0
	v_mov_b32_e32 v22, 0
	v_mov_b32_e32 v23, 0
	v_mov_b32_e32 v24, 0
	v_mov_b32_e32 v25, 0
	v_mov_b32_e32 v26, 0
	v_mov_b32_e32 v27, 0
	v_mov_b32_e32 v28, 0
	v_mov_b32_e32 v29, 0
	v_mov_b32_e32 v30, 0
	v_mov_b32_e32 v31, 0
	v_mov_b32_e32 v32, 0
	v_mov_b32_e32 v33, 0
	v_mov_b32_e32 v34, 0
	v_mov_b32_e32 v35, 0
	v_mov_b32_e32 v36, 0
	v_mov_b32_e32 v37, 0
	v_mov_b32_e32 v38, 0
	v_mov_b32_e32 v39, 0
	v_mov_b32_e32 v40, 0
	v_mov_b32_e32 v41, 0
	v_mov_b32_e32 v42, 0
	v_mov_b32_e32 v43, 0
	v_mov_b32_e32 v44, 0
	v_mov_b32_e32 v45, 0
	v_mov_b32_e32 v46, 0
	v_mov_b32_e32 v47, 0
	v_mov_b32_e32 v48, 0
	v_mov_b32_e32 v49, 0
	v_mov_b32_e32 v50, 0
	v_mov_b32_e32 v51, 0
	v_mov_b32_e32 v52, 0
	v_mov_b32_e32 v53, 0
	v_mov_b32_e32 v54, 0
	v_mov_b32_e32 v55, 0
	v_mov_b32_e32 v56, 0
	v_mov_b32_e32 v57, 0
	v_mov_b32_e32 v58, 0
	v_mov_b32_e32 v59, 0
	v_mov_b32_e32 v60, 0
	v_mov_b32_e32 v61, 0
	v_mov_b32_e32 v62, 0
	v_mov_b32_e32 v63, 0
	s_waitcnt vmcnt(18)
	v_mul_f32_e32 v78, 0xbfb8aa3b, v224
	v_exp_f32_e32 v78, v78
	s_nop 0
	v_mul_f32_e32 v246, v246, v78
	v_mul_f32_e32 v79, v225, v246
	v_mul_f32_e32 v80, v226, v246
	v_rcp_f32_e32 v248, v246
	s_nop 0
	ds_write2st64_b32 v77, v248, v79 offset0:0 offset1:1
	ds_write_b32 v77, v80 offset:512
	ds_read_b32 v249, v251 offset:0
	ds_read_b32 v250, v251 offset:128
	s_waitcnt lgkmcnt(0)
	v_mul_f32_e32 v240, v227, v249
	v_mul_f32_e32 v241, v228, v250
	v_mov_b32_e32 v244, 0
	v_mov_b32_e32 v245, v229
	s_nop 0
	s_nop 0
	v_permlane32_swap_b32_e32 v244, v245
	s_movk_i32 s41, 0
; template <bool ID> __device__ __forceinline__ void rwkv_scan(const bf16_t* __restrict__ R, const bf16_t* __restrict__ EW, const bf16_t* __restrict__ K, const bf16_t* __restrict__ V, ...
;     ...
;     for (int s = 0; s < nsteps; ++s) {
;         L[lane] = bf2f(q2[4]); L[64 + lane] = __expf(-bf2f(q1[1])); L[128 + lane] = bf2f(q1[5]); L[192 + lane] = bf2f(q1[2]); L[256 + lane] = bf2f(q1[0]);
;         const float v = bf2f(q1[3]);
; #pragma unroll
;         for (int j = 0; j < 6; ++j) q1[j] = q2[j];
;         { const unsigned o = base + (unsigned)(s + 2 < nsteps ? s + 2 : nsteps - 1) * 512u; q2[0] = R[o]; q2[1] = EW[o]; q2[2] = K[o]; q2[3] = V[o]; q2[4] = A[o]; q2[5] = B[o]; }
;         const f2 sav2 = {sav, sav}, sai2 = {sai, sai}, v2 = {v, v};
;         f2 yv = {0.f, 0.f}, yi = {0.f, 0.f}, yv1 = {0.f, 0.f}, yi1 = {0.f, 0.f}, nv = {0.f, 0.f}, ni = {0.f, 0.f}, nv1 = {0.f, 0.f}, ni1 = {0.f, 0.f};
;         f32x4 ca = pa[0], cw = pa[16], cb = pa[32], ck = pa[48], cr = pa[64];
; #pragma unroll
;         for (int q = 0; q < 16; ++q) {
;             const f32x4 a4 = ca, w4 = cw, b4 = cb, k4 = ck, r4 = cr;
;             if (q < 15) { ca = pa[1 + q]; cw = pa[17 + q]; cb = pa[33 + q]; ck = pa[49 + q]; cr = pa[65 + q]; }
;             __builtin_amdgcn_sched_barrier(0);
;             { const f2 a2 = {a4[0], a4[1]}, w2 = {w4[0], w4[1]}, b2 = {b4[0], b4[1]}, k2 = {k4[0], k4[1]}, r2 = {r4[0], r4[1]};
;               f2 tv = sav2 * b2; tv = pfma(v2, k2, tv); Sv[2 * q] = pfma(Sv[2 * q], w2, tv); yv = pfma(Sv[2 * q], r2, yv); nv = pfma(Sv[2 * q], a2, nv);
;               if (ID) { const f2 ti = sai2 * b2; Si[2 * q] = pfma(Si[2 * q], w2, ti); yi = pfma(Si[2 * q], r2, yi); ni = pfma(Si[2 * q], a2, ni); } }
;             { const f2 a2 = {a4[2], a4[3]}, w2 = {w4[2], w4[3]}, b2 = {b4[2], b4[3]}, k2 = {k4[2], k4[3]}, r2 = {r4[2], r4[3]};
;               f2 tv = sav2 * b2; tv = pfma(v2, k2, tv); Sv[2 * q + 1] = pfma(Sv[2 * q + 1], w2, tv); yv1 = pfma(Sv[2 * q + 1], r2, yv1); nv1 = pfma(Sv[2 * q + 1], a2, nv1);
;               if (ID) { const f2 ti = sai2 * b2; Si[2 * q + 1] = pfma(Si[2 * q + 1], w2, ti); yi1 = pfma(Si[2 * q + 1], r2, yi1); ni1 = pfma(Si[2 * q + 1], a2, ni1); } }
;         }
;         sav = (nv[0] + nv[1]) + (nv1[0] + nv1[1]); sai = (ni[0] + ni[1]) + (ni1[0] + ni1[1]);
;         const unsigned cbo = base + (unsigned)s * 512u;
.Lscan_v_loop:
	ds_read_b128 v[192:195], v76 offset:256
	ds_read_b128 v[196:199], v76 offset:288
	ds_read_b128 v[200:203], v76 offset:320
	ds_read_b128 v[204:207], v76 offset:352
	ds_read_b128 v[208:211], v76 offset:512
	ds_read_b128 v[212:215], v76 offset:544
	ds_read_b128 v[216:219], v76 offset:576
	ds_read_b128 v[220:223], v76 offset:608
	global_load_short_d16_hi v224, v72, s[4:5] offset:0
	global_load_short_d16_hi v225, v72, s[0:1] offset:0
	global_load_short_d16_hi v226, v72, s[12:13] offset:1024
	global_load_short_d16_hi v227, v[74:75], off offset:0
	global_load_short_d16_hi v228, v[74:75], off offset:64
	global_load_short_d16_hi v229, v72, s[2:3] offset:0
	v_mfma_f32_32x32x2_f32 v[0:15], v240, v244, v[0:15]
	v_mfma_f32_32x32x2_f32 v[32:47], v240, v245, v[32:47]
	ds_read_b128 v[148:151], v76 offset:384
	ds_read_b128 v[152:155], v76 offset:416
	ds_read_b128 v[156:159], v76 offset:448
	ds_read_b128 v[160:163], v76 offset:480
	ds_read_b128 v[164:167], v76 offset:640
	ds_read_b128 v[168:171], v76 offset:672
	ds_read_b128 v[172:175], v76 offset:704
	ds_read_b128 v[176:179], v76 offset:736
	v_mfma_f32_32x32x2_f32 v[16:31], v241, v244, v[16:31]
	v_mfma_f32_32x32x2_f32 v[48:63], v241, v245, v[48:63]
	s_waitcnt vmcnt(18)
	v_mul_f32_e32 v78, 0xbfb8aa3b, v230
	v_exp_f32_e32 v78, v78
	s_nop 0
	v_mul_f32_e32 v246, v246, v78
	v_mul_f32_e32 v79, v231, v246
	v_mul_f32_e32 v80, v232, v246
	v_rcp_f32_e32 v248, v246
	s_nop 0
	ds_write2st64_b32 v77, v248, v79 offset0:3 offset1:4
	ds_write_b32 v77, v80 offset:1280
	s_waitcnt lgkmcnt(10)
	v_pk_mul_f32 v[64:65], v[0:1], v[192:193]
	v_pk_mul_f32 v[68:69], v[0:1], v[208:209]
	v_pk_fma_f32 v[64:65], v[2:3], v[194:195], v[64:65]
	v_pk_fma_f32 v[68:69], v[2:3], v[210:211], v[68:69]
	v_pk_fma_f32 v[64:65], v[4:5], v[196:197], v[64:65]
	v_pk_fma_f32 v[68:69], v[4:5], v[212:213], v[68:69]
	v_pk_fma_f32 v[64:65], v[6:7], v[198:199], v[64:65]
	v_pk_fma_f32 v[68:69], v[6:7], v[214:215], v[68:69]
	v_pk_fma_f32 v[64:65], v[8:9], v[200:201], v[64:65]
	v_pk_fma_f32 v[68:69], v[8:9], v[216:217], v[68:69]
	v_pk_fma_f32 v[64:65], v[10:11], v[202:203], v[64:65]
	v_pk_fma_f32 v[68:69], v[10:11], v[218:219], v[68:69]
	v_pk_fma_f32 v[64:65], v[12:13], v[204:205], v[64:65]
	v_pk_fma_f32 v[68:69], v[12:13], v[220:221], v[68:69]
	v_pk_fma_f32 v[64:65], v[14:15], v[206:207], v[64:65]
	v_pk_fma_f32 v[68:69], v[14:15], v[222:223], v[68:69]
	v_pk_mul_f32 v[66:67], v[32:33], v[192:193]
	v_pk_mul_f32 v[70:71], v[32:33], v[208:209]
	v_pk_fma_f32 v[66:67], v[34:35], v[194:195], v[66:67]
	v_pk_fma_f32 v[70:71], v[34:35], v[210:211], v[70:71]
	v_pk_fma_f32 v[66:67], v[36:37], v[196:197], v[66:67]
	v_pk_fma_f32 v[70:71], v[36:37], v[212:213], v[70:71]
	v_pk_fma_f32 v[66:67], v[38:39], v[198:199], v[66:67]
	v_pk_fma_f32 v[70:71], v[38:39], v[214:215], v[70:71]
	v_pk_fma_f32 v[66:67], v[40:41], v[200:201], v[66:67]
	v_pk_fma_f32 v[70:71], v[40:41], v[216:217], v[70:71]
	v_pk_fma_f32 v[66:67], v[42:43], v[202:203], v[66:67]
	v_pk_fma_f32 v[70:71], v[42:43], v[218:219], v[70:71]
	v_pk_fma_f32 v[66:67], v[44:45], v[204:205], v[66:67]
	v_pk_fma_f32 v[70:71], v[44:45], v[220:221], v[70:71]
	v_pk_fma_f32 v[66:67], v[46:47], v[206:207], v[66:67]
	v_pk_fma_f32 v[70:71], v[46:47], v[222:223], v[70:71]
	s_waitcnt lgkmcnt(2)
	v_pk_fma_f32 v[64:65], v[16:17], v[148:149], v[64:65]
	v_pk_fma_f32 v[68:69], v[16:17], v[164:165], v[68:69]
	v_pk_fma_f32 v[64:65], v[18:19], v[150:151], v[64:65]
	v_pk_fma_f32 v[68:69], v[18:19], v[166:167], v[68:69]
	v_pk_fma_f32 v[64:65], v[20:21], v[152:153], v[64:65]
	v_pk_fma_f32 v[68:69], v[20:21], v[168:169], v[68:69]
	v_pk_fma_f32 v[64:65], v[22:23], v[154:155], v[64:65]
	v_pk_fma_f32 v[68:69], v[22:23], v[170:171], v[68:69]
	v_pk_fma_f32 v[64:65], v[24:25], v[156:157], v[64:65]
	v_pk_fma_f32 v[68:69], v[24:25], v[172:173], v[68:69]
	v_pk_fma_f32 v[64:65], v[26:27], v[158:159], v[64:65]
	v_pk_fma_f32 v[68:69], v[26:27], v[174:175], v[68:69]
	v_pk_fma_f32 v[64:65], v[28:29], v[160:161], v[64:65]
	v_pk_fma_f32 v[68:69], v[28:29], v[176:177], v[68:69]
	v_pk_fma_f32 v[64:65], v[30:31], v[162:163], v[64:65]
	v_pk_fma_f32 v[68:69], v[30:31], v[178:179], v[68:69]
	v_pk_fma_f32 v[66:67], v[48:49], v[148:149], v[66:67]
	v_pk_fma_f32 v[70:71], v[48:49], v[164:165], v[70:71]
	v_pk_fma_f32 v[66:67], v[50:51], v[150:151], v[66:67]
	v_pk_fma_f32 v[70:71], v[50:51], v[166:167], v[70:71]
	v_pk_fma_f32 v[66:67], v[52:53], v[152:153], v[66:67]
	v_pk_fma_f32 v[70:71], v[52:53], v[168:169], v[70:71]
	v_pk_fma_f32 v[66:67], v[54:55], v[154:155], v[66:67]
	v_pk_fma_f32 v[70:71], v[54:55], v[170:171], v[70:71]
	v_pk_fma_f32 v[66:67], v[56:57], v[156:157], v[66:67]
	v_pk_fma_f32 v[70:71], v[56:57], v[172:173], v[70:71]
	v_pk_fma_f32 v[66:67], v[58:59], v[158:159], v[66:67]
	v_pk_fma_f32 v[70:71], v[58:59], v[174:175], v[70:71]
	v_pk_fma_f32 v[66:67], v[60:61], v[160:161], v[66:67]
	v_pk_fma_f32 v[70:71], v[60:61], v[176:177], v[70:71]
	v_pk_fma_f32 v[66:67], v[62:63], v[162:163], v[66:67]
	v_pk_fma_f32 v[70:71], v[62:63], v[178:179], v[70:71]
	ds_read_b32 v249, v251 offset:768
	ds_read_b32 v250, v251 offset:896
	s_waitcnt lgkmcnt(0)
; template <bool ID> __device__ __forceinline__ void rwkv_scan(const bf16_t* __restrict__ R, const bf16_t* __restrict__ EW, const bf16_t* __restrict__ K, const bf16_t* __restrict__ V, ...
;     ...
;     for (int s = 0; s < nsteps; ++s) {
;         L[lane] = bf2f(q2[4]); L[64 + lane] = __expf(-bf2f(q1[1])); L[128 + lane] = bf2f(q1[5]); L[192 + lane] = bf2f(q1[2]); L[256 + lane] = bf2f(q1[0]);
;         const float v = bf2f(q1[3]);
; #pragma unroll
;         for (int j = 0; j < 6; ++j) q1[j] = q2[j];
;         { const unsigned o = base + (unsigned)(s + 2 < nsteps ? s + 2 : nsteps - 1) * 512u; q2[0] = R[o]; q2[1] = EW[o]; q2[2] = K[o]; q2[3] = V[o]; q2[4] = A[o]; q2[5] = B[o]; }
;         const f2 sav2 = {sav, sav}, sai2 = {sai, sai}, v2 = {v, v};
;         f2 yv = {0.f, 0.f}, yi = {0.f, 0.f}, yv1 = {0.f, 0.f}, yi1 = {0.f, 0.f}, nv = {0.f, 0.f}, ni = {0.f, 0.f}, nv1 = {0.f, 0.f}, ni1 = {0.f, 0.f};
;         f32x4 ca = pa[0], cw = pa[16], cb = pa[32], ck = pa[48], cr = pa[64];
; #pragma unroll
;         for (int q = 0; q < 16; ++q) {
;             const f32x4 a4 = ca, w4 = cw, b4 = cb, k4 = ck, r4 = cr;
;             if (q < 15) { ca = pa[1 + q]; cw = pa[17 + q]; cb = pa[33 + q]; ck = pa[49 + q]; cr = pa[65 + q]; }
;             __builtin_amdgcn_sched_barrier(0);
;             { const f2 a2 = {a4[0], a4[1]}, w2 = {w4[0], w4[1]}, b2 = {b4[0], b4[1]}, k2 = {k4[0], k4[1]}, r2 = {r4[0], r4[1]};
;               f2 tv = sav2 * b2; tv = pfma(v2, k2, tv); Sv[2 * q] = pfma(Sv[2 * q], w2, tv); yv = pfma(Sv[2 * q], r2, yv); nv = pfma(Sv[2 * q], a2, nv);
;               if (ID) { const f2 ti = sai2 * b2; Si[2 * q] = pfma(Si[2 * q], w2, ti); yi = pfma(Si[2 * q], r2, yi); ni = pfma(Si[2 * q], a2, ni); } }
;             { const f2 a2 = {a4[2], a4[3]}, w2 = {w4[2], w4[3]}, b2 = {b4[2], b4[3]}, k2 = {k4[2], k4[3]}, r2 = {r4[2], r4[3]};
;               f2 tv = sav2 * b2; tv = pfma(v2, k2, tv); Sv[2 * q + 1] = pfma(Sv[2 * q + 1], w2, tv); yv1 = pfma(Sv[2 * q + 1], r2, yv1); nv1 = pfma(Sv[2 * q + 1], a2, nv1);
;               if (ID) { const f2 ti = sai2 * b2; Si[2 * q + 1] = pfma(Si[2 * q + 1], w2, ti); yi1 = pfma(Si[2 * q + 1], r2, yi1); ni1 = pfma(Si[2 * q + 1], a2, ni1); } }
;         }
;         sav = (nv[0] + nv[1]) + (nv1[0] + nv1[1]); sai = (ni[0] + ni[1]) + (ni1[0] + ni1[1]);
;         const unsigned cbo = base + (unsigned)s * 512u;
	v_mul_f32_e32 v240, v233, v249
	v_mul_f32_e32 v241, v234, v250
	v_add_f32_e32 v68, v68, v69
	v_add_f32_e32 v70, v70, v71
	v_add_f32_e32 v64, v64, v65
	v_add_f32_e32 v66, v66, v67
	v_mov_b32_e32 v245, v235
	v_permlane32_swap_b32_e32 v68, v70
	v_permlane32_swap_b32_e32 v64, v66
	v_add_f32_e32 v244, v68, v70
	v_add_f32_e32 v64, v64, v66
	v_bfe_u32 v66, v64, 16, 1
	v_add3_u32 v66, v64, v66, s69
	v_permlane32_swap_b32_e32 v244, v245
	global_store_short_d16_hi v72, v66, s[22:23] offset:-4096
	v_add_u32_e32 v72, 0x400, v72
	v_lshl_add_u64 v[74:75], v[74:75], 0, s[54:55]
	ds_read_b128 v[148:151], v76 offset:1024
	ds_read_b128 v[152:155], v76 offset:1056
	ds_read_b128 v[156:159], v76 offset:1088
	ds_read_b128 v[160:163], v76 offset:1120
	ds_read_b128 v[164:167], v76 offset:1280
	ds_read_b128 v[168:171], v76 offset:1312
	ds_read_b128 v[172:175], v76 offset:1344
	ds_read_b128 v[176:179], v76 offset:1376
	global_load_short_d16_hi v230, v72, s[4:5] offset:0
	global_load_short_d16_hi v231, v72, s[0:1] offset:0
	global_load_short_d16_hi v232, v72, s[12:13] offset:1024
	global_load_short_d16_hi v233, v[74:75], off offset:0
	global_load_short_d16_hi v234, v[74:75], off offset:64
	global_load_short_d16_hi v235, v72, s[2:3] offset:0
	v_mfma_f32_32x32x2_f32 v[0:15], v240, v244, v[0:15]
	v_mfma_f32_32x32x2_f32 v[32:47], v240, v245, v[32:47]
	ds_read_b128 v[192:195], v76 offset:1152
	ds_read_b128 v[196:199], v76 offset:1184
	ds_read_b128 v[200:203], v76 offset:1216
	ds_read_b128 v[204:207], v76 offset:1248
	ds_read_b128 v[208:211], v76 offset:1408
	ds_read_b128 v[212:215], v76 offset:1440
	ds_read_b128 v[216:219], v76 offset:1472
	ds_read_b128 v[220:223], v76 offset:1504
	v_mfma_f32_32x32x2_f32 v[16:31], v241, v244, v[16:31]
	v_mfma_f32_32x32x2_f32 v[48:63], v241, v245, v[48:63]
	s_waitcnt vmcnt(19)
	v_mul_f32_e32 v78, 0xbfb8aa3b, v82
	v_exp_f32_e32 v78, v78
	s_nop 0
	v_mul_f32_e32 v246, v246, v78
	v_mul_f32_e32 v79, v83, v246
	v_mul_f32_e32 v80, v84, v246
	v_rcp_f32_e32 v248, v246
	s_nop 0
	ds_write2st64_b32 v77, v248, v79 offset0:0 offset1:1
	ds_write_b32 v77, v80 offset:512
	s_waitcnt lgkmcnt(10)
	v_pk_mul_f32 v[64:65], v[0:1], v[148:149]
	v_pk_mul_f32 v[68:69], v[0:1], v[164:165]
	v_pk_fma_f32 v[64:65], v[2:3], v[150:151], v[64:65]
	v_pk_fma_f32 v[68:69], v[2:3], v[166:167], v[68:69]
	v_pk_fma_f32 v[64:65], v[4:5], v[152:153], v[64:65]
	v_pk_fma_f32 v[68:69], v[4:5], v[168:169], v[68:69]
	v_pk_fma_f32 v[64:65], v[6:7], v[154:155], v[64:65]
	v_pk_fma_f32 v[68:69], v[6:7], v[170:171], v[68:69]
	v_pk_fma_f32 v[64:65], v[8:9], v[156:157], v[64:65]
	v_pk_fma_f32 v[68:69], v[8:9], v[172:173], v[68:69]
	v_pk_fma_f32 v[64:65], v[10:11], v[158:159], v[64:65]
	v_pk_fma_f32 v[68:69], v[10:11], v[174:175], v[68:69]
	v_pk_fma_f32 v[64:65], v[12:13], v[160:161], v[64:65]
	v_pk_fma_f32 v[68:69], v[12:13], v[176:177], v[68:69]
	v_pk_fma_f32 v[64:65], v[14:15], v[162:163], v[64:65]
	v_pk_fma_f32 v[68:69], v[14:15], v[178:179], v[68:69]
	v_pk_mul_f32 v[66:67], v[32:33], v[148:149]
	v_pk_mul_f32 v[70:71], v[32:33], v[164:165]
	v_pk_fma_f32 v[66:67], v[34:35], v[150:151], v[66:67]
	v_pk_fma_f32 v[70:71], v[34:35], v[166:167], v[70:71]
	v_pk_fma_f32 v[66:67], v[36:37], v[152:153], v[66:67]
	v_pk_fma_f32 v[70:71], v[36:37], v[168:169], v[70:71]
	v_pk_fma_f32 v[66:67], v[38:39], v[154:155], v[66:67]
	v_pk_fma_f32 v[70:71], v[38:39], v[170:171], v[70:71]
	v_pk_fma_f32 v[66:67], v[40:41], v[156:157], v[66:67]
	v_pk_fma_f32 v[70:71], v[40:41], v[172:173], v[70:71]
	v_pk_fma_f32 v[66:67], v[42:43], v[158:159], v[66:67]
	v_pk_fma_f32 v[70:71], v[42:43], v[174:175], v[70:71]
	v_pk_fma_f32 v[66:67], v[44:45], v[160:161], v[66:67]
	v_pk_fma_f32 v[70:71], v[44:45], v[176:177], v[70:71]
	v_pk_fma_f32 v[66:67], v[46:47], v[162:163], v[66:67]
	v_pk_fma_f32 v[70:71], v[46:47], v[178:179], v[70:71]
	s_waitcnt lgkmcnt(2)
	v_pk_fma_f32 v[64:65], v[16:17], v[192:193], v[64:65]
	v_pk_fma_f32 v[68:69], v[16:17], v[208:209], v[68:69]
	v_pk_fma_f32 v[64:65], v[18:19], v[194:195], v[64:65]
	v_pk_fma_f32 v[68:69], v[18:19], v[210:211], v[68:69]
	v_pk_fma_f32 v[64:65], v[20:21], v[196:197], v[64:65]
	v_pk_fma_f32 v[68:69], v[20:21], v[212:213], v[68:69]
	v_pk_fma_f32 v[64:65], v[22:23], v[198:199], v[64:65]
	v_pk_fma_f32 v[68:69], v[22:23], v[214:215], v[68:69]
	v_pk_fma_f32 v[64:65], v[24:25], v[200:201], v[64:65]
	v_pk_fma_f32 v[68:69], v[24:25], v[216:217], v[68:69]
	v_pk_fma_f32 v[64:65], v[26:27], v[202:203], v[64:65]
	v_pk_fma_f32 v[68:69], v[26:27], v[218:219], v[68:69]
	v_pk_fma_f32 v[64:65], v[28:29], v[204:205], v[64:65]
	v_pk_fma_f32 v[68:69], v[28:29], v[220:221], v[68:69]
	v_pk_fma_f32 v[64:65], v[30:31], v[206:207], v[64:65]
	v_pk_fma_f32 v[68:69], v[30:31], v[222:223], v[68:69]
	v_pk_fma_f32 v[66:67], v[48:49], v[192:193], v[66:67]
	v_pk_fma_f32 v[70:71], v[48:49], v[208:209], v[70:71]
	v_pk_fma_f32 v[66:67], v[50:51], v[194:195], v[66:67]
	v_pk_fma_f32 v[70:71], v[50:51], v[210:211], v[70:71]
	v_pk_fma_f32 v[66:67], v[52:53], v[196:197], v[66:67]
	v_pk_fma_f32 v[70:71], v[52:53], v[212:213], v[70:71]
	v_pk_fma_f32 v[66:67], v[54:55], v[198:199], v[66:67]
	v_pk_fma_f32 v[70:71], v[54:55], v[214:215], v[70:71]
	v_pk_fma_f32 v[66:67], v[56:57], v[200:201], v[66:67]
	v_pk_fma_f32 v[70:71], v[56:57], v[216:217], v[70:71]
	v_pk_fma_f32 v[66:67], v[58:59], v[202:203], v[66:67]
	v_pk_fma_f32 v[70:71], v[58:59], v[218:219], v[70:71]
	v_pk_fma_f32 v[66:67], v[60:61], v[204:205], v[66:67]
	v_pk_fma_f32 v[70:71], v[60:61], v[220:221], v[70:71]
	v_pk_fma_f32 v[66:67], v[62:63], v[206:207], v[66:67]
	v_pk_fma_f32 v[70:71], v[62:63], v[222:223], v[70:71]
	ds_read_b32 v249, v251 offset:0
	ds_read_b32 v250, v251 offset:128
	s_waitcnt lgkmcnt(0)
; template <bool ID> __device__ __forceinline__ void rwkv_scan(const bf16_t* __restrict__ R, const bf16_t* __restrict__ EW, const bf16_t* __restrict__ K, const bf16_t* __restrict__ V, ...
;     ...
;     for (int s = 0; s < nsteps; ++s) {
;         L[lane] = bf2f(q2[4]); L[64 + lane] = __expf(-bf2f(q1[1])); L[128 + lane] = bf2f(q1[5]); L[192 + lane] = bf2f(q1[2]); L[256 + lane] = bf2f(q1[0]);
;         const float v = bf2f(q1[3]);
; #pragma unroll
;         for (int j = 0; j < 6; ++j) q1[j] = q2[j];
;         { const unsigned o = base + (unsigned)(s + 2 < nsteps ? s + 2 : nsteps - 1) * 512u; q2[0] = R[o]; q2[1] = EW[o]; q2[2] = K[o]; q2[3] = V[o]; q2[4] = A[o]; q2[5] = B[o]; }
;         const f2 sav2 = {sav, sav}, sai2 = {sai, sai}, v2 = {v, v};
;         f2 yv = {0.f, 0.f}, yi = {0.f, 0.f}, yv1 = {0.f, 0.f}, yi1 = {0.f, 0.f}, nv = {0.f, 0.f}, ni = {0.f, 0.f}, nv1 = {0.f, 0.f}, ni1 = {0.f, 0.f};
;         f32x4 ca = pa[0], cw = pa[16], cb = pa[32], ck = pa[48], cr = pa[64];
; #pragma unroll
;         for (int q = 0; q < 16; ++q) {
;             const f32x4 a4 = ca, w4 = cw, b4 = cb, k4 = ck, r4 = cr;
;             if (q < 15) { ca = pa[1 + q]; cw = pa[17 + q]; cb = pa[33 + q]; ck = pa[49 + q]; cr = pa[65 + q]; }
;             __builtin_amdgcn_sched_barrier(0);
;             { const f2 a2 = {a4[0], a4[1]}, w2 = {w4[0], w4[1]}, b2 = {b4[0], b4[1]}, k2 = {k4[0], k4[1]}, r2 = {r4[0], r4[1]};
;               f2 tv = sav2 * b2; tv = pfma(v2, k2, tv); Sv[2 * q] = pfma(Sv[2 * q], w2, tv); yv = pfma(Sv[2 * q], r2, yv); nv = pfma(Sv[2 * q], a2, nv);
;               if (ID) { const f2 ti = sai2 * b2; Si[2 * q] = pfma(Si[2 * q], w2, ti); yi = pfma(Si[2 * q], r2, yi); ni = pfma(Si[2 * q], a2, ni); } }
;             { const f2 a2 = {a4[2], a4[3]}, w2 = {w4[2], w4[3]}, b2 = {b4[2], b4[3]}, k2 = {k4[2], k4[3]}, r2 = {r4[2], r4[3]};
;               f2 tv = sav2 * b2; tv = pfma(v2, k2, tv); Sv[2 * q + 1] = pfma(Sv[2 * q + 1], w2, tv); yv1 = pfma(Sv[2 * q + 1], r2, yv1); nv1 = pfma(Sv[2 * q + 1], a2, nv1);
;               if (ID) { const f2 ti = sai2 * b2; Si[2 * q + 1] = pfma(Si[2 * q + 1], w2, ti); yi1 = pfma(Si[2 * q + 1], r2, yi1); ni1 = pfma(Si[2 * q + 1], a2, ni1); } }
;         }
;         sav = (nv[0] + nv[1]) + (nv1[0] + nv1[1]); sai = (ni[0] + ni[1]) + (ni1[0] + ni1[1]);
;         const unsigned cbo = base + (unsigned)s * 512u;
	v_mul_f32_e32 v240, v85, v249
	v_mul_f32_e32 v241, v86, v250
	v_add_f32_e32 v68, v68, v69
	v_add_f32_e32 v70, v70, v71
	v_add_f32_e32 v64, v64, v65
	v_add_f32_e32 v66, v66, v67
	v_mov_b32_e32 v245, v87
	v_permlane32_swap_b32_e32 v68, v70
	v_permlane32_swap_b32_e32 v64, v66
	v_add_f32_e32 v244, v68, v70
	v_add_f32_e32 v64, v64, v66
	v_bfe_u32 v66, v64, 16, 1
	v_add3_u32 v66, v64, v66, s69
	v_permlane32_swap_b32_e32 v244, v245
	global_store_short_d16_hi v72, v66, s[22:23] offset:-4096
	v_add_u32_e32 v72, 0x400, v72
	v_lshl_add_u64 v[74:75], v[74:75], 0, s[54:55]
	ds_read_b128 v[192:195], v76 offset:256
	ds_read_b128 v[196:199], v76 offset:288
	ds_read_b128 v[200:203], v76 offset:320
	ds_read_b128 v[204:207], v76 offset:352
	ds_read_b128 v[208:211], v76 offset:512
	ds_read_b128 v[212:215], v76 offset:544
	ds_read_b128 v[216:219], v76 offset:576
	ds_read_b128 v[220:223], v76 offset:608
	global_load_short_d16_hi v82, v72, s[4:5] offset:0
	global_load_short_d16_hi v83, v72, s[0:1] offset:0
	global_load_short_d16_hi v84, v72, s[12:13] offset:1024
	global_load_short_d16_hi v85, v[74:75], off offset:0
	global_load_short_d16_hi v86, v[74:75], off offset:64
	global_load_short_d16_hi v87, v72, s[2:3] offset:0
	v_mfma_f32_32x32x2_f32 v[0:15], v240, v244, v[0:15]
	v_mfma_f32_32x32x2_f32 v[32:47], v240, v245, v[32:47]
	ds_read_b128 v[148:151], v76 offset:384
	ds_read_b128 v[152:155], v76 offset:416
	ds_read_b128 v[156:159], v76 offset:448
	ds_read_b128 v[160:163], v76 offset:480
	ds_read_b128 v[164:167], v76 offset:640
	ds_read_b128 v[168:171], v76 offset:672
	ds_read_b128 v[172:175], v76 offset:704
	ds_read_b128 v[176:179], v76 offset:736
	v_mfma_f32_32x32x2_f32 v[16:31], v241, v244, v[16:31]
	v_mfma_f32_32x32x2_f32 v[48:63], v241, v245, v[48:63]
	s_waitcnt vmcnt(20)
	v_mul_f32_e32 v78, 0xbfb8aa3b, v88
	v_exp_f32_e32 v78, v78
	s_nop 0
	v_mul_f32_e32 v246, v246, v78
	v_mul_f32_e32 v79, v89, v246
	v_mul_f32_e32 v80, v90, v246
	v_rcp_f32_e32 v248, v246
	s_nop 0
	ds_write2st64_b32 v77, v248, v79 offset0:3 offset1:4
	ds_write_b32 v77, v80 offset:1280
	s_waitcnt lgkmcnt(10)
	v_pk_mul_f32 v[64:65], v[0:1], v[192:193]
	v_pk_mul_f32 v[68:69], v[0:1], v[208:209]
	v_pk_fma_f32 v[64:65], v[2:3], v[194:195], v[64:65]
	v_pk_fma_f32 v[68:69], v[2:3], v[210:211], v[68:69]
	v_pk_fma_f32 v[64:65], v[4:5], v[196:197], v[64:65]
	v_pk_fma_f32 v[68:69], v[4:5], v[212:213], v[68:69]
	v_pk_fma_f32 v[64:65], v[6:7], v[198:199], v[64:65]
	v_pk_fma_f32 v[68:69], v[6:7], v[214:215], v[68:69]
	v_pk_fma_f32 v[64:65], v[8:9], v[200:201], v[64:65]
	v_pk_fma_f32 v[68:69], v[8:9], v[216:217], v[68:69]
	v_pk_fma_f32 v[64:65], v[10:11], v[202:203], v[64:65]
	v_pk_fma_f32 v[68:69], v[10:11], v[218:219], v[68:69]
	v_pk_fma_f32 v[64:65], v[12:13], v[204:205], v[64:65]
	v_pk_fma_f32 v[68:69], v[12:13], v[220:221], v[68:69]
	v_pk_fma_f32 v[64:65], v[14:15], v[206:207], v[64:65]
	v_pk_fma_f32 v[68:69], v[14:15], v[222:223], v[68:69]
	v_pk_mul_f32 v[66:67], v[32:33], v[192:193]
	v_pk_mul_f32 v[70:71], v[32:33], v[208:209]
	v_pk_fma_f32 v[66:67], v[34:35], v[194:195], v[66:67]
	v_pk_fma_f32 v[70:71], v[34:35], v[210:211], v[70:71]
	v_pk_fma_f32 v[66:67], v[36:37], v[196:197], v[66:67]
	v_pk_fma_f32 v[70:71], v[36:37], v[212:213], v[70:71]
	v_pk_fma_f32 v[66:67], v[38:39], v[198:199], v[66:67]
	v_pk_fma_f32 v[70:71], v[38:39], v[214:215], v[70:71]
	v_pk_fma_f32 v[66:67], v[40:41], v[200:201], v[66:67]
	v_pk_fma_f32 v[70:71], v[40:41], v[216:217], v[70:71]
	v_pk_fma_f32 v[66:67], v[42:43], v[202:203], v[66:67]
	v_pk_fma_f32 v[70:71], v[42:43], v[218:219], v[70:71]
	v_pk_fma_f32 v[66:67], v[44:45], v[204:205], v[66:67]
	v_pk_fma_f32 v[70:71], v[44:45], v[220:221], v[70:71]
	v_pk_fma_f32 v[66:67], v[46:47], v[206:207], v[66:67]
	v_pk_fma_f32 v[70:71], v[46:47], v[222:223], v[70:71]
	s_waitcnt lgkmcnt(2)
	v_pk_fma_f32 v[64:65], v[16:17], v[148:149], v[64:65]
	v_pk_fma_f32 v[68:69], v[16:17], v[164:165], v[68:69]
	v_pk_fma_f32 v[64:65], v[18:19], v[150:151], v[64:65]
	v_pk_fma_f32 v[68:69], v[18:19], v[166:167], v[68:69]
	v_pk_fma_f32 v[64:65], v[20:21], v[152:153], v[64:65]
	v_pk_fma_f32 v[68:69], v[20:21], v[168:169], v[68:69]
	v_pk_fma_f32 v[64:65], v[22:23], v[154:155], v[64:65]
	v_pk_fma_f32 v[68:69], v[22:23], v[170:171], v[68:69]
	v_pk_fma_f32 v[64:65], v[24:25], v[156:157], v[64:65]
	v_pk_fma_f32 v[68:69], v[24:25], v[172:173], v[68:69]
	v_pk_fma_f32 v[64:65], v[26:27], v[158:159], v[64:65]
	v_pk_fma_f32 v[68:69], v[26:27], v[174:175], v[68:69]
	v_pk_fma_f32 v[64:65], v[28:29], v[160:161], v[64:65]
	v_pk_fma_f32 v[68:69], v[28:29], v[176:177], v[68:69]
	v_pk_fma_f32 v[64:65], v[30:31], v[162:163], v[64:65]
	v_pk_fma_f32 v[68:69], v[30:31], v[178:179], v[68:69]
	v_pk_fma_f32 v[66:67], v[48:49], v[148:149], v[66:67]
	v_pk_fma_f32 v[70:71], v[48:49], v[164:165], v[70:71]
	v_pk_fma_f32 v[66:67], v[50:51], v[150:151], v[66:67]
	v_pk_fma_f32 v[70:71], v[50:51], v[166:167], v[70:71]
	v_pk_fma_f32 v[66:67], v[52:53], v[152:153], v[66:67]
	v_pk_fma_f32 v[70:71], v[52:53], v[168:169], v[70:71]
	v_pk_fma_f32 v[66:67], v[54:55], v[154:155], v[66:67]
	v_pk_fma_f32 v[70:71], v[54:55], v[170:171], v[70:71]
	v_pk_fma_f32 v[66:67], v[56:57], v[156:157], v[66:67]
	v_pk_fma_f32 v[70:71], v[56:57], v[172:173], v[70:71]
	v_pk_fma_f32 v[66:67], v[58:59], v[158:159], v[66:67]
	v_pk_fma_f32 v[70:71], v[58:59], v[174:175], v[70:71]
	v_pk_fma_f32 v[66:67], v[60:61], v[160:161], v[66:67]
	v_pk_fma_f32 v[70:71], v[60:61], v[176:177], v[70:71]
	v_pk_fma_f32 v[66:67], v[62:63], v[162:163], v[66:67]
	v_pk_fma_f32 v[70:71], v[62:63], v[178:179], v[70:71]
	ds_read_b32 v249, v251 offset:768
	ds_read_b32 v250, v251 offset:896
	s_waitcnt lgkmcnt(0)
	v_mul_f32_e32 v240, v91, v249
	v_mul_f32_e32 v241, v92, v250
	v_add_f32_e32 v68, v68, v69
	v_add_f32_e32 v70, v70, v71
	v_add_f32_e32 v64, v64, v65
	v_add_f32_e32 v66, v66, v67
	v_mov_b32_e32 v245, v93
	v_permlane32_swap_b32_e32 v68, v70
	v_permlane32_swap_b32_e32 v64, v66
	v_add_f32_e32 v244, v68, v70
	v_add_f32_e32 v64, v64, v66
	v_bfe_u32 v66, v64, 16, 1
	v_add3_u32 v66, v64, v66, s69
	v_permlane32_swap_b32_e32 v244, v245
	global_store_short_d16_hi v72, v66, s[22:23] offset:-4096
	v_add_u32_e32 v72, 0x400, v72
	v_lshl_add_u64 v[74:75], v[74:75], 0, s[54:55]
	s_and_b32 s14, s41, 15
	s_cmp_eq_u32 s14, 15
	s_cbranch_scc1 .Lscan_v_s3x
; template <bool ID> __device__ __forceinline__ void rwkv_scan(const bf16_t* __restrict__ R, const bf16_t* __restrict__ EW, const bf16_t* __restrict__ K, const bf16_t* __restrict__ V, ...
;     ...
;     for (int s = 0; s < nsteps; ++s) {
;         L[lane] = bf2f(q2[4]); L[64 + lane] = __expf(-bf2f(q1[1])); L[128 + lane] = bf2f(q1[5]); L[192 + lane] = bf2f(q1[2]); L[256 + lane] = bf2f(q1[0]);
;         const float v = bf2f(q1[3]);
; #pragma unroll
;         for (int j = 0; j < 6; ++j) q1[j] = q2[j];
;         { const unsigned o = base + (unsigned)(s + 2 < nsteps ? s + 2 : nsteps - 1) * 512u; q2[0] = R[o]; q2[1] = EW[o]; q2[2] = K[o]; q2[3] = V[o]; q2[4] = A[o]; q2[5] = B[o]; }
;         const f2 sav2 = {sav, sav}, sai2 = {sai, sai}, v2 = {v, v};
;         f2 yv = {0.f, 0.f}, yi = {0.f, 0.f}, yv1 = {0.f, 0.f}, yi1 = {0.f, 0.f}, nv = {0.f, 0.f}, ni = {0.f, 0.f}, nv1 = {0.f, 0.f}, ni1 = {0.f, 0.f};
;         f32x4 ca = pa[0], cw = pa[16], cb = pa[32], ck = pa[48], cr = pa[64];
; #pragma unroll
;         for (int q = 0; q < 16; ++q) {
;             const f32x4 a4 = ca, w4 = cw, b4 = cb, k4 = ck, r4 = cr;
;             if (q < 15) { ca = pa[1 + q]; cw = pa[17 + q]; cb = pa[33 + q]; ck = pa[49 + q]; cr = pa[65 + q]; }
;             __builtin_amdgcn_sched_barrier(0);
;             { const f2 a2 = {a4[0], a4[1]}, w2 = {w4[0], w4[1]}, b2 = {b4[0], b4[1]}, k2 = {k4[0], k4[1]}, r2 = {r4[0], r4[1]};
;               f2 tv = sav2 * b2; tv = pfma(v2, k2, tv); Sv[2 * q] = pfma(Sv[2 * q], w2, tv); yv = pfma(Sv[2 * q], r2, yv); nv = pfma(Sv[2 * q], a2, nv);
;               if (ID) { const f2 ti = sai2 * b2; Si[2 * q] = pfma(Si[2 * q], w2, ti); yi = pfma(Si[2 * q], r2, yi); ni = pfma(Si[2 * q], a2, ni); } }
;             { const f2 a2 = {a4[2], a4[3]}, w2 = {w4[2], w4[3]}, b2 = {b4[2], b4[3]}, k2 = {k4[2], k4[3]}, r2 = {r4[2], r4[3]};
;               f2 tv = sav2 * b2; tv = pfma(v2, k2, tv); Sv[2 * q + 1] = pfma(Sv[2 * q + 1], w2, tv); yv1 = pfma(Sv[2 * q + 1], r2, yv1); nv1 = pfma(Sv[2 * q + 1], a2, nv1);
;               if (ID) { const f2 ti = sai2 * b2; Si[2 * q + 1] = pfma(Si[2 * q + 1], w2, ti); yi1 = pfma(Si[2 * q + 1], r2, yi1); ni1 = pfma(Si[2 * q + 1], a2, ni1); } }
;         }
;         sav = (nv[0] + nv[1]) + (nv1[0] + nv1[1]); sai = (ni[0] + ni[1]) + (ni1[0] + ni1[1]);
;         const unsigned cbo = base + (unsigned)s * 512u;
	ds_read_b128 v[148:151], v76 offset:1024
	ds_read_b128 v[152:155], v76 offset:1056
	ds_read_b128 v[156:159], v76 offset:1088
	ds_read_b128 v[160:163], v76 offset:1120
	ds_read_b128 v[164:167], v76 offset:1280
	ds_read_b128 v[168:171], v76 offset:1312
	ds_read_b128 v[172:175], v76 offset:1344
	ds_read_b128 v[176:179], v76 offset:1376
	global_load_short_d16_hi v88, v72, s[4:5] offset:0
	global_load_short_d16_hi v89, v72, s[0:1] offset:0
	global_load_short_d16_hi v90, v72, s[12:13] offset:1024
	global_load_short_d16_hi v91, v[74:75], off offset:0
	global_load_short_d16_hi v92, v[74:75], off offset:64
	global_load_short_d16_hi v93, v72, s[2:3] offset:0
	v_mfma_f32_32x32x2_f32 v[0:15], v240, v244, v[0:15]
	v_mfma_f32_32x32x2_f32 v[32:47], v240, v245, v[32:47]
	ds_read_b128 v[192:195], v76 offset:1152
	ds_read_b128 v[196:199], v76 offset:1184
	ds_read_b128 v[200:203], v76 offset:1216
	ds_read_b128 v[204:207], v76 offset:1248
	ds_read_b128 v[208:211], v76 offset:1408
	ds_read_b128 v[212:215], v76 offset:1440
	ds_read_b128 v[216:219], v76 offset:1472
	ds_read_b128 v[220:223], v76 offset:1504
	v_mfma_f32_32x32x2_f32 v[16:31], v241, v244, v[16:31]
	v_mfma_f32_32x32x2_f32 v[48:63], v241, v245, v[48:63]
	s_waitcnt vmcnt(21)
	v_mul_f32_e32 v78, 0xbfb8aa3b, v224
	v_exp_f32_e32 v78, v78
	s_nop 0
	v_mul_f32_e32 v246, v246, v78
	v_mul_f32_e32 v79, v225, v246
	v_mul_f32_e32 v80, v226, v246
	v_rcp_f32_e32 v248, v246
	s_nop 0
	ds_write2st64_b32 v77, v248, v79 offset0:0 offset1:1
	ds_write_b32 v77, v80 offset:512
	s_waitcnt lgkmcnt(10)
	v_pk_mul_f32 v[64:65], v[0:1], v[148:149]
	v_pk_mul_f32 v[68:69], v[0:1], v[164:165]
	v_pk_fma_f32 v[64:65], v[2:3], v[150:151], v[64:65]
	v_pk_fma_f32 v[68:69], v[2:3], v[166:167], v[68:69]
	v_pk_fma_f32 v[64:65], v[4:5], v[152:153], v[64:65]
	v_pk_fma_f32 v[68:69], v[4:5], v[168:169], v[68:69]
	v_pk_fma_f32 v[64:65], v[6:7], v[154:155], v[64:65]
	v_pk_fma_f32 v[68:69], v[6:7], v[170:171], v[68:69]
	v_pk_fma_f32 v[64:65], v[8:9], v[156:157], v[64:65]
	v_pk_fma_f32 v[68:69], v[8:9], v[172:173], v[68:69]
	v_pk_fma_f32 v[64:65], v[10:11], v[158:159], v[64:65]
	v_pk_fma_f32 v[68:69], v[10:11], v[174:175], v[68:69]
	v_pk_fma_f32 v[64:65], v[12:13], v[160:161], v[64:65]
	v_pk_fma_f32 v[68:69], v[12:13], v[176:177], v[68:69]
	v_pk_fma_f32 v[64:65], v[14:15], v[162:163], v[64:65]
	v_pk_fma_f32 v[68:69], v[14:15], v[178:179], v[68:69]
	v_pk_mul_f32 v[66:67], v[32:33], v[148:149]
	v_pk_mul_f32 v[70:71], v[32:33], v[164:165]
	v_pk_fma_f32 v[66:67], v[34:35], v[150:151], v[66:67]
	v_pk_fma_f32 v[70:71], v[34:35], v[166:167], v[70:71]
	v_pk_fma_f32 v[66:67], v[36:37], v[152:153], v[66:67]
	v_pk_fma_f32 v[70:71], v[36:37], v[168:169], v[70:71]
	v_pk_fma_f32 v[66:67], v[38:39], v[154:155], v[66:67]
	v_pk_fma_f32 v[70:71], v[38:39], v[170:171], v[70:71]
	v_pk_fma_f32 v[66:67], v[40:41], v[156:157], v[66:67]
	v_pk_fma_f32 v[70:71], v[40:41], v[172:173], v[70:71]
	v_pk_fma_f32 v[66:67], v[42:43], v[158:159], v[66:67]
	v_pk_fma_f32 v[70:71], v[42:43], v[174:175], v[70:71]
	v_pk_fma_f32 v[66:67], v[44:45], v[160:161], v[66:67]
	v_pk_fma_f32 v[70:71], v[44:45], v[176:177], v[70:71]
	v_pk_fma_f32 v[66:67], v[46:47], v[162:163], v[66:67]
	v_pk_fma_f32 v[70:71], v[46:47], v[178:179], v[70:71]
	s_waitcnt lgkmcnt(2)
	v_pk_fma_f32 v[64:65], v[16:17], v[192:193], v[64:65]
	v_pk_fma_f32 v[68:69], v[16:17], v[208:209], v[68:69]
	v_pk_fma_f32 v[64:65], v[18:19], v[194:195], v[64:65]
	v_pk_fma_f32 v[68:69], v[18:19], v[210:211], v[68:69]
	v_pk_fma_f32 v[64:65], v[20:21], v[196:197], v[64:65]
	v_pk_fma_f32 v[68:69], v[20:21], v[212:213], v[68:69]
	v_pk_fma_f32 v[64:65], v[22:23], v[198:199], v[64:65]
	v_pk_fma_f32 v[68:69], v[22:23], v[214:215], v[68:69]
	v_pk_fma_f32 v[64:65], v[24:25], v[200:201], v[64:65]
	v_pk_fma_f32 v[68:69], v[24:25], v[216:217], v[68:69]
	v_pk_fma_f32 v[64:65], v[26:27], v[202:203], v[64:65]
	v_pk_fma_f32 v[68:69], v[26:27], v[218:219], v[68:69]
	v_pk_fma_f32 v[64:65], v[28:29], v[204:205], v[64:65]
	v_pk_fma_f32 v[68:69], v[28:29], v[220:221], v[68:69]
	v_pk_fma_f32 v[64:65], v[30:31], v[206:207], v[64:65]
	v_pk_fma_f32 v[68:69], v[30:31], v[222:223], v[68:69]
	v_pk_fma_f32 v[66:67], v[48:49], v[192:193], v[66:67]
	v_pk_fma_f32 v[70:71], v[48:49], v[208:209], v[70:71]
	v_pk_fma_f32 v[66:67], v[50:51], v[194:195], v[66:67]
	v_pk_fma_f32 v[70:71], v[50:51], v[210:211], v[70:71]
	v_pk_fma_f32 v[66:67], v[52:53], v[196:197], v[66:67]
	v_pk_fma_f32 v[70:71], v[52:53], v[212:213], v[70:71]
	v_pk_fma_f32 v[66:67], v[54:55], v[198:199], v[66:67]
	v_pk_fma_f32 v[70:71], v[54:55], v[214:215], v[70:71]
	v_pk_fma_f32 v[66:67], v[56:57], v[200:201], v[66:67]
	v_pk_fma_f32 v[70:71], v[56:57], v[216:217], v[70:71]
	v_pk_fma_f32 v[66:67], v[58:59], v[202:203], v[66:67]
	v_pk_fma_f32 v[70:71], v[58:59], v[218:219], v[70:71]
	v_pk_fma_f32 v[66:67], v[60:61], v[204:205], v[66:67]
	v_pk_fma_f32 v[70:71], v[60:61], v[220:221], v[70:71]
	v_pk_fma_f32 v[66:67], v[62:63], v[206:207], v[66:67]
	v_pk_fma_f32 v[70:71], v[62:63], v[222:223], v[70:71]
	ds_read_b32 v249, v251 offset:0
	ds_read_b32 v250, v251 offset:128
	s_waitcnt lgkmcnt(0)
	v_mul_f32_e32 v240, v227, v249
	v_mul_f32_e32 v241, v228, v250
	v_add_f32_e32 v68, v68, v69
	v_add_f32_e32 v70, v70, v71
	v_add_f32_e32 v64, v64, v65
	v_add_f32_e32 v66, v66, v67
	v_mov_b32_e32 v245, v229
	v_permlane32_swap_b32_e32 v68, v70
	v_permlane32_swap_b32_e32 v64, v66
	v_add_f32_e32 v244, v68, v70
	v_add_f32_e32 v64, v64, v66
	v_bfe_u32 v66, v64, 16, 1
	v_add3_u32 v66, v64, v66, s69
	v_permlane32_swap_b32_e32 v244, v245
	global_store_short_d16_hi v72, v66, s[22:23] offset:-4096
	v_add_u32_e32 v72, 0x400, v72
	v_lshl_add_u64 v[74:75], v[74:75], 0, s[54:55]
	s_branch .Lscan_v_s3e

; __device__ __forceinline__ int tidx() { int t = threadIdx.x; asm volatile("" : "+v"(t)); return t; }
; __device__ __forceinline__ float bf2f(unsigned short b) { return __uint_as_float((unsigned)b << 16); }
; __device__ __forceinline__ f2 pfma(f2 a, f2 b, f2 c) { return __builtin_elementwise_fma(a, b, c); }
; template <bool ID> __device__ __forceinline__ void rwkv_scan(const bf16_t* __restrict__ R, const bf16_t* __restrict__ EW, const bf16_t* __restrict__ K, const bf16_t* __restrict__ V, ...
;     ...
;     { unsigned o = base; q1[0] = R[o]; q1[1] = EW[o]; q1[2] = K[o]; q1[3] = V[o]; q1[4] = A[o]; q1[5] = B[o];
;       o = base + 512u; q2[0] = R[o]; q2[1] = EW[o]; q2[2] = K[o]; q2[3] = V[o]; q2[4] = A[o]; q2[5] = B[o]; }
;     const LAS f32x4* pa = (const LAS f32x4*)L;
;     float sav, sai;
;     { L[lane] = bf2f(q1[4]);
;       f2 av = {0.f, 0.f}, ai = {0.f, 0.f};
; #pragma unroll
;       for (int q = 0; q < 16; ++q) { const f32x4 a4 = pa[q]; const f2 a01 = {a4[0], a4[1]}, a23 = {a4[2], a4[3]};
;           av = pfma(Sv[2 * q], a01, av); av = pfma(Sv[2 * q + 1], a23, av); if (ID) { ai = pfma(Si[2 * q], a01, ai); ai = pfma(Si[2 * q + 1], a23, ai); } }
;       sav = av[0] + av[1]; sai = ai[0] + ai[1]; }
; __device__ void phase_rwkv_scan(const Ctx& p, int l, LAS unsigned char* lds) {
;     ...
;             f2 Sv[32], Si[32]; const int li = tidx() & 63;
; #pragma unroll
;             for (int i = 0; i < 32; ++i) { Sv[i] = (f2){0.f, 0.f}; Si[i] = (f2){(2 * i == li) ? 1.f : 0.f, (2 * i + 1 == li) ? 1.f : 0.f}; }
;             rwkv_scan<true>(R, EW, K, V, A, B, (unsigned)((b * 8192 + c * 128) * 512 + h * 64 + lane), 128, Sv, Si, YH, QH, L, lane);
.Lscan_i:
	v_lshrrev_b32_e32 v78, 5, v139
	v_and_b32_e32 v79, 31, v139
	s_mov_b32 s26, -1
	s_mov_b32 s27, 0
	s_lshl_b32 s14, s36, 13
	s_and_b32 s14, s14, 0xffff0000
	s_lshl_b32 s15, s36, 6
	s_and_b32 s15, s15, 0x1c0
	s_or_b32 s14, s14, s15
	v_add_lshl_u32 v72, s14, v139, 1
	v_add_lshl_u32 v81, s14, v79, 1
	v_mov_b32_e32 v74, s20
	v_mov_b32_e32 v75, s21
	v_add_co_u32_e32 v74, vcc, v74, v81
	s_nop 1
	v_addc_co_u32_e32 v75, vcc, 0, v75, vcc
	v_lshl_add_u32 v76, v78, 4, s10
	v_lshl_add_u32 v77, v139, 2, s10
	v_lshl_add_u32 v251, v79, 2, s10
	v_mov_b32_e32 v246, 1.0
	v_lshlrev_b32_e32 v81, 2, v78
	v_sub_u32_e32 v81, v79, v81
	global_load_short_d16_hi v244, v72, s[12:13]
	global_load_short_d16_hi v224, v72, s[4:5] offset:0
	global_load_short_d16_hi v225, v72, s[0:1] offset:0
	global_load_short_d16_hi v226, v72, s[12:13] offset:1024
	global_load_short_d16_hi v227, v[74:75], off offset:0
	global_load_short_d16_hi v228, v[74:75], off offset:64
	global_load_short_d16_hi v230, v72, s[4:5] offset:1024
	global_load_short_d16_hi v231, v72, s[0:1] offset:1024
	global_load_short_d16_hi v232, v72, s[12:13] offset:2048
	global_load_short_d16_hi v233, v[74:75], off offset:1024
	global_load_short_d16_hi v234, v[74:75], off offset:1088
	global_load_short_d16_hi v82, v72, s[4:5] offset:2048
	global_load_short_d16_hi v83, v72, s[0:1] offset:2048
	global_load_short_d16_hi v84, v72, s[12:13] offset:3072
	global_load_short_d16_hi v85, v[74:75], off offset:2048
	global_load_short_d16_hi v86, v[74:75], off offset:2112
	v_add_u32_e32 v72, 0xc00, v72
	v_lshl_add_u64 v[74:75], v[74:75], 0, s[54:55]
	v_lshl_add_u64 v[74:75], v[74:75], 0, s[54:55]
	v_lshl_add_u64 v[74:75], v[74:75], 0, s[54:55]
	global_load_short_d16_hi v88, v72, s[4:5] offset:0
	global_load_short_d16_hi v89, v72, s[0:1] offset:0
	global_load_short_d16_hi v90, v72, s[12:13] offset:1024
	global_load_short_d16_hi v91, v[74:75], off offset:0
	global_load_short_d16_hi v92, v[74:75], off offset:64
	v_add_u32_e32 v72, 0x400, v72
	v_lshl_add_u64 v[74:75], v[74:75], 0, s[54:55]
	v_mov_b32_e32 v32, 0
	v_mov_b32_e32 v33, 0
	v_mov_b32_e32 v34, 0
	v_mov_b32_e32 v35, 0
	v_mov_b32_e32 v36, 0
	v_mov_b32_e32 v37, 0
	v_mov_b32_e32 v38, 0
	v_mov_b32_e32 v39, 0
	v_mov_b32_e32 v40, 0
	v_mov_b32_e32 v41, 0
	v_mov_b32_e32 v42, 0
	v_mov_b32_e32 v43, 0
	v_mov_b32_e32 v44, 0
	v_mov_b32_e32 v45, 0
	v_mov_b32_e32 v46, 0
	v_mov_b32_e32 v47, 0
	v_mov_b32_e32 v16, 0
	v_mov_b32_e32 v17, 0
	v_mov_b32_e32 v18, 0
	v_mov_b32_e32 v19, 0
	v_mov_b32_e32 v20, 0
	v_mov_b32_e32 v21, 0
	v_mov_b32_e32 v22, 0
	v_mov_b32_e32 v23, 0
	v_mov_b32_e32 v24, 0
	v_mov_b32_e32 v25, 0
	v_mov_b32_e32 v26, 0
	v_mov_b32_e32 v27, 0
	v_mov_b32_e32 v28, 0
	v_mov_b32_e32 v29, 0
	v_mov_b32_e32 v30, 0
	v_mov_b32_e32 v31, 0
	v_cmp_eq_u32_e64 s[14:15], 0, v81
	s_nop 1
	v_cndmask_b32_e64 v0, 0, 1.0, s[14:15]
	v_cndmask_b32_e64 v48, 0, 1.0, s[14:15]
	v_cmp_eq_u32_e64 s[14:15], 1, v81
	s_nop 1
	v_cndmask_b32_e64 v1, 0, 1.0, s[14:15]
	v_cndmask_b32_e64 v49, 0, 1.0, s[14:15]
	v_cmp_eq_u32_e64 s[14:15], 2, v81
	s_nop 1
	v_cndmask_b32_e64 v2, 0, 1.0, s[14:15]
	v_cndmask_b32_e64 v50, 0, 1.0, s[14:15]
	v_cmp_eq_u32_e64 s[14:15], 3, v81
	s_nop 1
	v_cndmask_b32_e64 v3, 0, 1.0, s[14:15]
	v_cndmask_b32_e64 v51, 0, 1.0, s[14:15]
	v_cmp_eq_u32_e64 s[14:15], 8, v81
	s_nop 1
	v_cndmask_b32_e64 v4, 0, 1.0, s[14:15]
	v_cndmask_b32_e64 v52, 0, 1.0, s[14:15]
	v_cmp_eq_u32_e64 s[14:15], 9, v81
	s_nop 1
	v_cndmask_b32_e64 v5, 0, 1.0, s[14:15]
	v_cndmask_b32_e64 v53, 0, 1.0, s[14:15]
	v_cmp_eq_u32_e64 s[14:15], 10, v81
	s_nop 1
	v_cndmask_b32_e64 v6, 0, 1.0, s[14:15]
	v_cndmask_b32_e64 v54, 0, 1.0, s[14:15]
	v_cmp_eq_u32_e64 s[14:15], 11, v81
	s_nop 1
	v_cndmask_b32_e64 v7, 0, 1.0, s[14:15]
	v_cndmask_b32_e64 v55, 0, 1.0, s[14:15]
	v_cmp_eq_u32_e64 s[14:15], 16, v81
	s_nop 1
	v_cndmask_b32_e64 v8, 0, 1.0, s[14:15]
	v_cndmask_b32_e64 v56, 0, 1.0, s[14:15]
	v_cmp_eq_u32_e64 s[14:15], 17, v81
	s_nop 1
	v_cndmask_b32_e64 v9, 0, 1.0, s[14:15]
	v_cndmask_b32_e64 v57, 0, 1.0, s[14:15]
	v_cmp_eq_u32_e64 s[14:15], 18, v81
	s_nop 1
	v_cndmask_b32_e64 v10, 0, 1.0, s[14:15]
	v_cndmask_b32_e64 v58, 0, 1.0, s[14:15]
	v_cmp_eq_u32_e64 s[14:15], 19, v81
	s_nop 1
	v_cndmask_b32_e64 v11, 0, 1.0, s[14:15]
	v_cndmask_b32_e64 v59, 0, 1.0, s[14:15]
	v_cmp_eq_u32_e64 s[14:15], 24, v81
	s_nop 1
	v_cndmask_b32_e64 v12, 0, 1.0, s[14:15]
	v_cndmask_b32_e64 v60, 0, 1.0, s[14:15]
	v_cmp_eq_u32_e64 s[14:15], 25, v81
	s_nop 1
	v_cndmask_b32_e64 v13, 0, 1.0, s[14:15]
	v_cndmask_b32_e64 v61, 0, 1.0, s[14:15]
	v_cmp_eq_u32_e64 s[14:15], 26, v81
	s_nop 1
	v_cndmask_b32_e64 v14, 0, 1.0, s[14:15]
	v_cndmask_b32_e64 v62, 0, 1.0, s[14:15]
	v_cmp_eq_u32_e64 s[14:15], 27, v81
	s_nop 1
	v_cndmask_b32_e64 v15, 0, 1.0, s[14:15]
	v_cndmask_b32_e64 v63, 0, 1.0, s[14:15]
	s_waitcnt vmcnt(15)
	v_mul_f32_e32 v78, 0xbfb8aa3b, v224
	v_exp_f32_e32 v78, v78
	s_nop 0
	v_mul_f32_e32 v246, v246, v78
	v_mul_f32_e32 v79, v225, v246
	v_mul_f32_e32 v80, v226, v246
	v_rcp_f32_e32 v248, v246
	s_nop 0
	ds_write2st64_b32 v77, v248, v79 offset0:0 offset1:1
	ds_write_b32 v77, v80 offset:512
	ds_read_b32 v249, v251 offset:0
	ds_read_b32 v250, v251 offset:128
	s_waitcnt lgkmcnt(0)
	v_mul_f32_e32 v240, v227, v249
	v_mul_f32_e32 v241, v228, v250
	s_movk_i32 s41, 0
; template <bool ID> __device__ __forceinline__ void rwkv_scan(const bf16_t* __restrict__ R, const bf16_t* __restrict__ EW, const bf16_t* __restrict__ K, const bf16_t* __restrict__ V, ...
;     ...
;     for (int s = 0; s < nsteps; ++s) {
;         L[lane] = bf2f(q2[4]); L[64 + lane] = __expf(-bf2f(q1[1])); L[128 + lane] = bf2f(q1[5]); L[192 + lane] = bf2f(q1[2]); L[256 + lane] = bf2f(q1[0]);
;         const float v = bf2f(q1[3]);
; #pragma unroll
;         for (int j = 0; j < 6; ++j) q1[j] = q2[j];
;         { const unsigned o = base + (unsigned)(s + 2 < nsteps ? s + 2 : nsteps - 1) * 512u; q2[0] = R[o]; q2[1] = EW[o]; q2[2] = K[o]; q2[3] = V[o]; q2[4] = A[o]; q2[5] = B[o]; }
;         const f2 sav2 = {sav, sav}, sai2 = {sai, sai}, v2 = {v, v};
;         f2 yv = {0.f, 0.f}, yi = {0.f, 0.f}, yv1 = {0.f, 0.f}, yi1 = {0.f, 0.f}, nv = {0.f, 0.f}, ni = {0.f, 0.f}, nv1 = {0.f, 0.f}, ni1 = {0.f, 0.f};
;         f32x4 ca = pa[0], cw = pa[16], cb = pa[32], ck = pa[48], cr = pa[64];
; #pragma unroll
;         for (int q = 0; q < 16; ++q) {
;             const f32x4 a4 = ca, w4 = cw, b4 = cb, k4 = ck, r4 = cr;
;             if (q < 15) { ca = pa[1 + q]; cw = pa[17 + q]; cb = pa[33 + q]; ck = pa[49 + q]; cr = pa[65 + q]; }
;             __builtin_amdgcn_sched_barrier(0);
;             { const f2 a2 = {a4[0], a4[1]}, w2 = {w4[0], w4[1]}, b2 = {b4[0], b4[1]}, k2 = {k4[0], k4[1]}, r2 = {r4[0], r4[1]};
;               f2 tv = sav2 * b2; tv = pfma(v2, k2, tv); Sv[2 * q] = pfma(Sv[2 * q], w2, tv); yv = pfma(Sv[2 * q], r2, yv); nv = pfma(Sv[2 * q], a2, nv);
;               if (ID) { const f2 ti = sai2 * b2; Si[2 * q] = pfma(Si[2 * q], w2, ti); yi = pfma(Si[2 * q], r2, yi); ni = pfma(Si[2 * q], a2, ni); } }
;             { const f2 a2 = {a4[2], a4[3]}, w2 = {w4[2], w4[3]}, b2 = {b4[2], b4[3]}, k2 = {k4[2], k4[3]}, r2 = {r4[2], r4[3]};
;               f2 tv = sav2 * b2; tv = pfma(v2, k2, tv); Sv[2 * q + 1] = pfma(Sv[2 * q + 1], w2, tv); yv1 = pfma(Sv[2 * q + 1], r2, yv1); nv1 = pfma(Sv[2 * q + 1], a2, nv1);
;               if (ID) { const f2 ti = sai2 * b2; Si[2 * q + 1] = pfma(Si[2 * q + 1], w2, ti); yi1 = pfma(Si[2 * q + 1], r2, yi1); ni1 = pfma(Si[2 * q + 1], a2, ni1); } }
;         }
;         sav = (nv[0] + nv[1]) + (nv1[0] + nv1[1]); sai = (ni[0] + ni[1]) + (ni1[0] + ni1[1]);
;         const unsigned cbo = base + (unsigned)s * 512u;
.Lscan_i_loop:
	ds_read_b128 v[192:195], v76 offset:256
	ds_read_b128 v[196:199], v76 offset:288
	ds_read_b128 v[200:203], v76 offset:320
	ds_read_b128 v[204:207], v76 offset:352
	ds_read_b128 v[208:211], v76 offset:512
	ds_read_b128 v[212:215], v76 offset:544
	ds_read_b128 v[216:219], v76 offset:576
	ds_read_b128 v[220:223], v76 offset:608
	global_load_short_d16_hi v224, v72, s[4:5] offset:0
	global_load_short_d16_hi v225, v72, s[0:1] offset:0
	global_load_short_d16_hi v226, v72, s[12:13] offset:1024
	global_load_short_d16_hi v227, v[74:75], off offset:0
	global_load_short_d16_hi v228, v[74:75], off offset:64
	v_mfma_f32_32x32x1_2b_f32 v[0:31], v240, v244, v[0:31]
	ds_read_b128 v[148:151], v76 offset:384
	ds_read_b128 v[152:155], v76 offset:416
	ds_read_b128 v[156:159], v76 offset:448
	ds_read_b128 v[160:163], v76 offset:480
	ds_read_b128 v[164:167], v76 offset:640
	ds_read_b128 v[168:171], v76 offset:672
	ds_read_b128 v[172:175], v76 offset:704
	ds_read_b128 v[176:179], v76 offset:736
	v_mfma_f32_32x32x1_2b_f32 v[32:63], v241, v244, v[32:63]
	s_waitcnt vmcnt(15)
	v_mul_f32_e32 v78, 0xbfb8aa3b, v230
	v_exp_f32_e32 v78, v78
	s_nop 0
	v_mul_f32_e32 v246, v246, v78
	v_mul_f32_e32 v79, v231, v246
	v_mul_f32_e32 v80, v232, v246
	v_rcp_f32_e32 v248, v246
	s_nop 0
	ds_write2st64_b32 v77, v248, v79 offset0:3 offset1:4
	ds_write_b32 v77, v80 offset:1280
	s_waitcnt lgkmcnt(10)
	v_pk_mul_f32 v[64:65], v[0:1], v[192:193]
	v_pk_mul_f32 v[68:69], v[0:1], v[208:209]
	v_pk_fma_f32 v[64:65], v[2:3], v[194:195], v[64:65]
	v_pk_fma_f32 v[68:69], v[2:3], v[210:211], v[68:69]
	v_pk_fma_f32 v[64:65], v[4:5], v[196:197], v[64:65]
	v_pk_fma_f32 v[68:69], v[4:5], v[212:213], v[68:69]
	v_pk_fma_f32 v[64:65], v[6:7], v[198:199], v[64:65]
	v_pk_fma_f32 v[68:69], v[6:7], v[214:215], v[68:69]
	v_pk_fma_f32 v[64:65], v[8:9], v[200:201], v[64:65]
	v_pk_fma_f32 v[68:69], v[8:9], v[216:217], v[68:69]
	v_pk_fma_f32 v[64:65], v[10:11], v[202:203], v[64:65]
	v_pk_fma_f32 v[68:69], v[10:11], v[218:219], v[68:69]
	v_pk_fma_f32 v[64:65], v[12:13], v[204:205], v[64:65]
	v_pk_fma_f32 v[68:69], v[12:13], v[220:221], v[68:69]
	v_pk_fma_f32 v[64:65], v[14:15], v[206:207], v[64:65]
	v_pk_fma_f32 v[68:69], v[14:15], v[222:223], v[68:69]
	v_pk_mul_f32 v[66:67], v[16:17], v[192:193]
	v_pk_mul_f32 v[70:71], v[16:17], v[208:209]
	v_pk_fma_f32 v[66:67], v[18:19], v[194:195], v[66:67]
	v_pk_fma_f32 v[70:71], v[18:19], v[210:211], v[70:71]
	v_pk_fma_f32 v[66:67], v[20:21], v[196:197], v[66:67]
	v_pk_fma_f32 v[70:71], v[20:21], v[212:213], v[70:71]
	v_pk_fma_f32 v[66:67], v[22:23], v[198:199], v[66:67]
	v_pk_fma_f32 v[70:71], v[22:23], v[214:215], v[70:71]
	v_pk_fma_f32 v[66:67], v[24:25], v[200:201], v[66:67]
	v_pk_fma_f32 v[70:71], v[24:25], v[216:217], v[70:71]
	v_pk_fma_f32 v[66:67], v[26:27], v[202:203], v[66:67]
	v_pk_fma_f32 v[70:71], v[26:27], v[218:219], v[70:71]
	v_pk_fma_f32 v[66:67], v[28:29], v[204:205], v[66:67]
	v_pk_fma_f32 v[70:71], v[28:29], v[220:221], v[70:71]
	v_pk_fma_f32 v[66:67], v[30:31], v[206:207], v[66:67]
	v_pk_fma_f32 v[70:71], v[30:31], v[222:223], v[70:71]
	s_waitcnt lgkmcnt(2)
	v_pk_fma_f32 v[64:65], v[32:33], v[148:149], v[64:65]
	v_pk_fma_f32 v[68:69], v[32:33], v[164:165], v[68:69]
	v_pk_fma_f32 v[64:65], v[34:35], v[150:151], v[64:65]
	v_pk_fma_f32 v[68:69], v[34:35], v[166:167], v[68:69]
	v_pk_fma_f32 v[64:65], v[36:37], v[152:153], v[64:65]
	v_pk_fma_f32 v[68:69], v[36:37], v[168:169], v[68:69]
	v_pk_fma_f32 v[64:65], v[38:39], v[154:155], v[64:65]
	v_pk_fma_f32 v[68:69], v[38:39], v[170:171], v[68:69]
	v_pk_fma_f32 v[64:65], v[40:41], v[156:157], v[64:65]
	v_pk_fma_f32 v[68:69], v[40:41], v[172:173], v[68:69]
	v_pk_fma_f32 v[64:65], v[42:43], v[158:159], v[64:65]
	v_pk_fma_f32 v[68:69], v[42:43], v[174:175], v[68:69]
	v_pk_fma_f32 v[64:65], v[44:45], v[160:161], v[64:65]
	v_pk_fma_f32 v[68:69], v[44:45], v[176:177], v[68:69]
	v_pk_fma_f32 v[64:65], v[46:47], v[162:163], v[64:65]
	v_pk_fma_f32 v[68:69], v[46:47], v[178:179], v[68:69]
	v_pk_fma_f32 v[66:67], v[48:49], v[148:149], v[66:67]
	v_pk_fma_f32 v[70:71], v[48:49], v[164:165], v[70:71]
	v_pk_fma_f32 v[66:67], v[50:51], v[150:151], v[66:67]
	v_pk_fma_f32 v[70:71], v[50:51], v[166:167], v[70:71]
	v_pk_fma_f32 v[66:67], v[52:53], v[152:153], v[66:67]
	v_pk_fma_f32 v[70:71], v[52:53], v[168:169], v[70:71]
	v_pk_fma_f32 v[66:67], v[54:55], v[154:155], v[66:67]
	v_pk_fma_f32 v[70:71], v[54:55], v[170:171], v[70:71]
	v_pk_fma_f32 v[66:67], v[56:57], v[156:157], v[66:67]
	v_pk_fma_f32 v[70:71], v[56:57], v[172:173], v[70:71]
	v_pk_fma_f32 v[66:67], v[58:59], v[158:159], v[66:67]
	v_pk_fma_f32 v[70:71], v[58:59], v[174:175], v[70:71]
	v_pk_fma_f32 v[66:67], v[60:61], v[160:161], v[66:67]
	v_pk_fma_f32 v[70:71], v[60:61], v[176:177], v[70:71]
	v_pk_fma_f32 v[66:67], v[62:63], v[162:163], v[66:67]
	v_pk_fma_f32 v[70:71], v[62:63], v[178:179], v[70:71]
	ds_read_b32 v249, v251 offset:768
	ds_read_b32 v250, v251 offset:896
	s_waitcnt lgkmcnt(0)
; template <bool ID> __device__ __forceinline__ void rwkv_scan(const bf16_t* __restrict__ R, const bf16_t* __restrict__ EW, const bf16_t* __restrict__ K, const bf16_t* __restrict__ V, ...
;     ...
;     for (int s = 0; s < nsteps; ++s) {
;         L[lane] = bf2f(q2[4]); L[64 + lane] = __expf(-bf2f(q1[1])); L[128 + lane] = bf2f(q1[5]); L[192 + lane] = bf2f(q1[2]); L[256 + lane] = bf2f(q1[0]);
;         const float v = bf2f(q1[3]);
; #pragma unroll
;         for (int j = 0; j < 6; ++j) q1[j] = q2[j];
;         { const unsigned o = base + (unsigned)(s + 2 < nsteps ? s + 2 : nsteps - 1) * 512u; q2[0] = R[o]; q2[1] = EW[o]; q2[2] = K[o]; q2[3] = V[o]; q2[4] = A[o]; q2[5] = B[o]; }
;         const f2 sav2 = {sav, sav}, sai2 = {sai, sai}, v2 = {v, v};
;         f2 yv = {0.f, 0.f}, yi = {0.f, 0.f}, yv1 = {0.f, 0.f}, yi1 = {0.f, 0.f}, nv = {0.f, 0.f}, ni = {0.f, 0.f}, nv1 = {0.f, 0.f}, ni1 = {0.f, 0.f};
;         f32x4 ca = pa[0], cw = pa[16], cb = pa[32], ck = pa[48], cr = pa[64];
; #pragma unroll
;         for (int q = 0; q < 16; ++q) {
;             const f32x4 a4 = ca, w4 = cw, b4 = cb, k4 = ck, r4 = cr;
;             if (q < 15) { ca = pa[1 + q]; cw = pa[17 + q]; cb = pa[33 + q]; ck = pa[49 + q]; cr = pa[65 + q]; }
;             __builtin_amdgcn_sched_barrier(0);
;             { const f2 a2 = {a4[0], a4[1]}, w2 = {w4[0], w4[1]}, b2 = {b4[0], b4[1]}, k2 = {k4[0], k4[1]}, r2 = {r4[0], r4[1]};
;               f2 tv = sav2 * b2; tv = pfma(v2, k2, tv); Sv[2 * q] = pfma(Sv[2 * q], w2, tv); yv = pfma(Sv[2 * q], r2, yv); nv = pfma(Sv[2 * q], a2, nv);
;               if (ID) { const f2 ti = sai2 * b2; Si[2 * q] = pfma(Si[2 * q], w2, ti); yi = pfma(Si[2 * q], r2, yi); ni = pfma(Si[2 * q], a2, ni); } }
;             { const f2 a2 = {a4[2], a4[3]}, w2 = {w4[2], w4[3]}, b2 = {b4[2], b4[3]}, k2 = {k4[2], k4[3]}, r2 = {r4[2], r4[3]};
;               f2 tv = sav2 * b2; tv = pfma(v2, k2, tv); Sv[2 * q + 1] = pfma(Sv[2 * q + 1], w2, tv); yv1 = pfma(Sv[2 * q + 1], r2, yv1); nv1 = pfma(Sv[2 * q + 1], a2, nv1);
;               if (ID) { const f2 ti = sai2 * b2; Si[2 * q + 1] = pfma(Si[2 * q + 1], w2, ti); yi1 = pfma(Si[2 * q + 1], r2, yi1); ni1 = pfma(Si[2 * q + 1], a2, ni1); } }
;         }
;         sav = (nv[0] + nv[1]) + (nv1[0] + nv1[1]); sai = (ni[0] + ni[1]) + (ni1[0] + ni1[1]);
;         const unsigned cbo = base + (unsigned)s * 512u;
	v_mul_f32_e32 v240, v233, v249
	v_mul_f32_e32 v241, v234, v250
	v_add_f32_e32 v68, v68, v69
	v_add_f32_e32 v70, v70, v71
	v_add_f32_e32 v64, v64, v65
	v_add_f32_e32 v66, v66, v67
	v_permlane32_swap_b32_e32 v68, v70
	s_nop 0
	v_permlane32_swap_b32_e32 v64, v66
	v_add_f32_e32 v244, v68, v70
	v_add_f32_e32 v64, v64, v66
	v_bfe_u32 v66, v64, 16, 1
	v_add3_u32 v66, v64, v66, s69
	global_store_short_d16_hi v72, v66, s[24:25] offset:-4096
	v_add_u32_e32 v72, 0x400, v72
	v_lshl_add_u64 v[74:75], v[74:75], 0, s[54:55]
	ds_read_b128 v[148:151], v76 offset:1024
	ds_read_b128 v[152:155], v76 offset:1056
	ds_read_b128 v[156:159], v76 offset:1088
	ds_read_b128 v[160:163], v76 offset:1120
	ds_read_b128 v[164:167], v76 offset:1280
	ds_read_b128 v[168:171], v76 offset:1312
	ds_read_b128 v[172:175], v76 offset:1344
	ds_read_b128 v[176:179], v76 offset:1376
	global_load_short_d16_hi v230, v72, s[4:5] offset:0
	global_load_short_d16_hi v231, v72, s[0:1] offset:0
	global_load_short_d16_hi v232, v72, s[12:13] offset:1024
	global_load_short_d16_hi v233, v[74:75], off offset:0
	global_load_short_d16_hi v234, v[74:75], off offset:64
	v_mfma_f32_32x32x1_2b_f32 v[0:31], v240, v244, v[0:31]
	ds_read_b128 v[192:195], v76 offset:1152
	ds_read_b128 v[196:199], v76 offset:1184
	ds_read_b128 v[200:203], v76 offset:1216
	ds_read_b128 v[204:207], v76 offset:1248
	ds_read_b128 v[208:211], v76 offset:1408
	ds_read_b128 v[212:215], v76 offset:1440
	ds_read_b128 v[216:219], v76 offset:1472
	ds_read_b128 v[220:223], v76 offset:1504
	v_mfma_f32_32x32x1_2b_f32 v[32:63], v241, v244, v[32:63]
	s_waitcnt vmcnt(16)
	v_mul_f32_e32 v78, 0xbfb8aa3b, v82
	v_exp_f32_e32 v78, v78
	s_nop 0
	v_mul_f32_e32 v246, v246, v78
	v_mul_f32_e32 v79, v83, v246
	v_mul_f32_e32 v80, v84, v246
	v_rcp_f32_e32 v248, v246
	s_nop 0
	ds_write2st64_b32 v77, v248, v79 offset0:0 offset1:1
	ds_write_b32 v77, v80 offset:512
	s_waitcnt lgkmcnt(10)
	v_pk_mul_f32 v[64:65], v[0:1], v[148:149]
	v_pk_mul_f32 v[68:69], v[0:1], v[164:165]
	v_pk_fma_f32 v[64:65], v[2:3], v[150:151], v[64:65]
	v_pk_fma_f32 v[68:69], v[2:3], v[166:167], v[68:69]
	v_pk_fma_f32 v[64:65], v[4:5], v[152:153], v[64:65]
	v_pk_fma_f32 v[68:69], v[4:5], v[168:169], v[68:69]
	v_pk_fma_f32 v[64:65], v[6:7], v[154:155], v[64:65]
	v_pk_fma_f32 v[68:69], v[6:7], v[170:171], v[68:69]
	v_pk_fma_f32 v[64:65], v[8:9], v[156:157], v[64:65]
	v_pk_fma_f32 v[68:69], v[8:9], v[172:173], v[68:69]
	v_pk_fma_f32 v[64:65], v[10:11], v[158:159], v[64:65]
	v_pk_fma_f32 v[68:69], v[10:11], v[174:175], v[68:69]
	v_pk_fma_f32 v[64:65], v[12:13], v[160:161], v[64:65]
	v_pk_fma_f32 v[68:69], v[12:13], v[176:177], v[68:69]
	v_pk_fma_f32 v[64:65], v[14:15], v[162:163], v[64:65]
	v_pk_fma_f32 v[68:69], v[14:15], v[178:179], v[68:69]
	v_pk_mul_f32 v[66:67], v[16:17], v[148:149]
	v_pk_mul_f32 v[70:71], v[16:17], v[164:165]
	v_pk_fma_f32 v[66:67], v[18:19], v[150:151], v[66:67]
	v_pk_fma_f32 v[70:71], v[18:19], v[166:167], v[70:71]
	v_pk_fma_f32 v[66:67], v[20:21], v[152:153], v[66:67]
	v_pk_fma_f32 v[70:71], v[20:21], v[168:169], v[70:71]
	v_pk_fma_f32 v[66:67], v[22:23], v[154:155], v[66:67]
	v_pk_fma_f32 v[70:71], v[22:23], v[170:171], v[70:71]
	v_pk_fma_f32 v[66:67], v[24:25], v[156:157], v[66:67]
	v_pk_fma_f32 v[70:71], v[24:25], v[172:173], v[70:71]
	v_pk_fma_f32 v[66:67], v[26:27], v[158:159], v[66:67]
	v_pk_fma_f32 v[70:71], v[26:27], v[174:175], v[70:71]
	v_pk_fma_f32 v[66:67], v[28:29], v[160:161], v[66:67]
	v_pk_fma_f32 v[70:71], v[28:29], v[176:177], v[70:71]
	v_pk_fma_f32 v[66:67], v[30:31], v[162:163], v[66:67]
	v_pk_fma_f32 v[70:71], v[30:31], v[178:179], v[70:71]
	s_waitcnt lgkmcnt(2)
	v_pk_fma_f32 v[64:65], v[32:33], v[192:193], v[64:65]
	v_pk_fma_f32 v[68:69], v[32:33], v[208:209], v[68:69]
	v_pk_fma_f32 v[64:65], v[34:35], v[194:195], v[64:65]
	v_pk_fma_f32 v[68:69], v[34:35], v[210:211], v[68:69]
	v_pk_fma_f32 v[64:65], v[36:37], v[196:197], v[64:65]
	v_pk_fma_f32 v[68:69], v[36:37], v[212:213], v[68:69]
	v_pk_fma_f32 v[64:65], v[38:39], v[198:199], v[64:65]
	v_pk_fma_f32 v[68:69], v[38:39], v[214:215], v[68:69]
	v_pk_fma_f32 v[64:65], v[40:41], v[200:201], v[64:65]
	v_pk_fma_f32 v[68:69], v[40:41], v[216:217], v[68:69]
	v_pk_fma_f32 v[64:65], v[42:43], v[202:203], v[64:65]
	v_pk_fma_f32 v[68:69], v[42:43], v[218:219], v[68:69]
	v_pk_fma_f32 v[64:65], v[44:45], v[204:205], v[64:65]
	v_pk_fma_f32 v[68:69], v[44:45], v[220:221], v[68:69]
	v_pk_fma_f32 v[64:65], v[46:47], v[206:207], v[64:65]
	v_pk_fma_f32 v[68:69], v[46:47], v[222:223], v[68:69]
	v_pk_fma_f32 v[66:67], v[48:49], v[192:193], v[66:67]
	v_pk_fma_f32 v[70:71], v[48:49], v[208:209], v[70:71]
	v_pk_fma_f32 v[66:67], v[50:51], v[194:195], v[66:67]
	v_pk_fma_f32 v[70:71], v[50:51], v[210:211], v[70:71]
	v_pk_fma_f32 v[66:67], v[52:53], v[196:197], v[66:67]
	v_pk_fma_f32 v[70:71], v[52:53], v[212:213], v[70:71]
	v_pk_fma_f32 v[66:67], v[54:55], v[198:199], v[66:67]
	v_pk_fma_f32 v[70:71], v[54:55], v[214:215], v[70:71]
	v_pk_fma_f32 v[66:67], v[56:57], v[200:201], v[66:67]
	v_pk_fma_f32 v[70:71], v[56:57], v[216:217], v[70:71]
	v_pk_fma_f32 v[66:67], v[58:59], v[202:203], v[66:67]
	v_pk_fma_f32 v[70:71], v[58:59], v[218:219], v[70:71]
	v_pk_fma_f32 v[66:67], v[60:61], v[204:205], v[66:67]
	v_pk_fma_f32 v[70:71], v[60:61], v[220:221], v[70:71]
	v_pk_fma_f32 v[66:67], v[62:63], v[206:207], v[66:67]
	v_pk_fma_f32 v[70:71], v[62:63], v[222:223], v[70:71]
	ds_read_b32 v249, v251 offset:0
	ds_read_b32 v250, v251 offset:128
	s_waitcnt lgkmcnt(0)
; template <bool ID> __device__ __forceinline__ void rwkv_scan(const bf16_t* __restrict__ R, const bf16_t* __restrict__ EW, const bf16_t* __restrict__ K, const bf16_t* __restrict__ V, ...
;     ...
;     for (int s = 0; s < nsteps; ++s) {
;         L[lane] = bf2f(q2[4]); L[64 + lane] = __expf(-bf2f(q1[1])); L[128 + lane] = bf2f(q1[5]); L[192 + lane] = bf2f(q1[2]); L[256 + lane] = bf2f(q1[0]);
;         const float v = bf2f(q1[3]);
; #pragma unroll
;         for (int j = 0; j < 6; ++j) q1[j] = q2[j];
;         { const unsigned o = base + (unsigned)(s + 2 < nsteps ? s + 2 : nsteps - 1) * 512u; q2[0] = R[o]; q2[1] = EW[o]; q2[2] = K[o]; q2[3] = V[o]; q2[4] = A[o]; q2[5] = B[o]; }
;         const f2 sav2 = {sav, sav}, sai2 = {sai, sai}, v2 = {v, v};
;         f2 yv = {0.f, 0.f}, yi = {0.f, 0.f}, yv1 = {0.f, 0.f}, yi1 = {0.f, 0.f}, nv = {0.f, 0.f}, ni = {0.f, 0.f}, nv1 = {0.f, 0.f}, ni1 = {0.f, 0.f};
;         f32x4 ca = pa[0], cw = pa[16], cb = pa[32], ck = pa[48], cr = pa[64];
; #pragma unroll
;         for (int q = 0; q < 16; ++q) {
;             const f32x4 a4 = ca, w4 = cw, b4 = cb, k4 = ck, r4 = cr;
;             if (q < 15) { ca = pa[1 + q]; cw = pa[17 + q]; cb = pa[33 + q]; ck = pa[49 + q]; cr = pa[65 + q]; }
;             __builtin_amdgcn_sched_barrier(0);
;             { const f2 a2 = {a4[0], a4[1]}, w2 = {w4[0], w4[1]}, b2 = {b4[0], b4[1]}, k2 = {k4[0], k4[1]}, r2 = {r4[0], r4[1]};
;               f2 tv = sav2 * b2; tv = pfma(v2, k2, tv); Sv[2 * q] = pfma(Sv[2 * q], w2, tv); yv = pfma(Sv[2 * q], r2, yv); nv = pfma(Sv[2 * q], a2, nv);
;               if (ID) { const f2 ti = sai2 * b2; Si[2 * q] = pfma(Si[2 * q], w2, ti); yi = pfma(Si[2 * q], r2, yi); ni = pfma(Si[2 * q], a2, ni); } }
;             { const f2 a2 = {a4[2], a4[3]}, w2 = {w4[2], w4[3]}, b2 = {b4[2], b4[3]}, k2 = {k4[2], k4[3]}, r2 = {r4[2], r4[3]};
;               f2 tv = sav2 * b2; tv = pfma(v2, k2, tv); Sv[2 * q + 1] = pfma(Sv[2 * q + 1], w2, tv); yv1 = pfma(Sv[2 * q + 1], r2, yv1); nv1 = pfma(Sv[2 * q + 1], a2, nv1);
;               if (ID) { const f2 ti = sai2 * b2; Si[2 * q + 1] = pfma(Si[2 * q + 1], w2, ti); yi1 = pfma(Si[2 * q + 1], r2, yi1); ni1 = pfma(Si[2 * q + 1], a2, ni1); } }
;         }
;         sav = (nv[0] + nv[1]) + (nv1[0] + nv1[1]); sai = (ni[0] + ni[1]) + (ni1[0] + ni1[1]);
;         const unsigned cbo = base + (unsigned)s * 512u;
	v_mul_f32_e32 v240, v85, v249
	v_mul_f32_e32 v241, v86, v250
	v_add_f32_e32 v68, v68, v69
	v_add_f32_e32 v70, v70, v71
	v_add_f32_e32 v64, v64, v65
	v_add_f32_e32 v66, v66, v67
	v_permlane32_swap_b32_e32 v68, v70
	s_nop 0
	v_permlane32_swap_b32_e32 v64, v66
	v_add_f32_e32 v244, v68, v70
	v_add_f32_e32 v64, v64, v66
	v_bfe_u32 v66, v64, 16, 1
	v_add3_u32 v66, v64, v66, s69
	global_store_short_d16_hi v72, v66, s[24:25] offset:-4096
	v_add_u32_e32 v72, 0x400, v72
	v_lshl_add_u64 v[74:75], v[74:75], 0, s[54:55]
	ds_read_b128 v[192:195], v76 offset:256
	ds_read_b128 v[196:199], v76 offset:288
	ds_read_b128 v[200:203], v76 offset:320
	ds_read_b128 v[204:207], v76 offset:352
	ds_read_b128 v[208:211], v76 offset:512
	ds_read_b128 v[212:215], v76 offset:544
	ds_read_b128 v[216:219], v76 offset:576
	ds_read_b128 v[220:223], v76 offset:608
	global_load_short_d16_hi v82, v72, s[4:5] offset:0
	global_load_short_d16_hi v83, v72, s[0:1] offset:0
	global_load_short_d16_hi v84, v72, s[12:13] offset:1024
	global_load_short_d16_hi v85, v[74:75], off offset:0
	global_load_short_d16_hi v86, v[74:75], off offset:64
	v_mfma_f32_32x32x1_2b_f32 v[0:31], v240, v244, v[0:31]
	ds_read_b128 v[148:151], v76 offset:384
	ds_read_b128 v[152:155], v76 offset:416
	ds_read_b128 v[156:159], v76 offset:448
	ds_read_b128 v[160:163], v76 offset:480
	ds_read_b128 v[164:167], v76 offset:640
	ds_read_b128 v[168:171], v76 offset:672
	ds_read_b128 v[172:175], v76 offset:704
	ds_read_b128 v[176:179], v76 offset:736
	v_mfma_f32_32x32x1_2b_f32 v[32:63], v241, v244, v[32:63]
	s_waitcnt vmcnt(17)
	v_mul_f32_e32 v78, 0xbfb8aa3b, v88
	v_exp_f32_e32 v78, v78
	s_nop 0
	v_mul_f32_e32 v246, v246, v78
	v_mul_f32_e32 v79, v89, v246
	v_mul_f32_e32 v80, v90, v246
	v_rcp_f32_e32 v248, v246
	s_nop 0
	ds_write2st64_b32 v77, v248, v79 offset0:3 offset1:4
	ds_write_b32 v77, v80 offset:1280
	s_waitcnt lgkmcnt(10)
	v_pk_mul_f32 v[64:65], v[0:1], v[192:193]
	v_pk_mul_f32 v[68:69], v[0:1], v[208:209]
	v_pk_fma_f32 v[64:65], v[2:3], v[194:195], v[64:65]
	v_pk_fma_f32 v[68:69], v[2:3], v[210:211], v[68:69]
	v_pk_fma_f32 v[64:65], v[4:5], v[196:197], v[64:65]
	v_pk_fma_f32 v[68:69], v[4:5], v[212:213], v[68:69]
	v_pk_fma_f32 v[64:65], v[6:7], v[198:199], v[64:65]
	v_pk_fma_f32 v[68:69], v[6:7], v[214:215], v[68:69]
	v_pk_fma_f32 v[64:65], v[8:9], v[200:201], v[64:65]
	v_pk_fma_f32 v[68:69], v[8:9], v[216:217], v[68:69]
	v_pk_fma_f32 v[64:65], v[10:11], v[202:203], v[64:65]
	v_pk_fma_f32 v[68:69], v[10:11], v[218:219], v[68:69]
	v_pk_fma_f32 v[64:65], v[12:13], v[204:205], v[64:65]
	v_pk_fma_f32 v[68:69], v[12:13], v[220:221], v[68:69]
	v_pk_fma_f32 v[64:65], v[14:15], v[206:207], v[64:65]
	v_pk_fma_f32 v[68:69], v[14:15], v[222:223], v[68:69]
	v_pk_mul_f32 v[66:67], v[16:17], v[192:193]
	v_pk_mul_f32 v[70:71], v[16:17], v[208:209]
	v_pk_fma_f32 v[66:67], v[18:19], v[194:195], v[66:67]
	v_pk_fma_f32 v[70:71], v[18:19], v[210:211], v[70:71]
	v_pk_fma_f32 v[66:67], v[20:21], v[196:197], v[66:67]
	v_pk_fma_f32 v[70:71], v[20:21], v[212:213], v[70:71]
	v_pk_fma_f32 v[66:67], v[22:23], v[198:199], v[66:67]
	v_pk_fma_f32 v[70:71], v[22:23], v[214:215], v[70:71]
	v_pk_fma_f32 v[66:67], v[24:25], v[200:201], v[66:67]
	v_pk_fma_f32 v[70:71], v[24:25], v[216:217], v[70:71]
	v_pk_fma_f32 v[66:67], v[26:27], v[202:203], v[66:67]
	v_pk_fma_f32 v[70:71], v[26:27], v[218:219], v[70:71]
	v_pk_fma_f32 v[66:67], v[28:29], v[204:205], v[66:67]
	v_pk_fma_f32 v[70:71], v[28:29], v[220:221], v[70:71]
	v_pk_fma_f32 v[66:67], v[30:31], v[206:207], v[66:67]
	v_pk_fma_f32 v[70:71], v[30:31], v[222:223], v[70:71]
	s_waitcnt lgkmcnt(2)
	v_pk_fma_f32 v[64:65], v[32:33], v[148:149], v[64:65]
	v_pk_fma_f32 v[68:69], v[32:33], v[164:165], v[68:69]
	v_pk_fma_f32 v[64:65], v[34:35], v[150:151], v[64:65]
	v_pk_fma_f32 v[68:69], v[34:35], v[166:167], v[68:69]
	v_pk_fma_f32 v[64:65], v[36:37], v[152:153], v[64:65]
	v_pk_fma_f32 v[68:69], v[36:37], v[168:169], v[68:69]
	v_pk_fma_f32 v[64:65], v[38:39], v[154:155], v[64:65]
	v_pk_fma_f32 v[68:69], v[38:39], v[170:171], v[68:69]
	v_pk_fma_f32 v[64:65], v[40:41], v[156:157], v[64:65]
	v_pk_fma_f32 v[68:69], v[40:41], v[172:173], v[68:69]
	v_pk_fma_f32 v[64:65], v[42:43], v[158:159], v[64:65]
	v_pk_fma_f32 v[68:69], v[42:43], v[174:175], v[68:69]
	v_pk_fma_f32 v[64:65], v[44:45], v[160:161], v[64:65]
	v_pk_fma_f32 v[68:69], v[44:45], v[176:177], v[68:69]
	v_pk_fma_f32 v[64:65], v[46:47], v[162:163], v[64:65]
	v_pk_fma_f32 v[68:69], v[46:47], v[178:179], v[68:69]
	v_pk_fma_f32 v[66:67], v[48:49], v[148:149], v[66:67]
	v_pk_fma_f32 v[70:71], v[48:49], v[164:165], v[70:71]
	v_pk_fma_f32 v[66:67], v[50:51], v[150:151], v[66:67]
	v_pk_fma_f32 v[70:71], v[50:51], v[166:167], v[70:71]
	v_pk_fma_f32 v[66:67], v[52:53], v[152:153], v[66:67]
	v_pk_fma_f32 v[70:71], v[52:53], v[168:169], v[70:71]
	v_pk_fma_f32 v[66:67], v[54:55], v[154:155], v[66:67]
	v_pk_fma_f32 v[70:71], v[54:55], v[170:171], v[70:71]
	v_pk_fma_f32 v[66:67], v[56:57], v[156:157], v[66:67]
	v_pk_fma_f32 v[70:71], v[56:57], v[172:173], v[70:71]
	v_pk_fma_f32 v[66:67], v[58:59], v[158:159], v[66:67]
	v_pk_fma_f32 v[70:71], v[58:59], v[174:175], v[70:71]
	v_pk_fma_f32 v[66:67], v[60:61], v[160:161], v[66:67]
	v_pk_fma_f32 v[70:71], v[60:61], v[176:177], v[70:71]
	v_pk_fma_f32 v[66:67], v[62:63], v[162:163], v[66:67]
	v_pk_fma_f32 v[70:71], v[62:63], v[178:179], v[70:71]
	ds_read_b32 v249, v251 offset:768
	ds_read_b32 v250, v251 offset:896
	s_waitcnt lgkmcnt(0)
	v_mul_f32_e32 v240, v91, v249
	v_mul_f32_e32 v241, v92, v250
	v_add_f32_e32 v68, v68, v69
	v_add_f32_e32 v70, v70, v71
	v_add_f32_e32 v64, v64, v65
	v_add_f32_e32 v66, v66, v67
	v_permlane32_swap_b32_e32 v68, v70
	s_nop 0
	v_permlane32_swap_b32_e32 v64, v66
	v_add_f32_e32 v244, v68, v70
	v_add_f32_e32 v64, v64, v66
	v_bfe_u32 v66, v64, 16, 1
	v_add3_u32 v66, v64, v66, s69
	global_store_short_d16_hi v72, v66, s[24:25] offset:-4096
	v_add_u32_e32 v72, 0x400, v72
	v_lshl_add_u64 v[74:75], v[74:75], 0, s[54:55]
	s_and_b32 s14, s41, 15
	s_cmp_eq_u32 s14, 15
	s_cbranch_scc1 .Lscan_i_s3x
; template <bool ID> __device__ __forceinline__ void rwkv_scan(const bf16_t* __restrict__ R, const bf16_t* __restrict__ EW, const bf16_t* __restrict__ K, const bf16_t* __restrict__ V, ...
;     ...
;     for (int s = 0; s < nsteps; ++s) {
;         L[lane] = bf2f(q2[4]); L[64 + lane] = __expf(-bf2f(q1[1])); L[128 + lane] = bf2f(q1[5]); L[192 + lane] = bf2f(q1[2]); L[256 + lane] = bf2f(q1[0]);
;         const float v = bf2f(q1[3]);
; #pragma unroll
;         for (int j = 0; j < 6; ++j) q1[j] = q2[j];
;         { const unsigned o = base + (unsigned)(s + 2 < nsteps ? s + 2 : nsteps - 1) * 512u; q2[0] = R[o]; q2[1] = EW[o]; q2[2] = K[o]; q2[3] = V[o]; q2[4] = A[o]; q2[5] = B[o]; }
;         const f2 sav2 = {sav, sav}, sai2 = {sai, sai}, v2 = {v, v};
;         f2 yv = {0.f, 0.f}, yi = {0.f, 0.f}, yv1 = {0.f, 0.f}, yi1 = {0.f, 0.f}, nv = {0.f, 0.f}, ni = {0.f, 0.f}, nv1 = {0.f, 0.f}, ni1 = {0.f, 0.f};
;         f32x4 ca = pa[0], cw = pa[16], cb = pa[32], ck = pa[48], cr = pa[64];
; #pragma unroll
;         for (int q = 0; q < 16; ++q) {
;             const f32x4 a4 = ca, w4 = cw, b4 = cb, k4 = ck, r4 = cr;
;             if (q < 15) { ca = pa[1 + q]; cw = pa[17 + q]; cb = pa[33 + q]; ck = pa[49 + q]; cr = pa[65 + q]; }
;             __builtin_amdgcn_sched_barrier(0);
;             { const f2 a2 = {a4[0], a4[1]}, w2 = {w4[0], w4[1]}, b2 = {b4[0], b4[1]}, k2 = {k4[0], k4[1]}, r2 = {r4[0], r4[1]};
;               f2 tv = sav2 * b2; tv = pfma(v2, k2, tv); Sv[2 * q] = pfma(Sv[2 * q], w2, tv); yv = pfma(Sv[2 * q], r2, yv); nv = pfma(Sv[2 * q], a2, nv);
;               if (ID) { const f2 ti = sai2 * b2; Si[2 * q] = pfma(Si[2 * q], w2, ti); yi = pfma(Si[2 * q], r2, yi); ni = pfma(Si[2 * q], a2, ni); } }
;             { const f2 a2 = {a4[2], a4[3]}, w2 = {w4[2], w4[3]}, b2 = {b4[2], b4[3]}, k2 = {k4[2], k4[3]}, r2 = {r4[2], r4[3]};
;               f2 tv = sav2 * b2; tv = pfma(v2, k2, tv); Sv[2 * q + 1] = pfma(Sv[2 * q + 1], w2, tv); yv1 = pfma(Sv[2 * q + 1], r2, yv1); nv1 = pfma(Sv[2 * q + 1], a2, nv1);
;               if (ID) { const f2 ti = sai2 * b2; Si[2 * q + 1] = pfma(Si[2 * q + 1], w2, ti); yi1 = pfma(Si[2 * q + 1], r2, yi1); ni1 = pfma(Si[2 * q + 1], a2, ni1); } }
;         }
;         sav = (nv[0] + nv[1]) + (nv1[0] + nv1[1]); sai = (ni[0] + ni[1]) + (ni1[0] + ni1[1]);
;         const unsigned cbo = base + (unsigned)s * 512u;
	ds_read_b128 v[148:151], v76 offset:1024
	ds_read_b128 v[152:155], v76 offset:1056
	ds_read_b128 v[156:159], v76 offset:1088
	ds_read_b128 v[160:163], v76 offset:1120
	ds_read_b128 v[164:167], v76 offset:1280
	ds_read_b128 v[168:171], v76 offset:1312
	ds_read_b128 v[172:175], v76 offset:1344
	ds_read_b128 v[176:179], v76 offset:1376
	global_load_short_d16_hi v88, v72, s[4:5] offset:0
	global_load_short_d16_hi v89, v72, s[0:1] offset:0
	global_load_short_d16_hi v90, v72, s[12:13] offset:1024
	global_load_short_d16_hi v91, v[74:75], off offset:0
	global_load_short_d16_hi v92, v[74:75], off offset:64
	v_mfma_f32_32x32x1_2b_f32 v[0:31], v240, v244, v[0:31]
	ds_read_b128 v[192:195], v76 offset:1152
	ds_read_b128 v[196:199], v76 offset:1184
	ds_read_b128 v[200:203], v76 offset:1216
	ds_read_b128 v[204:207], v76 offset:1248
	ds_read_b128 v[208:211], v76 offset:1408
	ds_read_b128 v[212:215], v76 offset:1440
	ds_read_b128 v[216:219], v76 offset:1472
	ds_read_b128 v[220:223], v76 offset:1504
	v_mfma_f32_32x32x1_2b_f32 v[32:63], v241, v244, v[32:63]
	s_waitcnt vmcnt(18)
	v_mul_f32_e32 v78, 0xbfb8aa3b, v224
	v_exp_f32_e32 v78, v78
	s_nop 0
	v_mul_f32_e32 v246, v246, v78
	v_mul_f32_e32 v79, v225, v246
	v_mul_f32_e32 v80, v226, v246
	v_rcp_f32_e32 v248, v246
	s_nop 0
	ds_write2st64_b32 v77, v248, v79 offset0:0 offset1:1
	ds_write_b32 v77, v80 offset:512
	s_waitcnt lgkmcnt(10)
	v_pk_mul_f32 v[64:65], v[0:1], v[148:149]
	v_pk_mul_f32 v[68:69], v[0:1], v[164:165]
	v_pk_fma_f32 v[64:65], v[2:3], v[150:151], v[64:65]
	v_pk_fma_f32 v[68:69], v[2:3], v[166:167], v[68:69]
	v_pk_fma_f32 v[64:65], v[4:5], v[152:153], v[64:65]
	v_pk_fma_f32 v[68:69], v[4:5], v[168:169], v[68:69]
	v_pk_fma_f32 v[64:65], v[6:7], v[154:155], v[64:65]
	v_pk_fma_f32 v[68:69], v[6:7], v[170:171], v[68:69]
	v_pk_fma_f32 v[64:65], v[8:9], v[156:157], v[64:65]
	v_pk_fma_f32 v[68:69], v[8:9], v[172:173], v[68:69]
	v_pk_fma_f32 v[64:65], v[10:11], v[158:159], v[64:65]
	v_pk_fma_f32 v[68:69], v[10:11], v[174:175], v[68:69]
	v_pk_fma_f32 v[64:65], v[12:13], v[160:161], v[64:65]
	v_pk_fma_f32 v[68:69], v[12:13], v[176:177], v[68:69]
	v_pk_fma_f32 v[64:65], v[14:15], v[162:163], v[64:65]
	v_pk_fma_f32 v[68:69], v[14:15], v[178:179], v[68:69]
	v_pk_mul_f32 v[66:67], v[16:17], v[148:149]
	v_pk_mul_f32 v[70:71], v[16:17], v[164:165]
	v_pk_fma_f32 v[66:67], v[18:19], v[150:151], v[66:67]
	v_pk_fma_f32 v[70:71], v[18:19], v[166:167], v[70:71]
	v_pk_fma_f32 v[66:67], v[20:21], v[152:153], v[66:67]
	v_pk_fma_f32 v[70:71], v[20:21], v[168:169], v[70:71]
	v_pk_fma_f32 v[66:67], v[22:23], v[154:155], v[66:67]
	v_pk_fma_f32 v[70:71], v[22:23], v[170:171], v[70:71]
	v_pk_fma_f32 v[66:67], v[24:25], v[156:157], v[66:67]
	v_pk_fma_f32 v[70:71], v[24:25], v[172:173], v[70:71]
	v_pk_fma_f32 v[66:67], v[26:27], v[158:159], v[66:67]
	v_pk_fma_f32 v[70:71], v[26:27], v[174:175], v[70:71]
	v_pk_fma_f32 v[66:67], v[28:29], v[160:161], v[66:67]
	v_pk_fma_f32 v[70:71], v[28:29], v[176:177], v[70:71]
	v_pk_fma_f32 v[66:67], v[30:31], v[162:163], v[66:67]
	v_pk_fma_f32 v[70:71], v[30:31], v[178:179], v[70:71]
	s_waitcnt lgkmcnt(2)
	v_pk_fma_f32 v[64:65], v[32:33], v[192:193], v[64:65]
	v_pk_fma_f32 v[68:69], v[32:33], v[208:209], v[68:69]
	v_pk_fma_f32 v[64:65], v[34:35], v[194:195], v[64:65]
	v_pk_fma_f32 v[68:69], v[34:35], v[210:211], v[68:69]
	v_pk_fma_f32 v[64:65], v[36:37], v[196:197], v[64:65]
	v_pk_fma_f32 v[68:69], v[36:37], v[212:213], v[68:69]
	v_pk_fma_f32 v[64:65], v[38:39], v[198:199], v[64:65]
	v_pk_fma_f32 v[68:69], v[38:39], v[214:215], v[68:69]
	v_pk_fma_f32 v[64:65], v[40:41], v[200:201], v[64:65]
	v_pk_fma_f32 v[68:69], v[40:41], v[216:217], v[68:69]
	v_pk_fma_f32 v[64:65], v[42:43], v[202:203], v[64:65]
	v_pk_fma_f32 v[68:69], v[42:43], v[218:219], v[68:69]
	v_pk_fma_f32 v[64:65], v[44:45], v[204:205], v[64:65]
	v_pk_fma_f32 v[68:69], v[44:45], v[220:221], v[68:69]
	v_pk_fma_f32 v[64:65], v[46:47], v[206:207], v[64:65]
	v_pk_fma_f32 v[68:69], v[46:47], v[222:223], v[68:69]
	v_pk_fma_f32 v[66:67], v[48:49], v[192:193], v[66:67]
	v_pk_fma_f32 v[70:71], v[48:49], v[208:209], v[70:71]
	v_pk_fma_f32 v[66:67], v[50:51], v[194:195], v[66:67]
	v_pk_fma_f32 v[70:71], v[50:51], v[210:211], v[70:71]
	v_pk_fma_f32 v[66:67], v[52:53], v[196:197], v[66:67]
	v_pk_fma_f32 v[70:71], v[52:53], v[212:213], v[70:71]
	v_pk_fma_f32 v[66:67], v[54:55], v[198:199], v[66:67]
	v_pk_fma_f32 v[70:71], v[54:55], v[214:215], v[70:71]
	v_pk_fma_f32 v[66:67], v[56:57], v[200:201], v[66:67]
	v_pk_fma_f32 v[70:71], v[56:57], v[216:217], v[70:71]
	v_pk_fma_f32 v[66:67], v[58:59], v[202:203], v[66:67]
	v_pk_fma_f32 v[70:71], v[58:59], v[218:219], v[70:71]
	v_pk_fma_f32 v[66:67], v[60:61], v[204:205], v[66:67]
	v_pk_fma_f32 v[70:71], v[60:61], v[220:221], v[70:71]
	v_pk_fma_f32 v[66:67], v[62:63], v[206:207], v[66:67]
	v_pk_fma_f32 v[70:71], v[62:63], v[222:223], v[70:71]
	ds_read_b32 v249, v251 offset:0
	ds_read_b32 v250, v251 offset:128
	s_waitcnt lgkmcnt(0)
	v_mul_f32_e32 v240, v227, v249
	v_mul_f32_e32 v241, v228, v250
	v_add_f32_e32 v68, v68, v69
	v_add_f32_e32 v70, v70, v71
	v_add_f32_e32 v64, v64, v65
	v_add_f32_e32 v66, v66, v67
	v_permlane32_swap_b32_e32 v68, v70
	s_nop 0
	v_permlane32_swap_b32_e32 v64, v66
	v_add_f32_e32 v244, v68, v70
	v_add_f32_e32 v64, v64, v66
	v_bfe_u32 v66, v64, 16, 1
	v_add3_u32 v66, v64, v66, s69
	global_store_short_d16_hi v72, v66, s[24:25] offset:-4096
	v_add_u32_e32 v72, 0x400, v72
	v_lshl_add_u64 v[74:75], v[74:75], 0, s[54:55]
	s_branch .Lscan_i_s3e
; template <bool ID> __device__ __forceinline__ void rwkv_scan(const bf16_t* __restrict__ R, const bf16_t* __restrict__ EW, const bf16_t* __restrict__ K, const bf16_t* __restrict__ V, ...
;     ...
;     for (int s = 0; s < nsteps; ++s) {
;         L[lane] = bf2f(q2[4]); L[64 + lane] = __expf(-bf2f(q1[1])); L[128 + lane] = bf2f(q1[5]); L[192 + lane] = bf2f(q1[2]); L[256 + lane] = bf2f(q1[0]);
;         const float v = bf2f(q1[3]);
; #pragma unroll
;         for (int j = 0; j < 6; ++j) q1[j] = q2[j];
;         { const unsigned o = base + (unsigned)(s + 2 < nsteps ? s + 2 : nsteps - 1) * 512u; q2[0] = R[o]; q2[1] = EW[o]; q2[2] = K[o]; q2[3] = V[o]; q2[4] = A[o]; q2[5] = B[o]; }
;         const f2 sav2 = {sav, sav}, sai2 = {sai, sai}, v2 = {v, v};
;         f2 yv = {0.f, 0.f}, yi = {0.f, 0.f}, yv1 = {0.f, 0.f}, yi1 = {0.f, 0.f}, nv = {0.f, 0.f}, ni = {0.f, 0.f}, nv1 = {0.f, 0.f}, ni1 = {0.f, 0.f};
;         f32x4 ca = pa[0], cw = pa[16], cb = pa[32], ck = pa[48], cr = pa[64];
; #pragma unroll
;         for (int q = 0; q < 16; ++q) {
;             const f32x4 a4 = ca, w4 = cw, b4 = cb, k4 = ck, r4 = cr;
;             if (q < 15) { ca = pa[1 + q]; cw = pa[17 + q]; cb = pa[33 + q]; ck = pa[49 + q]; cr = pa[65 + q]; }
;             __builtin_amdgcn_sched_barrier(0);
;             { const f2 a2 = {a4[0], a4[1]}, w2 = {w4[0], w4[1]}, b2 = {b4[0], b4[1]}, k2 = {k4[0], k4[1]}, r2 = {r4[0], r4[1]};
;               f2 tv = sav2 * b2; tv = pfma(v2, k2, tv); Sv[2 * q] = pfma(Sv[2 * q], w2, tv); yv = pfma(Sv[2 * q], r2, yv); nv = pfma(Sv[2 * q], a2, nv);
;               if (ID) { const f2 ti = sai2 * b2; Si[2 * q] = pfma(Si[2 * q], w2, ti); yi = pfma(Si[2 * q], r2, yi); ni = pfma(Si[2 * q], a2, ni); } }
;             { const f2 a2 = {a4[2], a4[3]}, w2 = {w4[2], w4[3]}, b2 = {b4[2], b4[3]}, k2 = {k4[2], k4[3]}, r2 = {r4[2], r4[3]};
;               f2 tv = sav2 * b2; tv = pfma(v2, k2, tv); Sv[2 * q + 1] = pfma(Sv[2 * q + 1], w2, tv); yv1 = pfma(Sv[2 * q + 1], r2, yv1); nv1 = pfma(Sv[2 * q + 1], a2, nv1);
;               if (ID) { const f2 ti = sai2 * b2; Si[2 * q + 1] = pfma(Si[2 * q + 1], w2, ti); yi1 = pfma(Si[2 * q + 1], r2, yi1); ni1 = pfma(Si[2 * q + 1], a2, ni1); } }
;         }
;         sav = (nv[0] + nv[1]) + (nv1[0] + nv1[1]); sai = (ni[0] + ni[1]) + (ni1[0] + ni1[1]);
;         const unsigned cbo = base + (unsigned)s * 512u;
.Lscan_i_s3x:
	ds_read_b128 v[148:151], v76 offset:1024
	ds_read_b128 v[152:155], v76 offset:1056
	ds_read_b128 v[156:159], v76 offset:1088
	ds_read_b128 v[160:163], v76 offset:1120
	ds_read_b128 v[164:167], v76 offset:1280
	ds_read_b128 v[168:171], v76 offset:1312
	ds_read_b128 v[172:175], v76 offset:1344
	ds_read_b128 v[176:179], v76 offset:1376
	global_load_short_d16_hi v88, v72, s[4:5] offset:0
	global_load_short_d16_hi v89, v72, s[0:1] offset:0
	global_load_short_d16_hi v90, v72, s[12:13] offset:1024
	global_load_short_d16_hi v91, v[74:75], off offset:0
	global_load_short_d16_hi v92, v[74:75], off offset:64
	v_mfma_f32_32x32x1_2b_f32 v[0:31], v240, v244, v[0:31]
	ds_read_b128 v[192:195], v76 offset:1152
	ds_read_b128 v[196:199], v76 offset:1184
	ds_read_b128 v[200:203], v76 offset:1216
	ds_read_b128 v[204:207], v76 offset:1248
	ds_read_b128 v[208:211], v76 offset:1408
	ds_read_b128 v[212:215], v76 offset:1440
	ds_read_b128 v[216:219], v76 offset:1472
	ds_read_b128 v[220:223], v76 offset:1504
	v_mfma_f32_32x32x1_2b_f32 v[32:63], v241, v244, v[32:63]
	s_waitcnt vmcnt(18)
	s_waitcnt lgkmcnt(8)
	s_nop 6
	v_pk_mul_f32 v[64:65], v[0:1], v[148:149]
	v_pk_mul_f32 v[68:69], v[0:1], v[164:165]
	v_pk_fma_f32 v[64:65], v[2:3], v[150:151], v[64:65]
	v_pk_fma_f32 v[68:69], v[2:3], v[166:167], v[68:69]
	v_pk_fma_f32 v[64:65], v[4:5], v[152:153], v[64:65]
	v_pk_fma_f32 v[68:69], v[4:5], v[168:169], v[68:69]
	v_pk_fma_f32 v[64:65], v[6:7], v[154:155], v[64:65]
	v_pk_fma_f32 v[68:69], v[6:7], v[170:171], v[68:69]
	v_pk_fma_f32 v[64:65], v[8:9], v[156:157], v[64:65]
	v_pk_fma_f32 v[68:69], v[8:9], v[172:173], v[68:69]
	v_pk_fma_f32 v[64:65], v[10:11], v[158:159], v[64:65]
	v_pk_fma_f32 v[68:69], v[10:11], v[174:175], v[68:69]
	v_pk_fma_f32 v[64:65], v[12:13], v[160:161], v[64:65]
	v_pk_fma_f32 v[68:69], v[12:13], v[176:177], v[68:69]
	v_pk_fma_f32 v[64:65], v[14:15], v[162:163], v[64:65]
	v_pk_fma_f32 v[68:69], v[14:15], v[178:179], v[68:69]
	v_pk_mul_f32 v[66:67], v[16:17], v[148:149]
	v_pk_mul_f32 v[70:71], v[16:17], v[164:165]
	v_pk_fma_f32 v[66:67], v[18:19], v[150:151], v[66:67]
	v_pk_fma_f32 v[70:71], v[18:19], v[166:167], v[70:71]
	v_pk_fma_f32 v[66:67], v[20:21], v[152:153], v[66:67]
	v_pk_fma_f32 v[70:71], v[20:21], v[168:169], v[70:71]
	v_pk_fma_f32 v[66:67], v[22:23], v[154:155], v[66:67]
	v_pk_fma_f32 v[70:71], v[22:23], v[170:171], v[70:71]
	v_pk_fma_f32 v[66:67], v[24:25], v[156:157], v[66:67]
	v_pk_fma_f32 v[70:71], v[24:25], v[172:173], v[70:71]
	v_pk_fma_f32 v[66:67], v[26:27], v[158:159], v[66:67]
	v_pk_fma_f32 v[70:71], v[26:27], v[174:175], v[70:71]
	v_pk_fma_f32 v[66:67], v[28:29], v[160:161], v[66:67]
	v_pk_fma_f32 v[70:71], v[28:29], v[176:177], v[70:71]
	v_pk_fma_f32 v[66:67], v[30:31], v[162:163], v[66:67]
	v_pk_fma_f32 v[70:71], v[30:31], v[178:179], v[70:71]
	s_waitcnt lgkmcnt(0)
; template <bool ID> __device__ __forceinline__ void rwkv_scan(const bf16_t* __restrict__ R, const bf16_t* __restrict__ EW, const bf16_t* __restrict__ K, const bf16_t* __restrict__ V, ...
;     ...
;     for (int s = 0; s < nsteps; ++s) {
;         L[lane] = bf2f(q2[4]); L[64 + lane] = __expf(-bf2f(q1[1])); L[128 + lane] = bf2f(q1[5]); L[192 + lane] = bf2f(q1[2]); L[256 + lane] = bf2f(q1[0]);
;         const float v = bf2f(q1[3]);
; #pragma unroll
;         for (int j = 0; j < 6; ++j) q1[j] = q2[j];
;         { const unsigned o = base + (unsigned)(s + 2 < nsteps ? s + 2 : nsteps - 1) * 512u; q2[0] = R[o]; q2[1] = EW[o]; q2[2] = K[o]; q2[3] = V[o]; q2[4] = A[o]; q2[5] = B[o]; }
;         const f2 sav2 = {sav, sav}, sai2 = {sai, sai}, v2 = {v, v};
;         f2 yv = {0.f, 0.f}, yi = {0.f, 0.f}, yv1 = {0.f, 0.f}, yi1 = {0.f, 0.f}, nv = {0.f, 0.f}, ni = {0.f, 0.f}, nv1 = {0.f, 0.f}, ni1 = {0.f, 0.f};
;         f32x4 ca = pa[0], cw = pa[16], cb = pa[32], ck = pa[48], cr = pa[64];
; #pragma unroll
;         for (int q = 0; q < 16; ++q) {
;             const f32x4 a4 = ca, w4 = cw, b4 = cb, k4 = ck, r4 = cr;
;             if (q < 15) { ca = pa[1 + q]; cw = pa[17 + q]; cb = pa[33 + q]; ck = pa[49 + q]; cr = pa[65 + q]; }
;             __builtin_amdgcn_sched_barrier(0);
;             { const f2 a2 = {a4[0], a4[1]}, w2 = {w4[0], w4[1]}, b2 = {b4[0], b4[1]}, k2 = {k4[0], k4[1]}, r2 = {r4[0], r4[1]};
;               f2 tv = sav2 * b2; tv = pfma(v2, k2, tv); Sv[2 * q] = pfma(Sv[2 * q], w2, tv); yv = pfma(Sv[2 * q], r2, yv); nv = pfma(Sv[2 * q], a2, nv);
;               if (ID) { const f2 ti = sai2 * b2; Si[2 * q] = pfma(Si[2 * q], w2, ti); yi = pfma(Si[2 * q], r2, yi); ni = pfma(Si[2 * q], a2, ni); } }
;             { const f2 a2 = {a4[2], a4[3]}, w2 = {w4[2], w4[3]}, b2 = {b4[2], b4[3]}, k2 = {k4[2], k4[3]}, r2 = {r4[2], r4[3]};
;               f2 tv = sav2 * b2; tv = pfma(v2, k2, tv); Sv[2 * q + 1] = pfma(Sv[2 * q + 1], w2, tv); yv1 = pfma(Sv[2 * q + 1], r2, yv1); nv1 = pfma(Sv[2 * q + 1], a2, nv1);
;               if (ID) { const f2 ti = sai2 * b2; Si[2 * q + 1] = pfma(Si[2 * q + 1], w2, ti); yi1 = pfma(Si[2 * q + 1], r2, yi1); ni1 = pfma(Si[2 * q + 1], a2, ni1); } }
;         }
;         sav = (nv[0] + nv[1]) + (nv1[0] + nv1[1]); sai = (ni[0] + ni[1]) + (ni1[0] + ni1[1]);
;         const unsigned cbo = base + (unsigned)s * 512u;
	v_pk_fma_f32 v[64:65], v[32:33], v[192:193], v[64:65]
	v_pk_fma_f32 v[68:69], v[32:33], v[208:209], v[68:69]
	v_pk_fma_f32 v[64:65], v[34:35], v[194:195], v[64:65]
	v_pk_fma_f32 v[68:69], v[34:35], v[210:211], v[68:69]
	v_pk_fma_f32 v[64:65], v[36:37], v[196:197], v[64:65]
	v_pk_fma_f32 v[68:69], v[36:37], v[212:213], v[68:69]
	v_pk_fma_f32 v[64:65], v[38:39], v[198:199], v[64:65]
	v_pk_fma_f32 v[68:69], v[38:39], v[214:215], v[68:69]
	v_pk_fma_f32 v[64:65], v[40:41], v[200:201], v[64:65]
	v_pk_fma_f32 v[68:69], v[40:41], v[216:217], v[68:69]
	v_pk_fma_f32 v[64:65], v[42:43], v[202:203], v[64:65]
	v_pk_fma_f32 v[68:69], v[42:43], v[218:219], v[68:69]
	v_pk_fma_f32 v[64:65], v[44:45], v[204:205], v[64:65]
	v_pk_fma_f32 v[68:69], v[44:45], v[220:221], v[68:69]
	v_pk_fma_f32 v[64:65], v[46:47], v[206:207], v[64:65]
	v_pk_fma_f32 v[68:69], v[46:47], v[222:223], v[68:69]
	v_pk_fma_f32 v[66:67], v[48:49], v[192:193], v[66:67]
	v_pk_fma_f32 v[70:71], v[48:49], v[208:209], v[70:71]
	v_pk_fma_f32 v[66:67], v[50:51], v[194:195], v[66:67]
	v_pk_fma_f32 v[70:71], v[50:51], v[210:211], v[70:71]
	v_pk_fma_f32 v[66:67], v[52:53], v[196:197], v[66:67]
	v_pk_fma_f32 v[70:71], v[52:53], v[212:213], v[70:71]
	v_pk_fma_f32 v[66:67], v[54:55], v[198:199], v[66:67]
	v_pk_fma_f32 v[70:71], v[54:55], v[214:215], v[70:71]
	v_pk_fma_f32 v[66:67], v[56:57], v[200:201], v[66:67]
	v_pk_fma_f32 v[70:71], v[56:57], v[216:217], v[70:71]
	v_pk_fma_f32 v[66:67], v[58:59], v[202:203], v[66:67]
	v_pk_fma_f32 v[70:71], v[58:59], v[218:219], v[70:71]
	v_pk_fma_f32 v[66:67], v[60:61], v[204:205], v[66:67]
	v_pk_fma_f32 v[70:71], v[60:61], v[220:221], v[70:71]
	v_pk_fma_f32 v[66:67], v[62:63], v[206:207], v[66:67]
	v_pk_fma_f32 v[70:71], v[62:63], v[222:223], v[70:71]
	v_add_f32_e32 v68, v68, v69
	v_add_f32_e32 v70, v70, v71
	v_add_f32_e32 v64, v64, v65
	v_add_f32_e32 v66, v66, v67
	v_permlane32_swap_b32_e32 v68, v70
	s_nop 0
	v_permlane32_swap_b32_e32 v64, v66
	v_add_f32_e32 v244, v68, v70
	v_add_f32_e32 v64, v64, v66
	v_bfe_u32 v66, v64, 16, 1
	v_add3_u32 v66, v64, v66, s69
	global_store_short_d16_hi v72, v66, s[24:25] offset:-4096
	ds_write_b32 v77, v246 offset:0
	ds_read_b128 v[148:151], v76 offset:0
	ds_read_b128 v[152:155], v76 offset:32
	ds_read_b128 v[156:159], v76 offset:64
	ds_read_b128 v[160:163], v76 offset:96
	ds_read_b128 v[164:167], v76 offset:128
	ds_read_b128 v[168:171], v76 offset:160
	ds_read_b128 v[172:175], v76 offset:192
	ds_read_b128 v[176:179], v76 offset:224
	s_waitcnt lgkmcnt(0)
	v_pk_mul_f32 v[0:1], v[0:1], v[148:149]
	v_pk_mul_f32 v[2:3], v[2:3], v[150:151]
	v_pk_mul_f32 v[4:5], v[4:5], v[152:153]
	v_pk_mul_f32 v[6:7], v[6:7], v[154:155]
	v_pk_mul_f32 v[8:9], v[8:9], v[156:157]
	v_pk_mul_f32 v[10:11], v[10:11], v[158:159]
	v_pk_mul_f32 v[12:13], v[12:13], v[160:161]
	v_pk_mul_f32 v[14:15], v[14:15], v[162:163]
	v_pk_mul_f32 v[32:33], v[32:33], v[164:165]
	v_pk_mul_f32 v[34:35], v[34:35], v[166:167]
	v_pk_mul_f32 v[36:37], v[36:37], v[168:169]
	v_pk_mul_f32 v[38:39], v[38:39], v[170:171]
	v_pk_mul_f32 v[40:41], v[40:41], v[172:173]
	v_pk_mul_f32 v[42:43], v[42:43], v[174:175]
	v_pk_mul_f32 v[44:45], v[44:45], v[176:177]
	v_pk_mul_f32 v[46:47], v[46:47], v[178:179]
	v_pk_mul_f32 v[16:17], v[16:17], v[148:149]
	v_pk_mul_f32 v[18:19], v[18:19], v[150:151]
	v_pk_mul_f32 v[20:21], v[20:21], v[152:153]
	v_pk_mul_f32 v[22:23], v[22:23], v[154:155]
	v_pk_mul_f32 v[24:25], v[24:25], v[156:157]
	v_pk_mul_f32 v[26:27], v[26:27], v[158:159]
	v_pk_mul_f32 v[28:29], v[28:29], v[160:161]
	v_pk_mul_f32 v[30:31], v[30:31], v[162:163]
	v_pk_mul_f32 v[48:49], v[48:49], v[164:165]
	v_pk_mul_f32 v[50:51], v[50:51], v[166:167]
	v_pk_mul_f32 v[52:53], v[52:53], v[168:169]
	v_pk_mul_f32 v[54:55], v[54:55], v[170:171]
	v_pk_mul_f32 v[56:57], v[56:57], v[172:173]
	v_pk_mul_f32 v[58:59], v[58:59], v[174:175]
	v_pk_mul_f32 v[60:61], v[60:61], v[176:177]
	v_pk_mul_f32 v[62:63], v[62:63], v[178:179]
	v_mov_b32_e32 v246, 1.0
	v_mul_f32_e32 v78, 0xbfb8aa3b, v224
	v_exp_f32_e32 v78, v78
	s_nop 0
	v_mul_f32_e32 v246, v246, v78
	v_mul_f32_e32 v79, v225, v246
	v_mul_f32_e32 v80, v226, v246
	v_rcp_f32_e32 v248, v246
	s_nop 0
	ds_write2st64_b32 v77, v248, v79 offset0:0 offset1:1
	ds_write_b32 v77, v80 offset:512
	ds_read_b32 v249, v251 offset:0
	ds_read_b32 v250, v251 offset:128
	s_waitcnt lgkmcnt(0)
	v_mul_f32_e32 v240, v227, v249
	v_mul_f32_e32 v241, v228, v250
	s_waitcnt lgkmcnt(0)
	v_add_u32_e32 v72, 0x400, v72
	v_lshl_add_u64 v[74:75], v[74:75], 0, s[54:55]
